# plus sc1 output stores in the gMLP-in and FoX-in epilogues
# speedup vs baseline: 1.0485x; 1.0085x over previous
; __device__ __forceinline__ unsigned cvt_pk_bf16(float lo, float hi) { unsigned r; asm volatile("v_cvt_pk_bf16_f32 %0, %1, %2" : "=v"(r) : "v"(lo), "v"(hi)); return r; }
;     __device__ __forceinline__ void operator()(const f32x4 (&acc)[2][2][4][2], const Unit& u, int wr, int wc, int fr, int fq) const {
;     ...
;         } else {
; #pragma unroll
;             for (int ai = 0; ai < 2; ++ai)
; #pragma unroll
;                 for (int m = 0; m < 4; ++m) { bf16_t* rowp = base + (size_t)(row0 + ai * HALF + m * 16) * ldc + col0; const float rs = rsv[ai][m];
; #pragma unroll
;                     for (int bj = 0; bj < 2; ++bj) { const f32x4 v0 = acc[ai][bj][m][0] * rs, v1 = acc[ai][bj][m][1] * rs;
;                         u32x4 w; w.x = cvt_pk_bf16(v0[0], v0[1]); w.y = cvt_pk_bf16(v0[2], v0[3]); w.z = cvt_pk_bf16(v1[0], v1[1]); w.w = cvt_pk_bf16(v1[2], v1[3]);
;                         *(u32x4*)(rowp + bj * HALF) = w; } }
.LBB0_234:
	v_lshl_add_u64 v[138:139], s[0:1], 0, v[114:115]
	v_lshlrev_b64 v[132:133], 11, v[158:159]
	s_waitcnt lgkmcnt(0)
	v_pk_mul_f32 v[134:135], v[128:129], v[156:157] op_sel_hi:[1,0]
	v_lshl_add_u64 v[132:133], v[138:139], 0, v[132:133]
	v_pk_mul_f32 v[136:137], v[130:131], v[156:157] op_sel_hi:[1,0]
	v_cvt_pk_bf16_f32 v134, v134, v135
	v_pk_mul_f32 v[140:141], v[126:127], v[156:157] op_sel_hi:[1,0]
	v_cvt_pk_bf16_f32 v135, v136, v137
	v_pk_mul_f32 v[142:143], v[124:125], v[156:157] op_sel_hi:[1,0]
	s_mov_b32 s4, 0x40000
	v_cvt_pk_bf16_f32 v136, v142, v143
	v_cvt_pk_bf16_f32 v137, v140, v141
	global_store_dwordx4 v[132:133], v[134:137], off sc1
	v_pk_mul_f32 v[142:143], v[116:117], v[156:157] op_sel_hi:[1,0]
	v_pk_mul_f32 v[140:141], v[118:119], v[156:157] op_sel_hi:[1,0]
	v_pk_mul_f32 v[134:135], v[120:121], v[156:157] op_sel_hi:[1,0]
	v_pk_mul_f32 v[136:137], v[122:123], v[156:157] op_sel_hi:[1,0]
	v_cvt_pk_bf16_f32 v134, v134, v135
	s_nop 0
	v_cvt_pk_bf16_f32 v135, v136, v137
	v_cvt_pk_bf16_f32 v136, v142, v143
	v_cvt_pk_bf16_f32 v137, v140, v141
	global_store_dwordx4 v[132:133], v[134:137], off offset:256 sc1
	v_mov_b32_e32 v142, v157
	v_pk_mul_f32 v[200:201], v[104:105], v[142:143] op_sel_hi:[1,0]
	v_lshlrev_b64 v[134:135], 11, v[168:169]
	v_lshl_add_u64 v[140:141], v[138:139], 0, v[134:135]
	v_pk_mul_f32 v[134:135], v[108:109], v[142:143] op_sel_hi:[1,0]
	v_pk_mul_f32 v[136:137], v[110:111], v[142:143] op_sel_hi:[1,0]
	v_cvt_pk_bf16_f32 v134, v134, v135
	v_pk_mul_f32 v[168:169], v[106:107], v[142:143] op_sel_hi:[1,0]
	v_cvt_pk_bf16_f32 v135, v136, v137
	v_cvt_pk_bf16_f32 v136, v200, v201
	s_nop 0
	v_cvt_pk_bf16_f32 v137, v168, v169
	global_store_dwordx4 v[140:141], v[134:137], off sc1
	v_pk_mul_f32 v[168:169], v[98:99], v[142:143] op_sel_hi:[1,0]
	s_nop 0
	v_pk_mul_f32 v[134:135], v[100:101], v[142:143] op_sel_hi:[1,0]
	v_pk_mul_f32 v[136:137], v[102:103], v[142:143] op_sel_hi:[1,0]
	v_cvt_pk_bf16_f32 v134, v134, v135
	v_pk_mul_f32 v[142:143], v[96:97], v[142:143] op_sel_hi:[1,0]
	v_cvt_pk_bf16_f32 v135, v136, v137
	s_nop 0
	v_cvt_pk_bf16_f32 v136, v142, v143
	v_cvt_pk_bf16_f32 v137, v168, v169
	global_store_dwordx4 v[140:141], v[134:137], off offset:256 sc1
	v_pk_mul_f32 v[142:143], v[90:91], v[154:155] op_sel_hi:[1,0]
	s_nop 0
	v_lshlrev_b64 v[134:135], 11, v[166:167]
	v_lshl_add_u64 v[140:141], v[138:139], 0, v[134:135]
	v_pk_mul_f32 v[134:135], v[92:93], v[154:155] op_sel_hi:[1,0]
	v_pk_mul_f32 v[136:137], v[94:95], v[154:155] op_sel_hi:[1,0]
	v_cvt_pk_bf16_f32 v134, v134, v135
	v_pk_mul_f32 v[166:167], v[88:89], v[154:155] op_sel_hi:[1,0]
	v_cvt_pk_bf16_f32 v135, v136, v137
	s_nop 0
	v_cvt_pk_bf16_f32 v136, v166, v167
	v_cvt_pk_bf16_f32 v137, v142, v143
	global_store_dwordx4 v[140:141], v[134:137], off sc1
	v_pk_mul_f32 v[142:143], v[82:83], v[154:155] op_sel_hi:[1,0]
	v_pk_mul_f32 v[166:167], v[80:81], v[154:155] op_sel_hi:[1,0]
	v_pk_mul_f32 v[134:135], v[84:85], v[154:155] op_sel_hi:[1,0]
	v_pk_mul_f32 v[136:137], v[86:87], v[154:155] op_sel_hi:[1,0]
	v_cvt_pk_bf16_f32 v134, v134, v135
	s_nop 0
	v_cvt_pk_bf16_f32 v135, v136, v137
	v_cvt_pk_bf16_f32 v136, v166, v167
	v_cvt_pk_bf16_f32 v137, v142, v143
	global_store_dwordx4 v[140:141], v[134:137], off offset:256 sc1
	v_mov_b32_e32 v140, v155
	v_pk_mul_f32 v[142:143], v[74:75], v[140:141] op_sel_hi:[1,0]
	v_lshlrev_b64 v[134:135], 11, v[164:165]
	v_lshl_add_u64 v[138:139], v[138:139], 0, v[134:135]
	v_pk_mul_f32 v[136:137], v[78:79], v[140:141] op_sel_hi:[1,0]
	v_pk_mul_f32 v[134:135], v[76:77], v[140:141] op_sel_hi:[1,0]
	v_pk_mul_f32 v[164:165], v[72:73], v[140:141] op_sel_hi:[1,0]
	v_cvt_pk_bf16_f32 v134, v134, v135
	v_cvt_pk_bf16_f32 v135, v136, v137
	s_nop 0
	v_cvt_pk_bf16_f32 v136, v164, v165
	v_cvt_pk_bf16_f32 v137, v142, v143
	global_store_dwordx4 v[138:139], v[134:137], off sc1
	v_pk_mul_f32 v[142:143], v[66:67], v[140:141] op_sel_hi:[1,0]
	s_nop 0
	v_pk_mul_f32 v[136:137], v[70:71], v[140:141] op_sel_hi:[1,0]
	v_pk_mul_f32 v[134:135], v[68:69], v[140:141] op_sel_hi:[1,0]
	v_pk_mul_f32 v[140:141], v[64:65], v[140:141] op_sel_hi:[1,0]
	v_cvt_pk_bf16_f32 v134, v134, v135
	v_cvt_pk_bf16_f32 v135, v136, v137
	s_nop 0
	v_cvt_pk_bf16_f32 v136, v140, v141
	v_cvt_pk_bf16_f32 v137, v142, v143
	global_store_dwordx4 v[138:139], v[134:137], off offset:256 sc1
	v_pk_mul_f32 v[140:141], v[58:59], v[162:163] op_sel_hi:[1,0]
	v_pk_mul_f32 v[142:143], v[56:57], v[162:163] op_sel_hi:[1,0]
	v_pk_mul_f32 v[136:137], v[62:63], v[162:163] op_sel_hi:[1,0]
	v_pk_mul_f32 v[134:135], v[60:61], v[162:163] op_sel_hi:[1,0]
	v_lshl_add_u64 v[138:139], v[132:133], 0, s[34:35]
	v_cvt_pk_bf16_f32 v134, v134, v135
	v_cvt_pk_bf16_f32 v135, v136, v137
	v_cvt_pk_bf16_f32 v136, v142, v143
	v_cvt_pk_bf16_f32 v137, v140, v141
	v_add_co_u32_e32 v140, vcc, s4, v132
	v_pk_mul_f32 v[142:143], v[48:49], v[162:163] op_sel_hi:[1,0]
	s_nop 0
	v_addc_co_u32_e32 v141, vcc, 0, v133, vcc
	global_store_dwordx4 v[140:141], v[134:137], off sc1
	v_pk_mul_f32 v[140:141], v[50:51], v[162:163] op_sel_hi:[1,0]
	s_mov_b64 s[4:5], 0x48000
	v_pk_mul_f32 v[136:137], v[54:55], v[162:163] op_sel_hi:[1,0]
	v_pk_mul_f32 v[134:135], v[52:53], v[162:163] op_sel_hi:[1,0]
	s_nop 0
	v_cvt_pk_bf16_f32 v134, v134, v135
	v_cvt_pk_bf16_f32 v135, v136, v137
	v_cvt_pk_bf16_f32 v136, v142, v143
	v_cvt_pk_bf16_f32 v137, v140, v141
	v_mov_b32_e32 v140, v163
	global_store_dwordx4 v[138:139], v[134:137], off offset:256 sc1
	v_lshl_add_u64 v[138:139], v[132:133], 0, s[4:5]
	v_pk_mul_f32 v[142:143], v[42:43], v[140:141] op_sel_hi:[1,0]
	v_pk_mul_f32 v[136:137], v[46:47], v[140:141] op_sel_hi:[1,0]
	v_pk_mul_f32 v[134:135], v[44:45], v[140:141] op_sel_hi:[1,0]
; __device__ __forceinline__ unsigned cvt_pk_bf16(float lo, float hi) { unsigned r; asm volatile("v_cvt_pk_bf16_f32 %0, %1, %2" : "=v"(r) : "v"(lo), "v"(hi)); return r; }
;     __device__ __forceinline__ void operator()(const f32x4 (&acc)[2][2][4][2], const Unit& u, int wr, int wc, int fr, int fq) const {
;     ...
;                     for (int bj = 0; bj < 2; ++bj) { const f32x4 v0 = acc[ai][bj][m][0], v1 = acc[ai][bj][m][1];
;                         float ss = ((v0[0] * v0[0] + v0[1] * v0[1]) + (v0[2] * v0[2] + v0[3] * v0[3])) + ((v1[0] * v1[0] + v1[1] * v1[1]) + (v1[2] * v1[2] + v1[3] * v1[3]));
;                         ss = fq_sum(ss); ss *= rsv[ai][m] * rsv[ai][m];
;                         if (fq == 0) xl[((ai * HALF + wr * 64 + m * 16 + fr) * 2 + bj) * 4 + wc] = ss; asm volatile("" ::: "memory"); }
;     ...
;                 for (int m = 0; m < 4; ++m) { bf16_t* rowp = base + (size_t)(row0 + ai * HALF + m * 16) * ldc + col0; const float rs = rsv[ai][m];
; #pragma unroll
;                     for (int bj = 0; bj < 2; ++bj) { const f32x4 v0 = acc[ai][bj][m][0] * rs, v1 = acc[ai][bj][m][1] * rs;
;                         u32x4 w; w.x = cvt_pk_bf16(v0[0], v0[1]); w.y = cvt_pk_bf16(v0[2], v0[3]); w.z = cvt_pk_bf16(v1[0], v1[1]); w.w = cvt_pk_bf16(v1[2], v1[3]);
;                         *(u32x4*)(rowp + bj * HALF) = w; } }
	s_mov_b32 s4, 0x48000
	v_pk_mul_f32 v[164:165], v[40:41], v[140:141] op_sel_hi:[1,0]
	v_cvt_pk_bf16_f32 v134, v134, v135
	v_cvt_pk_bf16_f32 v135, v136, v137
	s_nop 0
	v_cvt_pk_bf16_f32 v136, v164, v165
	v_cvt_pk_bf16_f32 v137, v142, v143
	v_add_co_u32_e32 v142, vcc, s4, v132
	s_mov_b64 s[4:5], 0x50000
	s_nop 0
	v_addc_co_u32_e32 v143, vcc, 0, v133, vcc
	global_store_dwordx4 v[142:143], v[134:137], off sc1
	v_pk_mul_f32 v[142:143], v[34:35], v[140:141] op_sel_hi:[1,0]
	s_nop 0
	v_pk_mul_f32 v[136:137], v[38:39], v[140:141] op_sel_hi:[1,0]
	v_pk_mul_f32 v[134:135], v[36:37], v[140:141] op_sel_hi:[1,0]
	v_pk_mul_f32 v[140:141], v[32:33], v[140:141] op_sel_hi:[1,0]
	v_cvt_pk_bf16_f32 v134, v134, v135
	v_cvt_pk_bf16_f32 v135, v136, v137
	s_nop 0
	v_cvt_pk_bf16_f32 v136, v140, v141
	v_cvt_pk_bf16_f32 v137, v142, v143
	global_store_dwordx4 v[138:139], v[134:137], off offset:256 sc1
	v_lshl_add_u64 v[138:139], v[132:133], 0, s[4:5]
	v_pk_mul_f32 v[140:141], v[26:27], v[160:161] op_sel_hi:[1,0]
	v_pk_mul_f32 v[136:137], v[30:31], v[160:161] op_sel_hi:[1,0]
	v_pk_mul_f32 v[134:135], v[28:29], v[160:161] op_sel_hi:[1,0]
	s_mov_b32 s4, 0x50000
	v_pk_mul_f32 v[142:143], v[24:25], v[160:161] op_sel_hi:[1,0]
	v_cvt_pk_bf16_f32 v134, v134, v135
	v_cvt_pk_bf16_f32 v135, v136, v137
	s_nop 0
	v_cvt_pk_bf16_f32 v136, v142, v143
	v_cvt_pk_bf16_f32 v137, v140, v141
	v_add_co_u32_e32 v140, vcc, s4, v132
	s_mov_b64 s[4:5], 0x58000
	s_nop 0
	v_addc_co_u32_e32 v141, vcc, 0, v133, vcc
	global_store_dwordx4 v[140:141], v[134:137], off sc1
	v_pk_mul_f32 v[140:141], v[18:19], v[160:161] op_sel_hi:[1,0]
	v_pk_mul_f32 v[142:143], v[16:17], v[160:161] op_sel_hi:[1,0]
	v_pk_mul_f32 v[136:137], v[22:23], v[160:161] op_sel_hi:[1,0]
	v_pk_mul_f32 v[134:135], v[20:21], v[160:161] op_sel_hi:[1,0]
	s_nop 0
	v_cvt_pk_bf16_f32 v134, v134, v135
	v_cvt_pk_bf16_f32 v135, v136, v137
	v_cvt_pk_bf16_f32 v136, v142, v143
	v_cvt_pk_bf16_f32 v137, v140, v141
	global_store_dwordx4 v[138:139], v[134:137], off offset:256 sc1
	v_lshl_add_u64 v[138:139], v[132:133], 0, s[4:5]
	v_mov_b32_e32 v140, v161
	s_mov_b32 s4, 0x58000
	v_pk_mul_f32 v[134:135], v[12:13], v[140:141] op_sel_hi:[1,0]
	v_add_co_u32_e32 v132, vcc, s4, v132
	v_pk_mul_f32 v[136:137], v[14:15], v[140:141] op_sel_hi:[1,0]
	v_cvt_pk_bf16_f32 v134, v134, v135
	s_nop 0
	v_addc_co_u32_e32 v133, vcc, 0, v133, vcc
	v_cvt_pk_bf16_f32 v135, v136, v137
	v_pk_mul_f32 v[142:143], v[10:11], v[140:141] op_sel_hi:[1,0]
	v_pk_mul_f32 v[164:165], v[8:9], v[140:141] op_sel_hi:[1,0]
	s_nop 0
	v_cvt_pk_bf16_f32 v136, v164, v165
	v_cvt_pk_bf16_f32 v137, v142, v143
	global_store_dwordx4 v[132:133], v[134:137], off sc1
	v_pk_mul_f32 v[132:133], v[4:5], v[140:141] op_sel_hi:[1,0]
	s_nop 0
	v_pk_mul_f32 v[134:135], v[6:7], v[140:141] op_sel_hi:[1,0]
	v_pk_mul_f32 v[136:137], v[2:3], v[140:141] op_sel_hi:[1,0]
	v_pk_mul_f32 v[140:141], v[0:1], v[140:141] op_sel_hi:[1,0]
	v_cvt_pk_bf16_f32 v132, v132, v133
	v_cvt_pk_bf16_f32 v133, v134, v135
	s_nop 0
	v_cvt_pk_bf16_f32 v134, v140, v141
	v_cvt_pk_bf16_f32 v135, v136, v137
	global_store_dwordx4 v[138:139], v[132:135], off offset:256 sc1
	s_cbranch_execnz .LBB0_233
.LBB0_235:
	s_nop 0
	v_mul_f32_e32 v132, v129, v129
	v_mul_f32_e32 v133, v131, v131
	v_fmac_f32_e32 v132, v128, v128
	v_fmac_f32_e32 v133, v130, v130
	v_add_f32_e32 v132, v132, v133
	v_mul_f32_e32 v133, v125, v125
	v_mul_f32_e32 v134, v127, v127
	v_fmac_f32_e32 v133, v124, v124
	v_fmac_f32_e32 v134, v126, v126
	v_add_f32_e32 v133, v133, v134
	v_add_f32_e32 v132, v132, v133
	v_mov_b32_e32 v133, v132
	s_nop 1
	v_permlane16_swap_b32_e32 v132, v133
	v_add_f32_e32 v133, v132, v133
	v_mov_b32_e32 v134, v133
	s_nop 1
	v_permlane32_swap_b32_e32 v133, v134
	s_waitcnt lgkmcnt(0)
	v_mul_f32_e32 v132, v156, v156
	s_and_saveexec_b64 s[4:5], s[38:39]
	v_add_f32_e32 v133, v133, v134
	v_mul_f32_e32 v133, v132, v133
	ds_write_b32 v180, v133
	s_or_b64 exec, exec, s[4:5]
	v_mul_f32_e32 v133, v121, v121
	v_mul_f32_e32 v134, v123, v123
	v_fmac_f32_e32 v133, v120, v120
	v_fmac_f32_e32 v134, v122, v122
	v_add_f32_e32 v133, v133, v134
	v_mul_f32_e32 v134, v117, v117
	v_mul_f32_e32 v135, v119, v119
	v_fmac_f32_e32 v134, v116, v116
	v_fmac_f32_e32 v135, v118, v118
	v_add_f32_e32 v134, v134, v135
	v_add_f32_e32 v133, v133, v134
	v_mov_b32_e32 v134, v133
	s_nop 1
	v_permlane16_swap_b32_e32 v133, v134
	v_add_f32_e32 v133, v133, v134
	v_mov_b32_e32 v134, v133
	s_nop 1
	v_permlane32_swap_b32_e32 v133, v134
	s_and_saveexec_b64 s[4:5], s[38:39]
	v_add_f32_e32 v133, v133, v134
	v_mul_f32_e32 v132, v132, v133
	ds_write_b32 v180, v132 offset:16
	s_or_b64 exec, exec, s[4:5]
	v_mul_f32_e32 v132, v109, v109
	v_mul_f32_e32 v133, v111, v111
	v_fmac_f32_e32 v132, v108, v108
	v_fmac_f32_e32 v133, v110, v110
	v_add_f32_e32 v132, v132, v133
	v_mul_f32_e32 v133, v105, v105
	v_mul_f32_e32 v134, v107, v107
	v_fmac_f32_e32 v133, v104, v104
	v_fmac_f32_e32 v134, v106, v106
	v_add_f32_e32 v133, v133, v134
	v_add_f32_e32 v132, v132, v133
	v_mov_b32_e32 v133, v132
	s_nop 1
	v_permlane16_swap_b32_e32 v132, v133
	v_add_f32_e32 v133, v132, v133
	v_mov_b32_e32 v134, v133
	s_nop 1
	v_permlane32_swap_b32_e32 v133, v134
	v_mul_f32_e32 v132, v157, v157
	s_and_saveexec_b64 s[4:5], s[38:39]
	v_add_f32_e32 v133, v133, v134
	v_mul_f32_e32 v133, v132, v133
	ds_write_b32 v181, v133
	s_or_b64 exec, exec, s[4:5]
	v_mul_f32_e32 v133, v101, v101
	v_mul_f32_e32 v134, v103, v103
	v_fmac_f32_e32 v133, v100, v100
	v_fmac_f32_e32 v134, v102, v102
	v_add_f32_e32 v133, v133, v134
	v_mul_f32_e32 v134, v97, v97
	v_mul_f32_e32 v135, v99, v99
	v_fmac_f32_e32 v134, v96, v96
	v_fmac_f32_e32 v135, v98, v98
	v_add_f32_e32 v134, v134, v135
;     __device__ __forceinline__ void operator()(const f32x4 (&acc)[2][2][4][2], const Unit& u, int wr, int wc, int fr, int fq) const {
;     ...
;             for (int ai = 0; ai < 2; ++ai)
; #pragma unroll
;                 for (int m = 0; m < 4; ++m)
; #pragma unroll
;                     for (int bj = 0; bj < 2; ++bj) { const f32x4 v0 = acc[ai][bj][m][0], v1 = acc[ai][bj][m][1];
;                         float ss = ((v0[0] * v0[0] + v0[1] * v0[1]) + (v0[2] * v0[2] + v0[3] * v0[3])) + ((v1[0] * v1[0] + v1[1] * v1[1]) + (v1[2] * v1[2] + v1[3] * v1[3]));
;                         ss = fq_sum(ss); ss *= rsv[ai][m] * rsv[ai][m];
;                         if (fq == 0) xl[((ai * HALF + wr * 64 + m * 16 + fr) * 2 + bj) * 4 + wc] = ss; asm volatile("" ::: "memory"); }
	v_add_f32_e32 v133, v133, v134
	v_mov_b32_e32 v134, v133
	s_nop 1
	v_permlane16_swap_b32_e32 v133, v134
	v_add_f32_e32 v133, v133, v134
	v_mov_b32_e32 v134, v133
	s_nop 1
	v_permlane32_swap_b32_e32 v133, v134
	s_and_saveexec_b64 s[4:5], s[38:39]
	v_add_f32_e32 v133, v133, v134
	v_mul_f32_e32 v132, v132, v133
	ds_write_b32 v180, v132 offset:528
	s_or_b64 exec, exec, s[4:5]
	v_mul_f32_e32 v132, v93, v93
	v_mul_f32_e32 v133, v95, v95
	v_fmac_f32_e32 v132, v92, v92
	v_fmac_f32_e32 v133, v94, v94
	v_add_f32_e32 v132, v132, v133
	v_mul_f32_e32 v133, v89, v89
	v_mul_f32_e32 v134, v91, v91
	v_fmac_f32_e32 v133, v88, v88
	v_fmac_f32_e32 v134, v90, v90
	v_add_f32_e32 v133, v133, v134
	v_add_f32_e32 v132, v132, v133
	v_mov_b32_e32 v133, v132
	s_nop 1
	v_permlane16_swap_b32_e32 v132, v133
	v_add_f32_e32 v133, v132, v133
	v_mov_b32_e32 v134, v133
	s_nop 1
	v_permlane32_swap_b32_e32 v133, v134
	v_mul_f32_e32 v132, v154, v154
	s_and_saveexec_b64 s[4:5], s[38:39]
	v_add_f32_e32 v133, v133, v134
	v_mul_f32_e32 v133, v132, v133
	ds_write_b32 v182, v133
	s_or_b64 exec, exec, s[4:5]
	v_mul_f32_e32 v133, v85, v85
	v_mul_f32_e32 v134, v87, v87
	v_fmac_f32_e32 v133, v84, v84
	v_fmac_f32_e32 v134, v86, v86
	v_add_f32_e32 v133, v133, v134
	v_mul_f32_e32 v134, v81, v81
	v_mul_f32_e32 v135, v83, v83
	v_fmac_f32_e32 v134, v80, v80
	v_fmac_f32_e32 v135, v82, v82
	v_add_f32_e32 v134, v134, v135
	v_add_f32_e32 v133, v133, v134
	v_mov_b32_e32 v134, v133
	s_nop 1
	v_permlane16_swap_b32_e32 v133, v134
	v_add_f32_e32 v133, v133, v134
	v_mov_b32_e32 v134, v133
	s_nop 1
	v_permlane32_swap_b32_e32 v133, v134
	s_and_saveexec_b64 s[4:5], s[38:39]
	v_add_f32_e32 v133, v133, v134
	v_mul_f32_e32 v132, v132, v133
	ds_write_b32 v180, v132 offset:1040
	s_or_b64 exec, exec, s[4:5]
	v_mul_f32_e32 v132, v77, v77
	v_mul_f32_e32 v133, v79, v79
	v_fmac_f32_e32 v132, v76, v76
	v_fmac_f32_e32 v133, v78, v78
	v_add_f32_e32 v132, v132, v133
	v_mul_f32_e32 v133, v73, v73
	v_mul_f32_e32 v134, v75, v75
	v_fmac_f32_e32 v133, v72, v72
	v_fmac_f32_e32 v134, v74, v74
	v_add_f32_e32 v133, v133, v134
	v_add_f32_e32 v132, v132, v133
	v_mov_b32_e32 v133, v132
	s_nop 1
	v_permlane16_swap_b32_e32 v132, v133
	v_add_f32_e32 v133, v132, v133
	v_mov_b32_e32 v134, v133
	s_nop 1
	v_permlane32_swap_b32_e32 v133, v134
	v_mul_f32_e32 v132, v155, v155
	s_and_saveexec_b64 s[4:5], s[38:39]
	v_add_f32_e32 v133, v133, v134
	v_mul_f32_e32 v133, v132, v133
	ds_write_b32 v183, v133
	s_or_b64 exec, exec, s[4:5]
	v_mul_f32_e32 v133, v69, v69
	v_mul_f32_e32 v134, v71, v71
	v_fmac_f32_e32 v133, v68, v68
	v_fmac_f32_e32 v134, v70, v70
	v_add_f32_e32 v133, v133, v134
	v_mul_f32_e32 v134, v65, v65
	v_mul_f32_e32 v135, v67, v67
	v_fmac_f32_e32 v134, v64, v64
	v_fmac_f32_e32 v135, v66, v66
	v_add_f32_e32 v134, v134, v135
	v_add_f32_e32 v133, v133, v134
	v_mov_b32_e32 v134, v133
	s_nop 1
	v_permlane16_swap_b32_e32 v133, v134
	v_add_f32_e32 v133, v133, v134
	v_mov_b32_e32 v134, v133
	s_nop 1
	v_permlane32_swap_b32_e32 v133, v134
	s_and_saveexec_b64 s[4:5], s[38:39]
	v_add_f32_e32 v133, v133, v134
	v_mul_f32_e32 v132, v132, v133
	ds_write_b32 v180, v132 offset:1552
	s_or_b64 exec, exec, s[4:5]
	v_mul_f32_e32 v132, v61, v61
	v_mul_f32_e32 v133, v63, v63
	v_fmac_f32_e32 v132, v60, v60
	v_fmac_f32_e32 v133, v62, v62
	v_add_f32_e32 v132, v132, v133
	v_mul_f32_e32 v133, v57, v57
	v_mul_f32_e32 v134, v59, v59
	v_fmac_f32_e32 v133, v56, v56
	v_fmac_f32_e32 v134, v58, v58
	v_add_f32_e32 v133, v133, v134
	v_add_f32_e32 v132, v132, v133
	v_mov_b32_e32 v133, v132
	s_nop 1
	v_permlane16_swap_b32_e32 v132, v133
	v_add_f32_e32 v133, v132, v133
	v_mov_b32_e32 v134, v133
	s_nop 1
	v_permlane32_swap_b32_e32 v133, v134
	v_mul_f32_e32 v132, v162, v162
	s_and_saveexec_b64 s[4:5], s[38:39]
	v_add_f32_e32 v133, v133, v134
	v_mul_f32_e32 v133, v132, v133
	ds_write_b32 v184, v133
	s_or_b64 exec, exec, s[4:5]
	v_mul_f32_e32 v133, v53, v53
	v_mul_f32_e32 v134, v55, v55
	v_fmac_f32_e32 v133, v52, v52
	v_fmac_f32_e32 v134, v54, v54
	v_add_f32_e32 v133, v133, v134
	v_mul_f32_e32 v134, v49, v49
	v_mul_f32_e32 v135, v51, v51
	v_fmac_f32_e32 v134, v48, v48
	v_fmac_f32_e32 v135, v50, v50
	v_add_f32_e32 v134, v134, v135
	v_add_f32_e32 v133, v133, v134
	v_mov_b32_e32 v134, v133
	s_nop 1
	v_permlane16_swap_b32_e32 v133, v134
	v_add_f32_e32 v133, v133, v134
	v_mov_b32_e32 v134, v133
	s_nop 1
	v_permlane32_swap_b32_e32 v133, v134
	s_and_saveexec_b64 s[4:5], s[38:39]
	v_add_f32_e32 v133, v133, v134
	v_mul_f32_e32 v132, v132, v133
	ds_write_b32 v180, v132 offset:4112
	s_or_b64 exec, exec, s[4:5]
	v_mul_f32_e32 v132, v45, v45
	v_mul_f32_e32 v133, v47, v47
	v_fmac_f32_e32 v132, v44, v44
	v_fmac_f32_e32 v133, v46, v46
	v_add_f32_e32 v132, v132, v133
	v_mul_f32_e32 v133, v41, v41
	v_mul_f32_e32 v134, v43, v43
	v_fmac_f32_e32 v133, v40, v40
	v_fmac_f32_e32 v134, v42, v42
	v_add_f32_e32 v133, v133, v134
	v_add_f32_e32 v132, v132, v133
	v_mov_b32_e32 v133, v132
	s_nop 1
	v_permlane16_swap_b32_e32 v132, v133
	v_add_f32_e32 v133, v132, v133
	v_mov_b32_e32 v134, v133
	s_nop 1
	v_permlane32_swap_b32_e32 v133, v134
	v_mul_f32_e32 v132, v163, v163
	s_and_saveexec_b64 s[4:5], s[38:39]
	v_add_f32_e32 v133, v133, v134
	v_mul_f32_e32 v133, v132, v133
	ds_write_b32 v185, v133
	s_or_b64 exec, exec, s[4:5]
	v_mul_f32_e32 v133, v37, v37
	v_mul_f32_e32 v134, v39, v39
	v_fmac_f32_e32 v133, v36, v36
	v_fmac_f32_e32 v134, v38, v38
	v_add_f32_e32 v133, v133, v134
	v_mul_f32_e32 v134, v33, v33
	v_mul_f32_e32 v135, v35, v35
	v_fmac_f32_e32 v134, v32, v32
	v_fmac_f32_e32 v135, v34, v34
	v_add_f32_e32 v134, v134, v135
	v_add_f32_e32 v133, v133, v134
	v_mov_b32_e32 v134, v133
	s_nop 1
; #define PG8_LAS __attribute__((address_space(3)))
;     __device__ __forceinline__ void operator()(const f32x4 (&acc)[2][2][4][2], const Unit& u, int wr, int wc, int fr, int fq) const {
;     ...
;                     for (int bj = 0; bj < 2; ++bj) { const f32x4 v0 = acc[ai][bj][m][0], v1 = acc[ai][bj][m][1];
;                         float ss = ((v0[0] * v0[0] + v0[1] * v0[1]) + (v0[2] * v0[2] + v0[3] * v0[3])) + ((v1[0] * v1[0] + v1[1] * v1[1]) + (v1[2] * v1[2] + v1[3] * v1[3]));
;                         ss = fq_sum(ss); ss *= rsv[ai][m] * rsv[ai][m];
;                         if (fq == 0) xl[((ai * HALF + wr * 64 + m * 16 + fr) * 2 + bj) * 4 + wc] = ss; asm volatile("" ::: "memory"); }
;             asm volatile("s_waitcnt lgkmcnt(0)" ::: "memory"); __builtin_amdgcn_s_barrier(); asm volatile("" ::: "memory");
;             const float* gp = (t == 0 ? qg : kg) + 32 * (wc & 1) + 8 * fq; const f32x4 g0 = *(const f32x4*)gp, g1 = *(const f32x4*)(gp + 4); const float sc = (t == 0) ? qscale : 1.0f;
; #pragma unroll
;             for (int ai = 0; ai < 2; ++ai)
; #pragma unroll
;                 for (int m = 0; m < 4; ++m) { const int rl = ai * HALF + wr * 64 + m * 16 + fr; bf16_t* rowp = base + (size_t)(u.pm * BM + rl) * ldc + col0;
; #pragma unroll
;                     for (int bj = 0; bj < 2; ++bj) { const f32x2 pr = *(const PG8_LAS f32x2*)(xl + (rl * 2 + bj) * 4 + (wc & 2)); const float tot = pr[0] + pr[1];
;                         const float hr = sc * rsv[ai][m] / sqrtf(tot * (1.0f / 64.0f) + 1e-6f);
	v_permlane16_swap_b32_e32 v133, v134
	v_add_f32_e32 v133, v133, v134
	v_mov_b32_e32 v134, v133
	s_nop 1
	v_permlane32_swap_b32_e32 v133, v134
	s_and_saveexec_b64 s[4:5], s[38:39]
	v_add_f32_e32 v133, v133, v134
	v_mul_f32_e32 v132, v132, v133
	ds_write_b32 v180, v132 offset:4624
	s_or_b64 exec, exec, s[4:5]
	v_mul_f32_e32 v132, v29, v29
	v_mul_f32_e32 v133, v31, v31
	v_fmac_f32_e32 v132, v28, v28
	v_fmac_f32_e32 v133, v30, v30
	v_add_f32_e32 v132, v132, v133
	v_mul_f32_e32 v133, v25, v25
	v_mul_f32_e32 v134, v27, v27
	v_fmac_f32_e32 v133, v24, v24
	v_fmac_f32_e32 v134, v26, v26
	v_add_f32_e32 v133, v133, v134
	v_add_f32_e32 v132, v132, v133
	v_mov_b32_e32 v133, v132
	s_nop 1
	v_permlane16_swap_b32_e32 v132, v133
	v_add_f32_e32 v133, v132, v133
	v_mov_b32_e32 v134, v133
	s_nop 1
	v_permlane32_swap_b32_e32 v133, v134
	v_mul_f32_e32 v132, v160, v160
	s_and_saveexec_b64 s[4:5], s[38:39]
	v_add_f32_e32 v133, v133, v134
	v_mul_f32_e32 v133, v132, v133
	ds_write_b32 v186, v133
	s_or_b64 exec, exec, s[4:5]
	v_mul_f32_e32 v133, v21, v21
	v_mul_f32_e32 v134, v23, v23
	v_fmac_f32_e32 v133, v20, v20
	v_fmac_f32_e32 v134, v22, v22
	v_add_f32_e32 v133, v133, v134
	v_mul_f32_e32 v134, v17, v17
	v_mul_f32_e32 v135, v19, v19
	v_fmac_f32_e32 v134, v16, v16
	v_fmac_f32_e32 v135, v18, v18
	v_add_f32_e32 v134, v134, v135
	v_add_f32_e32 v133, v133, v134
	v_mov_b32_e32 v134, v133
	s_nop 1
	v_permlane16_swap_b32_e32 v133, v134
	v_add_f32_e32 v133, v133, v134
	v_mov_b32_e32 v134, v133
	s_nop 1
	v_permlane32_swap_b32_e32 v133, v134
	s_and_saveexec_b64 s[4:5], s[38:39]
	v_add_f32_e32 v133, v133, v134
	v_mul_f32_e32 v132, v132, v133
	ds_write_b32 v180, v132 offset:5136
	s_or_b64 exec, exec, s[4:5]
	v_mul_f32_e32 v132, v13, v13
	v_mul_f32_e32 v133, v15, v15
	v_fmac_f32_e32 v132, v12, v12
	v_fmac_f32_e32 v133, v14, v14
	v_add_f32_e32 v132, v132, v133
	v_mul_f32_e32 v133, v9, v9
	v_mul_f32_e32 v134, v11, v11
	v_fmac_f32_e32 v133, v8, v8
	v_fmac_f32_e32 v134, v10, v10
	v_add_f32_e32 v133, v133, v134
	v_add_f32_e32 v132, v132, v133
	v_mov_b32_e32 v133, v132
	s_nop 1
	v_permlane16_swap_b32_e32 v132, v133
	v_add_f32_e32 v133, v132, v133
	v_mov_b32_e32 v134, v133
	s_nop 1
	v_permlane32_swap_b32_e32 v133, v134
	v_mul_f32_e32 v132, v161, v161
	s_and_saveexec_b64 s[4:5], s[38:39]
	v_add_f32_e32 v133, v133, v134
	v_mul_f32_e32 v133, v132, v133
	ds_write_b32 v187, v133
	s_or_b64 exec, exec, s[4:5]
	v_mul_f32_e32 v133, v5, v5
	v_mul_f32_e32 v134, v7, v7
	v_fmac_f32_e32 v133, v4, v4
	v_fmac_f32_e32 v134, v6, v6
	v_add_f32_e32 v133, v133, v134
	v_mul_f32_e32 v134, v1, v1
	v_mul_f32_e32 v135, v3, v3
	v_fmac_f32_e32 v134, v0, v0
	v_fmac_f32_e32 v135, v2, v2
	v_add_f32_e32 v134, v134, v135
	v_add_f32_e32 v133, v133, v134
	v_mov_b32_e32 v134, v133
	s_nop 1
	v_permlane16_swap_b32_e32 v133, v134
	v_add_f32_e32 v133, v133, v134
	v_mov_b32_e32 v134, v133
	s_nop 1
	v_permlane32_swap_b32_e32 v133, v134
	s_and_saveexec_b64 s[4:5], s[38:39]
	v_add_f32_e32 v133, v133, v134
	v_mul_f32_e32 v132, v132, v133
	ds_write_b32 v180, v132 offset:5648
	s_or_b64 exec, exec, s[4:5]
	s_cmp_lt_u32 s67, 4
	s_cselect_b64 vcc, -1, 0
	s_and_b64 s[4:5], vcc, exec
	s_cselect_b32 s5, s44, s46
	s_cselect_b32 s4, s45, s47
	s_add_u32 s5, s5, s52
	s_addc_u32 s21, s4, s53
	s_add_u32 s4, s5, s48
	s_waitcnt lgkmcnt(0)
	s_barrier
	s_addc_u32 s5, s21, 0
	global_load_dwordx4 v[136:139], v198, s[4:5]
	global_load_dwordx4 v[132:135], v198, s[4:5] offset:16
	ds_read_b64 v[142:143], v188
	v_cndmask_b32_e32 v140, 1.0, v237, vcc
	v_mul_f32_e32 v156, v140, v156
	s_waitcnt lgkmcnt(0)
	v_add_f32_e32 v141, v142, v143
	v_fmamk_f32 v141, v141, 0x3c800000, v228
	v_mul_f32_e32 v142, 0x4f800000, v141
	v_cmp_gt_f32_e32 vcc, s36, v141
	s_nop 1
	v_cndmask_b32_e32 v141, v141, v142, vcc
	v_sqrt_f32_e32 v142, v141
	s_nop 0
	v_add_u32_e32 v143, -1, v142
	v_add_u32_e32 v164, 1, v142
	v_fma_f32 v165, -v143, v142, v141
	v_fma_f32 v166, -v164, v142, v141
	v_cmp_ge_f32_e64 s[4:5], 0, v165
	s_nop 1
	v_cndmask_b32_e64 v142, v142, v143, s[4:5]
	v_cmp_lt_f32_e64 s[4:5], 0, v166
	s_nop 1
	v_cndmask_b32_e64 v142, v142, v164, s[4:5]
	v_mul_f32_e32 v143, 0x37800000, v142
	v_cndmask_b32_e32 v142, v142, v143, vcc
	v_cmp_class_f32_e32 vcc, v141, v229
	s_nop 1
	v_cndmask_b32_e32 v141, v142, v141, vcc
	v_div_scale_f32 v142, s[4:5], v141, v141, v156
	v_rcp_f32_e32 v143, v142
	v_div_scale_f32 v164, vcc, v156, v141, v156
	v_fma_f32 v165, -v142, v143, 1.0
	v_fmac_f32_e32 v143, v165, v143
	v_mul_f32_e32 v165, v164, v143
	v_fma_f32 v166, -v142, v165, v164
	v_fmac_f32_e32 v165, v166, v143
	v_fma_f32 v142, -v142, v165, v164
	v_div_fmas_f32 v142, v142, v143, v165
	v_div_fixup_f32 v142, v142, v141, v156
	v_pk_mul_f32 v[128:129], v[128:129], v[142:143] op_sel_hi:[1,0]
	v_pk_mul_f32 v[124:125], v[124:125], v[142:143] op_sel_hi:[1,0]
	v_pk_mul_f32 v[130:131], v[130:131], v[142:143] op_sel_hi:[1,0]
	v_pk_mul_f32 v[126:127], v[126:127], v[142:143] op_sel_hi:[1,0]
	s_waitcnt vmcnt(0)
	v_pk_mul_f32 v[128:129], v[136:137], v[128:129]
	v_pk_mul_f32 v[124:125], v[132:133], v[124:125]
	v_pk_mul_f32 v[130:131], v[138:139], v[130:131]
	v_pk_mul_f32 v[142:143], v[134:135], v[126:127]
	v_cvt_pk_bf16_f32 v126, v128, v129
	v_cvt_pk_bf16_f32 v127, v130, v131
	v_cvt_pk_bf16_f32 v128, v124, v125
	v_lshlrev_b64 v[130:131], 11, v[158:159]
	v_cvt_pk_bf16_f32 v129, v142, v143
	ds_read_b64 v[124:125], v188 offset:16
	s_waitcnt lgkmcnt(0)
; #define PG8_LAS __attribute__((address_space(3)))
; __device__ __forceinline__ unsigned cvt_pk_bf16(float lo, float hi) { unsigned r; asm volatile("v_cvt_pk_bf16_f32 %0, %1, %2" : "=v"(r) : "v"(lo), "v"(hi)); return r; }
;     __device__ __forceinline__ void operator()(const f32x4 (&acc)[2][2][4][2], const Unit& u, int wr, int wc, int fr, int fq) const {
;     ...
;             for (int ai = 0; ai < 2; ++ai)
; #pragma unroll
;                 for (int m = 0; m < 4; ++m) { const int rl = ai * HALF + wr * 64 + m * 16 + fr; bf16_t* rowp = base + (size_t)(u.pm * BM + rl) * ldc + col0;
; #pragma unroll
;                     for (int bj = 0; bj < 2; ++bj) { const f32x2 pr = *(const PG8_LAS f32x2*)(xl + (rl * 2 + bj) * 4 + (wc & 2)); const float tot = pr[0] + pr[1];
;                         const float hr = sc * rsv[ai][m] / sqrtf(tot * (1.0f / 64.0f) + 1e-6f);
;                         const f32x4 v0 = acc[ai][bj][m][0] * hr * g0, v1 = acc[ai][bj][m][1] * hr * g1;
;                         u32x4 w; w.x = cvt_pk_bf16(v0[0], v0[1]); w.y = cvt_pk_bf16(v0[2], v0[3]); w.z = cvt_pk_bf16(v1[0], v1[1]); w.w = cvt_pk_bf16(v1[2], v1[3]);
;                         *(u32x4*)(rowp + bj * HALF) = w; }
	v_add_f32_e32 v124, v124, v125
	v_fmamk_f32 v124, v124, 0x3c800000, v228
	v_mul_f32_e32 v125, 0x4f800000, v124
	v_cmp_gt_f32_e32 vcc, s36, v124
	s_nop 1
	v_cndmask_b32_e32 v141, v124, v125, vcc
	v_sqrt_f32_e32 v142, v141
	v_lshl_add_u64 v[124:125], s[0:1], 0, v[114:115]
	v_lshl_add_u64 v[130:131], v[124:125], 0, v[130:131]
	global_store_dwordx4 v[130:131], v[126:129], off sc1
	v_add_u32_e32 v114, -1, v142
	v_add_u32_e32 v143, 1, v142
	v_fma_f32 v158, -v114, v142, v141
	v_fma_f32 v159, -v143, v142, v141
	v_cmp_ge_f32_e64 s[4:5], 0, v158
	s_nop 1
	v_cndmask_b32_e64 v114, v142, v114, s[4:5]
	v_cmp_lt_f32_e64 s[4:5], 0, v159
	s_nop 1
	v_cndmask_b32_e64 v114, v114, v143, s[4:5]
	v_mul_f32_e32 v142, 0x37800000, v114
	v_cndmask_b32_e32 v114, v114, v142, vcc
	v_cmp_class_f32_e32 vcc, v141, v229
	s_nop 1
	v_cndmask_b32_e32 v114, v114, v141, vcc
	v_div_scale_f32 v141, s[0:1], v114, v114, v156
	v_rcp_f32_e32 v142, v141
	v_div_scale_f32 v126, vcc, v156, v114, v156
	v_fma_f32 v127, -v141, v142, 1.0
	v_fmac_f32_e32 v142, v127, v142
	v_mul_f32_e32 v127, v126, v142
	v_fma_f32 v128, -v141, v127, v126
	v_fmac_f32_e32 v127, v128, v142
	v_fma_f32 v126, -v141, v127, v126
	v_div_fmas_f32 v126, v126, v142, v127
	v_div_fixup_f32 v114, v126, v114, v156
	v_pk_mul_f32 v[116:117], v[116:117], v[114:115] op_sel_hi:[1,0]
	v_pk_mul_f32 v[118:119], v[118:119], v[114:115] op_sel_hi:[1,0]
	v_pk_mul_f32 v[120:121], v[120:121], v[114:115] op_sel_hi:[1,0]
	v_pk_mul_f32 v[122:123], v[122:123], v[114:115] op_sel_hi:[1,0]
	v_pk_mul_f32 v[126:127], v[134:135], v[118:119]
	v_pk_mul_f32 v[118:119], v[132:133], v[116:117]
	v_pk_mul_f32 v[122:123], v[138:139], v[122:123]
	v_pk_mul_f32 v[120:121], v[136:137], v[120:121]
	s_nop 0
	v_cvt_pk_bf16_f32 v116, v120, v121
	v_cvt_pk_bf16_f32 v117, v122, v123
	v_cvt_pk_bf16_f32 v118, v118, v119
	v_cvt_pk_bf16_f32 v119, v126, v127
	global_store_dwordx4 v[130:131], v[116:119], off offset:256 sc1
	ds_read_b64 v[116:117], v189
	s_waitcnt lgkmcnt(0)
	v_add_f32_e32 v114, v116, v117
	v_fmamk_f32 v114, v114, 0x3c800000, v228
	v_mul_f32_e32 v116, 0x4f800000, v114
	v_cmp_gt_f32_e32 vcc, s36, v114
	v_mul_f32_e32 v118, v140, v157
	s_nop 0
	v_cndmask_b32_e32 v114, v114, v116, vcc
	v_sqrt_f32_e32 v116, v114
	s_nop 0
	v_add_u32_e32 v117, -1, v116
	v_add_u32_e32 v119, 1, v116
	v_fma_f32 v120, -v117, v116, v114
	v_fma_f32 v121, -v119, v116, v114
	v_cmp_ge_f32_e64 s[4:5], 0, v120
	s_nop 1
	v_cndmask_b32_e64 v116, v116, v117, s[4:5]
	v_cmp_lt_f32_e64 s[4:5], 0, v121
	s_nop 1
	v_cndmask_b32_e64 v116, v116, v119, s[4:5]
	v_mul_f32_e32 v117, 0x37800000, v116
	v_cndmask_b32_e32 v116, v116, v117, vcc
	v_cmp_class_f32_e32 vcc, v114, v229
	s_nop 1
	v_cndmask_b32_e32 v114, v116, v114, vcc
	v_div_scale_f32 v116, s[0:1], v114, v114, v118
	v_rcp_f32_e32 v117, v116
	v_div_scale_f32 v119, vcc, v118, v114, v118
	v_fma_f32 v120, -v116, v117, 1.0
	v_fmac_f32_e32 v117, v120, v117
	v_mul_f32_e32 v120, v119, v117
	v_fma_f32 v121, -v116, v120, v119
	v_fmac_f32_e32 v120, v121, v117
	v_fma_f32 v116, -v116, v120, v119
	v_div_fmas_f32 v116, v116, v117, v120
	v_div_fixup_f32 v114, v116, v114, v118
	v_pk_mul_f32 v[108:109], v[108:109], v[114:115] op_sel_hi:[1,0]
	v_pk_mul_f32 v[104:105], v[104:105], v[114:115] op_sel_hi:[1,0]
	v_pk_mul_f32 v[106:107], v[106:107], v[114:115] op_sel_hi:[1,0]
	v_pk_mul_f32 v[110:111], v[110:111], v[114:115] op_sel_hi:[1,0]
	v_pk_mul_f32 v[108:109], v[136:137], v[108:109]
	v_pk_mul_f32 v[116:117], v[134:135], v[106:107]
	v_pk_mul_f32 v[106:107], v[132:133], v[104:105]
	v_pk_mul_f32 v[110:111], v[138:139], v[110:111]
	v_cvt_pk_bf16_f32 v104, v108, v109
	s_nop 0
	v_cvt_pk_bf16_f32 v105, v110, v111
	v_cvt_pk_bf16_f32 v106, v106, v107
	v_cvt_pk_bf16_f32 v107, v116, v117
	ds_read_b64 v[108:109], v189 offset:16
	s_waitcnt lgkmcnt(0)
	v_add_f32_e32 v108, v108, v109
	v_fmamk_f32 v108, v108, 0x3c800000, v228
	v_mul_f32_e32 v109, 0x4f800000, v108
	v_cmp_gt_f32_e32 vcc, s36, v108
	s_nop 1
	v_cndmask_b32_e32 v110, v108, v109, vcc
	v_sqrt_f32_e32 v111, v110
	v_add_u32_e32 v108, s20, v172
	v_ashrrev_i32_e32 v109, 31, v108
	v_lshlrev_b64 v[108:109], 11, v[108:109]
	v_add_u32_e32 v114, -1, v111
	v_add_u32_e32 v116, 1, v111
	v_fma_f32 v117, -v114, v111, v110
	v_fma_f32 v119, -v116, v111, v110
	v_cmp_ge_f32_e64 s[4:5], 0, v117
	v_lshl_add_u64 v[108:109], v[124:125], 0, v[108:109]
	global_store_dwordx4 v[108:109], v[104:107], off sc1
	v_cndmask_b32_e64 v111, v111, v114, s[4:5]
	v_cmp_lt_f32_e64 s[4:5], 0, v119
	s_nop 1
	v_cndmask_b32_e64 v111, v111, v116, s[4:5]
	v_mul_f32_e32 v114, 0x37800000, v111
	v_cndmask_b32_e32 v111, v111, v114, vcc
	v_cmp_class_f32_e32 vcc, v110, v229
	s_nop 1
	v_cndmask_b32_e32 v110, v111, v110, vcc
	v_div_scale_f32 v111, s[0:1], v110, v110, v118
	v_rcp_f32_e32 v114, v111
	s_nop 0
	v_fma_f32 v104, -v111, v114, 1.0
	v_fmac_f32_e32 v114, v104, v114
	v_div_scale_f32 v104, vcc, v118, v110, v118
	v_mul_f32_e32 v105, v104, v114
	v_fma_f32 v106, -v111, v105, v104
	v_fmac_f32_e32 v105, v106, v114
	v_fma_f32 v104, -v111, v105, v104
	v_div_fmas_f32 v104, v104, v114, v105
	v_div_fixup_f32 v104, v104, v110, v118
	v_pk_mul_f32 v[96:97], v[96:97], v[104:105] op_sel_hi:[1,0]
	v_pk_mul_f32 v[98:99], v[98:99], v[104:105] op_sel_hi:[1,0]
	v_pk_mul_f32 v[100:101], v[100:101], v[104:105] op_sel_hi:[1,0]
	v_pk_mul_f32 v[102:103], v[102:103], v[104:105] op_sel_hi:[1,0]
	v_pk_mul_f32 v[104:105], v[134:135], v[98:99]
	v_pk_mul_f32 v[98:99], v[132:133], v[96:97]
	v_pk_mul_f32 v[102:103], v[138:139], v[102:103]
	v_pk_mul_f32 v[100:101], v[136:137], v[100:101]
	s_nop 0
	v_cvt_pk_bf16_f32 v96, v100, v101
	v_cvt_pk_bf16_f32 v97, v102, v103
	v_cvt_pk_bf16_f32 v98, v98, v99
	v_cvt_pk_bf16_f32 v99, v104, v105
	global_store_dwordx4 v[108:109], v[96:99], off offset:256 sc1
	ds_read_b64 v[96:97], v190
	s_nop 0
	v_mul_f32_e32 v98, v140, v154
	s_waitcnt lgkmcnt(0)
; #define PG8_LAS __attribute__((address_space(3)))
; __device__ __forceinline__ unsigned cvt_pk_bf16(float lo, float hi) { unsigned r; asm volatile("v_cvt_pk_bf16_f32 %0, %1, %2" : "=v"(r) : "v"(lo), "v"(hi)); return r; }
;     __device__ __forceinline__ void operator()(const f32x4 (&acc)[2][2][4][2], const Unit& u, int wr, int wc, int fr, int fq) const {
;     ...
;             for (int ai = 0; ai < 2; ++ai)
; #pragma unroll
;                 for (int m = 0; m < 4; ++m) { const int rl = ai * HALF + wr * 64 + m * 16 + fr; bf16_t* rowp = base + (size_t)(u.pm * BM + rl) * ldc + col0;
; #pragma unroll
;                     for (int bj = 0; bj < 2; ++bj) { const f32x2 pr = *(const PG8_LAS f32x2*)(xl + (rl * 2 + bj) * 4 + (wc & 2)); const float tot = pr[0] + pr[1];
;                         const float hr = sc * rsv[ai][m] / sqrtf(tot * (1.0f / 64.0f) + 1e-6f);
;                         const f32x4 v0 = acc[ai][bj][m][0] * hr * g0, v1 = acc[ai][bj][m][1] * hr * g1;
;                         u32x4 w; w.x = cvt_pk_bf16(v0[0], v0[1]); w.y = cvt_pk_bf16(v0[2], v0[3]); w.z = cvt_pk_bf16(v1[0], v1[1]); w.w = cvt_pk_bf16(v1[2], v1[3]);
;                         *(u32x4*)(rowp + bj * HALF) = w; }
	v_add_f32_e32 v96, v96, v97
	v_fmamk_f32 v96, v96, 0x3c800000, v228
	v_mul_f32_e32 v97, 0x4f800000, v96
	v_cmp_gt_f32_e32 vcc, s36, v96
	s_nop 1
	v_cndmask_b32_e32 v96, v96, v97, vcc
	v_sqrt_f32_e32 v97, v96
	s_nop 0
	v_add_u32_e32 v99, -1, v97
	v_fma_f32 v100, -v99, v97, v96
	v_cmp_ge_f32_e64 s[4:5], 0, v100
	v_add_u32_e32 v100, 1, v97
	s_nop 0
	v_cndmask_b32_e64 v99, v97, v99, s[4:5]
	v_fma_f32 v97, -v100, v97, v96
	v_cmp_lt_f32_e64 s[4:5], 0, v97
	s_nop 1
	v_cndmask_b32_e64 v97, v99, v100, s[4:5]
	v_mul_f32_e32 v99, 0x37800000, v97
	v_cndmask_b32_e32 v97, v97, v99, vcc
	v_cmp_class_f32_e32 vcc, v96, v229
	s_nop 1
	v_cndmask_b32_e32 v96, v97, v96, vcc
	v_div_scale_f32 v97, s[0:1], v96, v96, v98
	v_rcp_f32_e32 v99, v97
	s_nop 0
	v_fma_f32 v100, -v97, v99, 1.0
	v_fmac_f32_e32 v99, v100, v99
	v_div_scale_f32 v100, vcc, v98, v96, v98
	v_mul_f32_e32 v101, v100, v99
	v_fma_f32 v102, -v97, v101, v100
	v_fmac_f32_e32 v101, v102, v99
	v_fma_f32 v97, -v97, v101, v100
	v_div_fmas_f32 v97, v97, v99, v101
	v_div_fixup_f32 v96, v97, v96, v98
	v_pk_mul_f32 v[92:93], v[92:93], v[96:97] op_sel_hi:[1,0]
	v_pk_mul_f32 v[88:89], v[88:89], v[96:97] op_sel_hi:[1,0]
	v_pk_mul_f32 v[90:91], v[90:91], v[96:97] op_sel_hi:[1,0]
	v_pk_mul_f32 v[94:95], v[94:95], v[96:97] op_sel_hi:[1,0]
	v_pk_mul_f32 v[92:93], v[136:137], v[92:93]
	v_pk_mul_f32 v[96:97], v[134:135], v[90:91]
	v_pk_mul_f32 v[90:91], v[132:133], v[88:89]
	v_pk_mul_f32 v[94:95], v[138:139], v[94:95]
	v_cvt_pk_bf16_f32 v88, v92, v93
	s_nop 0
	v_cvt_pk_bf16_f32 v89, v94, v95
	v_cvt_pk_bf16_f32 v90, v90, v91
	v_cvt_pk_bf16_f32 v91, v96, v97
	ds_read_b64 v[92:93], v190 offset:16
	s_waitcnt lgkmcnt(0)
	v_add_f32_e32 v92, v92, v93
	v_fmamk_f32 v92, v92, 0x3c800000, v228
	v_mul_f32_e32 v93, 0x4f800000, v92
	v_cmp_gt_f32_e32 vcc, s36, v92
	s_nop 1
	v_cndmask_b32_e32 v94, v92, v93, vcc
	v_sqrt_f32_e32 v95, v94
	v_add_u32_e32 v92, s20, v173
	v_ashrrev_i32_e32 v93, 31, v92
	v_lshlrev_b64 v[92:93], 11, v[92:93]
	v_add_u32_e32 v96, -1, v95
	v_fma_f32 v97, -v96, v95, v94
	v_cmp_ge_f32_e64 s[4:5], 0, v97
	v_add_u32_e32 v97, 1, v95
	v_lshl_add_u64 v[92:93], v[124:125], 0, v[92:93]
	v_cndmask_b32_e64 v96, v95, v96, s[4:5]
	v_fma_f32 v95, -v97, v95, v94
	v_cmp_lt_f32_e64 s[4:5], 0, v95
	global_store_dwordx4 v[92:93], v[88:91], off sc1
	s_nop 0
	v_cndmask_b32_e64 v95, v96, v97, s[4:5]
	v_mul_f32_e32 v96, 0x37800000, v95
	v_cndmask_b32_e32 v95, v95, v96, vcc
	v_cmp_class_f32_e32 vcc, v94, v229
	s_nop 1
	v_cndmask_b32_e32 v94, v95, v94, vcc
	v_div_scale_f32 v95, s[0:1], v94, v94, v98
	v_rcp_f32_e32 v96, v95
	s_nop 0
	v_fma_f32 v88, -v95, v96, 1.0
	v_fmac_f32_e32 v96, v88, v96
	v_div_scale_f32 v88, vcc, v98, v94, v98
	v_mul_f32_e32 v89, v88, v96
	v_fma_f32 v90, -v95, v89, v88
	v_fmac_f32_e32 v89, v90, v96
	v_fma_f32 v88, -v95, v89, v88
	v_div_fmas_f32 v88, v88, v96, v89
	v_div_fixup_f32 v88, v88, v94, v98
	v_pk_mul_f32 v[80:81], v[80:81], v[88:89] op_sel_hi:[1,0]
	v_pk_mul_f32 v[82:83], v[82:83], v[88:89] op_sel_hi:[1,0]
	v_pk_mul_f32 v[84:85], v[84:85], v[88:89] op_sel_hi:[1,0]
	v_pk_mul_f32 v[86:87], v[86:87], v[88:89] op_sel_hi:[1,0]
	v_pk_mul_f32 v[88:89], v[134:135], v[82:83]
	v_pk_mul_f32 v[82:83], v[132:133], v[80:81]
	v_pk_mul_f32 v[86:87], v[138:139], v[86:87]
	v_pk_mul_f32 v[84:85], v[136:137], v[84:85]
	s_nop 0
	v_cvt_pk_bf16_f32 v80, v84, v85
	v_cvt_pk_bf16_f32 v81, v86, v87
	v_cvt_pk_bf16_f32 v82, v82, v83
	v_cvt_pk_bf16_f32 v83, v88, v89
	global_store_dwordx4 v[92:93], v[80:83], off offset:256 sc1
	ds_read_b64 v[80:81], v191
	s_nop 0
	v_mul_f32_e32 v82, v140, v155
	s_waitcnt lgkmcnt(0)
	v_add_f32_e32 v80, v80, v81
	v_fmamk_f32 v80, v80, 0x3c800000, v228
	v_mul_f32_e32 v81, 0x4f800000, v80
	v_cmp_gt_f32_e32 vcc, s36, v80
	s_nop 1
	v_cndmask_b32_e32 v80, v80, v81, vcc
	v_sqrt_f32_e32 v81, v80
	s_nop 0
	v_add_u32_e32 v83, -1, v81
	v_fma_f32 v84, -v83, v81, v80
	v_cmp_ge_f32_e64 s[4:5], 0, v84
	v_add_u32_e32 v84, 1, v81
	s_nop 0
	v_cndmask_b32_e64 v83, v81, v83, s[4:5]
	v_fma_f32 v81, -v84, v81, v80
	v_cmp_lt_f32_e64 s[4:5], 0, v81
	s_nop 1
	v_cndmask_b32_e64 v81, v83, v84, s[4:5]
	v_mul_f32_e32 v83, 0x37800000, v81
	v_cndmask_b32_e32 v81, v81, v83, vcc
	v_cmp_class_f32_e32 vcc, v80, v229
	s_nop 1
	v_cndmask_b32_e32 v80, v81, v80, vcc
	v_div_scale_f32 v81, s[0:1], v80, v80, v82
	v_rcp_f32_e32 v83, v81
	s_nop 0
	v_fma_f32 v84, -v81, v83, 1.0
	v_fmac_f32_e32 v83, v84, v83
	v_div_scale_f32 v84, vcc, v82, v80, v82
	v_mul_f32_e32 v85, v84, v83
	v_fma_f32 v86, -v81, v85, v84
	v_fmac_f32_e32 v85, v86, v83
	v_fma_f32 v81, -v81, v85, v84
	v_div_fmas_f32 v81, v81, v83, v85
	v_div_fixup_f32 v80, v81, v80, v82
	v_pk_mul_f32 v[76:77], v[76:77], v[80:81] op_sel_hi:[1,0]
	v_pk_mul_f32 v[72:73], v[72:73], v[80:81] op_sel_hi:[1,0]
	v_pk_mul_f32 v[74:75], v[74:75], v[80:81] op_sel_hi:[1,0]
	v_pk_mul_f32 v[78:79], v[78:79], v[80:81] op_sel_hi:[1,0]
	v_pk_mul_f32 v[76:77], v[136:137], v[76:77]
	v_pk_mul_f32 v[80:81], v[134:135], v[74:75]
	v_pk_mul_f32 v[74:75], v[132:133], v[72:73]
	v_pk_mul_f32 v[78:79], v[138:139], v[78:79]
	v_cvt_pk_bf16_f32 v72, v76, v77
	s_nop 0
	v_cvt_pk_bf16_f32 v73, v78, v79
	v_cvt_pk_bf16_f32 v74, v74, v75
	v_cvt_pk_bf16_f32 v75, v80, v81
	ds_read_b64 v[76:77], v191 offset:16
	s_waitcnt lgkmcnt(0)
; #define PG8_LAS __attribute__((address_space(3)))
; __device__ __forceinline__ unsigned cvt_pk_bf16(float lo, float hi) { unsigned r; asm volatile("v_cvt_pk_bf16_f32 %0, %1, %2" : "=v"(r) : "v"(lo), "v"(hi)); return r; }
;     __device__ __forceinline__ void operator()(const f32x4 (&acc)[2][2][4][2], const Unit& u, int wr, int wc, int fr, int fq) const {
;     ...
;             for (int ai = 0; ai < 2; ++ai)
; #pragma unroll
;                 for (int m = 0; m < 4; ++m) { const int rl = ai * HALF + wr * 64 + m * 16 + fr; bf16_t* rowp = base + (size_t)(u.pm * BM + rl) * ldc + col0;
; #pragma unroll
;                     for (int bj = 0; bj < 2; ++bj) { const f32x2 pr = *(const PG8_LAS f32x2*)(xl + (rl * 2 + bj) * 4 + (wc & 2)); const float tot = pr[0] + pr[1];
;                         const float hr = sc * rsv[ai][m] / sqrtf(tot * (1.0f / 64.0f) + 1e-6f);
;                         const f32x4 v0 = acc[ai][bj][m][0] * hr * g0, v1 = acc[ai][bj][m][1] * hr * g1;
;                         u32x4 w; w.x = cvt_pk_bf16(v0[0], v0[1]); w.y = cvt_pk_bf16(v0[2], v0[3]); w.z = cvt_pk_bf16(v1[0], v1[1]); w.w = cvt_pk_bf16(v1[2], v1[3]);
;                         *(u32x4*)(rowp + bj * HALF) = w; }
	v_add_f32_e32 v76, v76, v77
	v_fmamk_f32 v76, v76, 0x3c800000, v228
	v_mul_f32_e32 v77, 0x4f800000, v76
	v_cmp_gt_f32_e32 vcc, s36, v76
	s_nop 1
	v_cndmask_b32_e32 v78, v76, v77, vcc
	v_sqrt_f32_e32 v79, v78
	v_add_u32_e32 v76, s20, v174
	v_ashrrev_i32_e32 v77, 31, v76
	v_lshlrev_b64 v[76:77], 11, v[76:77]
	v_add_u32_e32 v80, -1, v79
	v_fma_f32 v81, -v80, v79, v78
	v_cmp_ge_f32_e64 s[4:5], 0, v81
	v_add_u32_e32 v81, 1, v79
	v_lshl_add_u64 v[76:77], v[124:125], 0, v[76:77]
	v_cndmask_b32_e64 v80, v79, v80, s[4:5]
	v_fma_f32 v79, -v81, v79, v78
	v_cmp_lt_f32_e64 s[4:5], 0, v79
	global_store_dwordx4 v[76:77], v[72:75], off sc1
	s_nop 0
	v_cndmask_b32_e64 v79, v80, v81, s[4:5]
	v_mul_f32_e32 v80, 0x37800000, v79
	v_cndmask_b32_e32 v79, v79, v80, vcc
	v_cmp_class_f32_e32 vcc, v78, v229
	s_nop 1
	v_cndmask_b32_e32 v78, v79, v78, vcc
	v_div_scale_f32 v79, s[0:1], v78, v78, v82
	v_rcp_f32_e32 v80, v79
	s_nop 0
	v_fma_f32 v72, -v79, v80, 1.0
	v_fmac_f32_e32 v80, v72, v80
	v_div_scale_f32 v72, vcc, v82, v78, v82
	v_mul_f32_e32 v73, v72, v80
	v_fma_f32 v74, -v79, v73, v72
	v_fmac_f32_e32 v73, v74, v80
	v_fma_f32 v72, -v79, v73, v72
	v_div_fmas_f32 v72, v72, v80, v73
	v_div_fixup_f32 v72, v72, v78, v82
	v_pk_mul_f32 v[64:65], v[64:65], v[72:73] op_sel_hi:[1,0]
	v_pk_mul_f32 v[66:67], v[66:67], v[72:73] op_sel_hi:[1,0]
	v_pk_mul_f32 v[68:69], v[68:69], v[72:73] op_sel_hi:[1,0]
	v_pk_mul_f32 v[70:71], v[70:71], v[72:73] op_sel_hi:[1,0]
	v_pk_mul_f32 v[72:73], v[134:135], v[66:67]
	v_pk_mul_f32 v[66:67], v[132:133], v[64:65]
	v_pk_mul_f32 v[70:71], v[138:139], v[70:71]
	v_pk_mul_f32 v[68:69], v[136:137], v[68:69]
	s_nop 0
	v_cvt_pk_bf16_f32 v64, v68, v69
	v_cvt_pk_bf16_f32 v65, v70, v71
	v_cvt_pk_bf16_f32 v66, v66, v67
	v_cvt_pk_bf16_f32 v67, v72, v73
	global_store_dwordx4 v[76:77], v[64:67], off offset:256 sc1
	ds_read_b64 v[64:65], v192
	s_nop 0
	v_mul_f32_e32 v66, v140, v162
	s_waitcnt lgkmcnt(0)
	v_add_f32_e32 v64, v64, v65
	v_fmamk_f32 v64, v64, 0x3c800000, v228
	v_mul_f32_e32 v65, 0x4f800000, v64
	v_cmp_gt_f32_e32 vcc, s36, v64
	s_nop 1
	v_cndmask_b32_e32 v64, v64, v65, vcc
	v_sqrt_f32_e32 v65, v64
	s_nop 0
	v_add_u32_e32 v67, -1, v65
	v_fma_f32 v68, -v67, v65, v64
	v_cmp_ge_f32_e64 s[4:5], 0, v68
	v_add_u32_e32 v68, 1, v65
	s_nop 0
	v_cndmask_b32_e64 v67, v65, v67, s[4:5]
	v_fma_f32 v65, -v68, v65, v64
	v_cmp_lt_f32_e64 s[4:5], 0, v65
	s_nop 1
	v_cndmask_b32_e64 v65, v67, v68, s[4:5]
	v_mul_f32_e32 v67, 0x37800000, v65
	v_cndmask_b32_e32 v65, v65, v67, vcc
	v_cmp_class_f32_e32 vcc, v64, v229
	s_nop 1
	v_cndmask_b32_e32 v64, v65, v64, vcc
	v_div_scale_f32 v65, s[0:1], v64, v64, v66
	v_rcp_f32_e32 v67, v65
	s_nop 0
	v_fma_f32 v68, -v65, v67, 1.0
	v_fmac_f32_e32 v67, v68, v67
	v_div_scale_f32 v68, vcc, v66, v64, v66
	v_mul_f32_e32 v69, v68, v67
	v_fma_f32 v70, -v65, v69, v68
	v_fmac_f32_e32 v69, v70, v67
	v_fma_f32 v65, -v65, v69, v68
	v_div_fmas_f32 v65, v65, v67, v69
	v_div_fixup_f32 v64, v65, v64, v66
	v_pk_mul_f32 v[60:61], v[60:61], v[64:65] op_sel_hi:[1,0]
	v_pk_mul_f32 v[56:57], v[56:57], v[64:65] op_sel_hi:[1,0]
	v_pk_mul_f32 v[58:59], v[58:59], v[64:65] op_sel_hi:[1,0]
	v_pk_mul_f32 v[62:63], v[62:63], v[64:65] op_sel_hi:[1,0]
	v_pk_mul_f32 v[60:61], v[136:137], v[60:61]
	v_pk_mul_f32 v[64:65], v[134:135], v[58:59]
	v_pk_mul_f32 v[58:59], v[132:133], v[56:57]
	v_pk_mul_f32 v[62:63], v[138:139], v[62:63]
	v_cvt_pk_bf16_f32 v56, v60, v61
	s_nop 0
	v_cvt_pk_bf16_f32 v57, v62, v63
	v_cvt_pk_bf16_f32 v58, v58, v59
	v_cvt_pk_bf16_f32 v59, v64, v65
	ds_read_b64 v[60:61], v192 offset:16
	s_waitcnt lgkmcnt(0)
	v_add_f32_e32 v60, v60, v61
	v_fmamk_f32 v60, v60, 0x3c800000, v228
	v_mul_f32_e32 v61, 0x4f800000, v60
	v_cmp_gt_f32_e32 vcc, s36, v60
	s_nop 1
	v_cndmask_b32_e32 v62, v60, v61, vcc
	v_sqrt_f32_e32 v63, v62
	v_add_u32_e32 v60, s20, v175
	v_ashrrev_i32_e32 v61, 31, v60
	v_lshlrev_b64 v[60:61], 11, v[60:61]
	v_add_u32_e32 v64, -1, v63
	v_fma_f32 v65, -v64, v63, v62
	v_cmp_ge_f32_e64 s[4:5], 0, v65
	v_add_u32_e32 v65, 1, v63
	v_lshl_add_u64 v[60:61], v[124:125], 0, v[60:61]
	v_cndmask_b32_e64 v64, v63, v64, s[4:5]
	v_fma_f32 v63, -v65, v63, v62
	v_cmp_lt_f32_e64 s[4:5], 0, v63
	global_store_dwordx4 v[60:61], v[56:59], off sc1
	s_nop 0
	v_cndmask_b32_e64 v63, v64, v65, s[4:5]
	v_mul_f32_e32 v64, 0x37800000, v63
	v_cndmask_b32_e32 v63, v63, v64, vcc
	v_cmp_class_f32_e32 vcc, v62, v229
	s_nop 1
	v_cndmask_b32_e32 v62, v63, v62, vcc
	v_div_scale_f32 v63, s[0:1], v62, v62, v66
	v_rcp_f32_e32 v64, v63
	s_nop 0
	v_fma_f32 v56, -v63, v64, 1.0
	v_fmac_f32_e32 v64, v56, v64
	v_div_scale_f32 v56, vcc, v66, v62, v66
	v_mul_f32_e32 v57, v56, v64
	v_fma_f32 v58, -v63, v57, v56
	v_fmac_f32_e32 v57, v58, v64
	v_fma_f32 v56, -v63, v57, v56
	v_div_fmas_f32 v56, v56, v64, v57
	v_div_fixup_f32 v56, v56, v62, v66
	v_pk_mul_f32 v[48:49], v[48:49], v[56:57] op_sel_hi:[1,0]
	v_pk_mul_f32 v[50:51], v[50:51], v[56:57] op_sel_hi:[1,0]
	v_pk_mul_f32 v[52:53], v[52:53], v[56:57] op_sel_hi:[1,0]
	v_pk_mul_f32 v[54:55], v[54:55], v[56:57] op_sel_hi:[1,0]
	v_pk_mul_f32 v[56:57], v[134:135], v[50:51]
	v_pk_mul_f32 v[50:51], v[132:133], v[48:49]
	v_pk_mul_f32 v[54:55], v[138:139], v[54:55]
	v_pk_mul_f32 v[52:53], v[136:137], v[52:53]
	s_nop 0
	v_cvt_pk_bf16_f32 v48, v52, v53
	v_cvt_pk_bf16_f32 v49, v54, v55
	v_cvt_pk_bf16_f32 v50, v50, v51
	v_cvt_pk_bf16_f32 v51, v56, v57
	global_store_dwordx4 v[60:61], v[48:51], off offset:256 sc1
	ds_read_b64 v[48:49], v193
	s_nop 0
	v_mul_f32_e32 v50, v140, v163
	s_waitcnt lgkmcnt(0)
; #define PG8_LAS __attribute__((address_space(3)))
; __device__ __forceinline__ unsigned cvt_pk_bf16(float lo, float hi) { unsigned r; asm volatile("v_cvt_pk_bf16_f32 %0, %1, %2" : "=v"(r) : "v"(lo), "v"(hi)); return r; }
;     __device__ __forceinline__ void operator()(const f32x4 (&acc)[2][2][4][2], const Unit& u, int wr, int wc, int fr, int fq) const {
;     ...
;                 for (int m = 0; m < 4; ++m) { const int rl = ai * HALF + wr * 64 + m * 16 + fr; bf16_t* rowp = base + (size_t)(u.pm * BM + rl) * ldc + col0;
; #pragma unroll
;                     for (int bj = 0; bj < 2; ++bj) { const f32x2 pr = *(const PG8_LAS f32x2*)(xl + (rl * 2 + bj) * 4 + (wc & 2)); const float tot = pr[0] + pr[1];
;                         const float hr = sc * rsv[ai][m] / sqrtf(tot * (1.0f / 64.0f) + 1e-6f);
;                         const f32x4 v0 = acc[ai][bj][m][0] * hr * g0, v1 = acc[ai][bj][m][1] * hr * g1;
;                         u32x4 w; w.x = cvt_pk_bf16(v0[0], v0[1]); w.y = cvt_pk_bf16(v0[2], v0[3]); w.z = cvt_pk_bf16(v1[0], v1[1]); w.w = cvt_pk_bf16(v1[2], v1[3]);
;                         *(u32x4*)(rowp + bj * HALF) = w; }
;                     asm volatile("" ::: "memory"); }
	v_add_f32_e32 v48, v48, v49
	v_fmamk_f32 v48, v48, 0x3c800000, v228
	v_mul_f32_e32 v49, 0x4f800000, v48
	v_cmp_gt_f32_e32 vcc, s36, v48
	s_nop 1
	v_cndmask_b32_e32 v48, v48, v49, vcc
	v_sqrt_f32_e32 v49, v48
	s_nop 0
	v_add_u32_e32 v51, -1, v49
	v_fma_f32 v52, -v51, v49, v48
	v_cmp_ge_f32_e64 s[4:5], 0, v52
	v_add_u32_e32 v52, 1, v49
	s_nop 0
	v_cndmask_b32_e64 v51, v49, v51, s[4:5]
	v_fma_f32 v49, -v52, v49, v48
	v_cmp_lt_f32_e64 s[4:5], 0, v49
	s_nop 1
	v_cndmask_b32_e64 v49, v51, v52, s[4:5]
	v_mul_f32_e32 v51, 0x37800000, v49
	v_cndmask_b32_e32 v49, v49, v51, vcc
	v_cmp_class_f32_e32 vcc, v48, v229
	s_nop 1
	v_cndmask_b32_e32 v48, v49, v48, vcc
	v_div_scale_f32 v49, s[0:1], v48, v48, v50
	v_rcp_f32_e32 v51, v49
	s_nop 0
	v_fma_f32 v52, -v49, v51, 1.0
	v_fmac_f32_e32 v51, v52, v51
	v_div_scale_f32 v52, vcc, v50, v48, v50
	v_mul_f32_e32 v53, v52, v51
	v_fma_f32 v54, -v49, v53, v52
	v_fmac_f32_e32 v53, v54, v51
	v_fma_f32 v49, -v49, v53, v52
	v_div_fmas_f32 v49, v49, v51, v53
	v_div_fixup_f32 v48, v49, v48, v50
	v_pk_mul_f32 v[44:45], v[44:45], v[48:49] op_sel_hi:[1,0]
	v_pk_mul_f32 v[40:41], v[40:41], v[48:49] op_sel_hi:[1,0]
	v_pk_mul_f32 v[42:43], v[42:43], v[48:49] op_sel_hi:[1,0]
	v_pk_mul_f32 v[46:47], v[46:47], v[48:49] op_sel_hi:[1,0]
	v_pk_mul_f32 v[44:45], v[136:137], v[44:45]
	v_pk_mul_f32 v[48:49], v[134:135], v[42:43]
	v_pk_mul_f32 v[42:43], v[132:133], v[40:41]
	v_pk_mul_f32 v[46:47], v[138:139], v[46:47]
	v_cvt_pk_bf16_f32 v40, v44, v45
	s_nop 0
	v_cvt_pk_bf16_f32 v41, v46, v47
	v_cvt_pk_bf16_f32 v42, v42, v43
	v_cvt_pk_bf16_f32 v43, v48, v49
	ds_read_b64 v[44:45], v193 offset:16
	s_waitcnt lgkmcnt(0)
	v_add_f32_e32 v44, v44, v45
	v_fmamk_f32 v44, v44, 0x3c800000, v228
	v_mul_f32_e32 v45, 0x4f800000, v44
	v_cmp_gt_f32_e32 vcc, s36, v44
	s_nop 1
	v_cndmask_b32_e32 v46, v44, v45, vcc
	v_sqrt_f32_e32 v47, v46
	v_add_u32_e32 v44, s20, v176
	v_ashrrev_i32_e32 v45, 31, v44
	v_lshlrev_b64 v[44:45], 11, v[44:45]
	v_add_u32_e32 v48, -1, v47
	v_fma_f32 v49, -v48, v47, v46
	v_cmp_ge_f32_e64 s[4:5], 0, v49
	v_add_u32_e32 v49, 1, v47
	v_lshl_add_u64 v[44:45], v[124:125], 0, v[44:45]
	v_cndmask_b32_e64 v48, v47, v48, s[4:5]
	v_fma_f32 v47, -v49, v47, v46
	v_cmp_lt_f32_e64 s[4:5], 0, v47
	global_store_dwordx4 v[44:45], v[40:43], off sc1
	s_nop 0
	v_cndmask_b32_e64 v47, v48, v49, s[4:5]
	v_mul_f32_e32 v48, 0x37800000, v47
	v_cndmask_b32_e32 v47, v47, v48, vcc
	v_cmp_class_f32_e32 vcc, v46, v229
	s_nop 1
	v_cndmask_b32_e32 v46, v47, v46, vcc
	v_div_scale_f32 v47, s[0:1], v46, v46, v50
	v_rcp_f32_e32 v48, v47
	s_nop 0
	v_fma_f32 v40, -v47, v48, 1.0
	v_fmac_f32_e32 v48, v40, v48
	v_div_scale_f32 v40, vcc, v50, v46, v50
	v_mul_f32_e32 v41, v40, v48
	v_fma_f32 v42, -v47, v41, v40
	v_fmac_f32_e32 v41, v42, v48
	v_fma_f32 v40, -v47, v41, v40
	v_div_fmas_f32 v40, v40, v48, v41
	v_div_fixup_f32 v40, v40, v46, v50
	v_pk_mul_f32 v[32:33], v[32:33], v[40:41] op_sel_hi:[1,0]
	v_pk_mul_f32 v[34:35], v[34:35], v[40:41] op_sel_hi:[1,0]
	v_pk_mul_f32 v[36:37], v[36:37], v[40:41] op_sel_hi:[1,0]
	v_pk_mul_f32 v[38:39], v[38:39], v[40:41] op_sel_hi:[1,0]
	v_pk_mul_f32 v[40:41], v[134:135], v[34:35]
	v_pk_mul_f32 v[34:35], v[132:133], v[32:33]
	v_pk_mul_f32 v[38:39], v[138:139], v[38:39]
	v_pk_mul_f32 v[36:37], v[136:137], v[36:37]
	s_nop 0
	v_cvt_pk_bf16_f32 v32, v36, v37
	v_cvt_pk_bf16_f32 v33, v38, v39
	v_cvt_pk_bf16_f32 v34, v34, v35
	v_cvt_pk_bf16_f32 v35, v40, v41
	global_store_dwordx4 v[44:45], v[32:35], off offset:256 sc1
	ds_read_b64 v[32:33], v194
	s_nop 0
	v_mul_f32_e32 v34, v140, v160
	s_waitcnt lgkmcnt(0)
	v_add_f32_e32 v32, v32, v33
	v_fmamk_f32 v32, v32, 0x3c800000, v228
	v_mul_f32_e32 v33, 0x4f800000, v32
	v_cmp_gt_f32_e32 vcc, s36, v32
	s_nop 1
	v_cndmask_b32_e32 v32, v32, v33, vcc
	v_sqrt_f32_e32 v33, v32
	s_nop 0
	v_add_u32_e32 v35, -1, v33
	v_fma_f32 v36, -v35, v33, v32
	v_cmp_ge_f32_e64 s[4:5], 0, v36
	v_add_u32_e32 v36, 1, v33
	s_nop 0
	v_cndmask_b32_e64 v35, v33, v35, s[4:5]
	v_fma_f32 v33, -v36, v33, v32
	v_cmp_lt_f32_e64 s[4:5], 0, v33
	s_nop 1
	v_cndmask_b32_e64 v33, v35, v36, s[4:5]
	v_mul_f32_e32 v35, 0x37800000, v33
	v_cndmask_b32_e32 v33, v33, v35, vcc
	v_cmp_class_f32_e32 vcc, v32, v229
	s_nop 1
	v_cndmask_b32_e32 v32, v33, v32, vcc
	v_div_scale_f32 v33, s[0:1], v32, v32, v34
	v_rcp_f32_e32 v35, v33
	s_nop 0
	v_fma_f32 v36, -v33, v35, 1.0
	v_fmac_f32_e32 v35, v36, v35
	v_div_scale_f32 v36, vcc, v34, v32, v34
	v_mul_f32_e32 v37, v36, v35
	v_fma_f32 v38, -v33, v37, v36
	v_fmac_f32_e32 v37, v38, v35
	v_fma_f32 v33, -v33, v37, v36
	v_div_fmas_f32 v33, v33, v35, v37
	v_div_fixup_f32 v32, v33, v32, v34
	v_pk_mul_f32 v[28:29], v[28:29], v[32:33] op_sel_hi:[1,0]
	v_pk_mul_f32 v[24:25], v[24:25], v[32:33] op_sel_hi:[1,0]
	v_pk_mul_f32 v[26:27], v[26:27], v[32:33] op_sel_hi:[1,0]
	v_pk_mul_f32 v[30:31], v[30:31], v[32:33] op_sel_hi:[1,0]
	v_pk_mul_f32 v[28:29], v[136:137], v[28:29]
	v_pk_mul_f32 v[32:33], v[134:135], v[26:27]
	v_pk_mul_f32 v[26:27], v[132:133], v[24:25]
	v_pk_mul_f32 v[30:31], v[138:139], v[30:31]
	v_cvt_pk_bf16_f32 v24, v28, v29
	s_nop 0
	v_cvt_pk_bf16_f32 v25, v30, v31
	v_cvt_pk_bf16_f32 v26, v26, v27
	v_cvt_pk_bf16_f32 v27, v32, v33
	ds_read_b64 v[28:29], v194 offset:16
	s_waitcnt lgkmcnt(0)
; #define PG8_LAS __attribute__((address_space(3)))
; __device__ __forceinline__ unsigned cvt_pk_bf16(float lo, float hi) { unsigned r; asm volatile("v_cvt_pk_bf16_f32 %0, %1, %2" : "=v"(r) : "v"(lo), "v"(hi)); return r; }
;     __device__ __forceinline__ void operator()(const f32x4 (&acc)[2][2][4][2], const Unit& u, int wr, int wc, int fr, int fq) const {
;     ...
;                 for (int m = 0; m < 4; ++m) { const int rl = ai * HALF + wr * 64 + m * 16 + fr; bf16_t* rowp = base + (size_t)(u.pm * BM + rl) * ldc + col0;
; #pragma unroll
;                     for (int bj = 0; bj < 2; ++bj) { const f32x2 pr = *(const PG8_LAS f32x2*)(xl + (rl * 2 + bj) * 4 + (wc & 2)); const float tot = pr[0] + pr[1];
;                         const float hr = sc * rsv[ai][m] / sqrtf(tot * (1.0f / 64.0f) + 1e-6f);
;                         const f32x4 v0 = acc[ai][bj][m][0] * hr * g0, v1 = acc[ai][bj][m][1] * hr * g1;
;                         u32x4 w; w.x = cvt_pk_bf16(v0[0], v0[1]); w.y = cvt_pk_bf16(v0[2], v0[3]); w.z = cvt_pk_bf16(v1[0], v1[1]); w.w = cvt_pk_bf16(v1[2], v1[3]);
;                         *(u32x4*)(rowp + bj * HALF) = w; }
;                     asm volatile("" ::: "memory"); }
	v_add_f32_e32 v28, v28, v29
	v_fmamk_f32 v28, v28, 0x3c800000, v228
	v_mul_f32_e32 v29, 0x4f800000, v28
	v_cmp_gt_f32_e32 vcc, s36, v28
	s_nop 1
	v_cndmask_b32_e32 v30, v28, v29, vcc
	v_sqrt_f32_e32 v31, v30
	v_add_u32_e32 v28, s20, v177
	v_ashrrev_i32_e32 v29, 31, v28
	v_lshlrev_b64 v[28:29], 11, v[28:29]
	v_add_u32_e32 v32, -1, v31
	v_fma_f32 v33, -v32, v31, v30
	v_cmp_ge_f32_e64 s[4:5], 0, v33
	v_add_u32_e32 v33, 1, v31
	v_lshl_add_u64 v[28:29], v[124:125], 0, v[28:29]
	v_cndmask_b32_e64 v32, v31, v32, s[4:5]
	v_fma_f32 v31, -v33, v31, v30
	v_cmp_lt_f32_e64 s[4:5], 0, v31
	global_store_dwordx4 v[28:29], v[24:27], off sc1
	s_nop 0
	v_cndmask_b32_e64 v31, v32, v33, s[4:5]
	v_mul_f32_e32 v32, 0x37800000, v31
	v_cndmask_b32_e32 v31, v31, v32, vcc
	v_cmp_class_f32_e32 vcc, v30, v229
	s_nop 1
	v_cndmask_b32_e32 v30, v31, v30, vcc
	v_div_scale_f32 v31, s[0:1], v30, v30, v34
	v_rcp_f32_e32 v32, v31
	s_nop 0
	v_fma_f32 v24, -v31, v32, 1.0
	v_fmac_f32_e32 v32, v24, v32
	v_div_scale_f32 v24, vcc, v34, v30, v34
	v_mul_f32_e32 v25, v24, v32
	v_fma_f32 v26, -v31, v25, v24
	v_fmac_f32_e32 v25, v26, v32
	v_fma_f32 v24, -v31, v25, v24
	v_div_fmas_f32 v24, v24, v32, v25
	v_div_fixup_f32 v24, v24, v30, v34
	v_pk_mul_f32 v[16:17], v[16:17], v[24:25] op_sel_hi:[1,0]
	v_pk_mul_f32 v[18:19], v[18:19], v[24:25] op_sel_hi:[1,0]
	v_pk_mul_f32 v[20:21], v[20:21], v[24:25] op_sel_hi:[1,0]
	v_pk_mul_f32 v[22:23], v[22:23], v[24:25] op_sel_hi:[1,0]
	v_pk_mul_f32 v[24:25], v[134:135], v[18:19]
	v_pk_mul_f32 v[18:19], v[132:133], v[16:17]
	v_pk_mul_f32 v[22:23], v[138:139], v[22:23]
	v_pk_mul_f32 v[20:21], v[136:137], v[20:21]
	s_nop 0
	v_cvt_pk_bf16_f32 v16, v20, v21
	v_cvt_pk_bf16_f32 v17, v22, v23
	v_cvt_pk_bf16_f32 v18, v18, v19
	v_cvt_pk_bf16_f32 v19, v24, v25
	global_store_dwordx4 v[28:29], v[16:19], off offset:256 sc1
	ds_read_b64 v[16:17], v195
	s_nop 0
	v_mul_f32_e32 v18, v140, v161
	s_waitcnt lgkmcnt(0)
	v_add_f32_e32 v16, v16, v17
	v_fmamk_f32 v16, v16, 0x3c800000, v228
	v_mul_f32_e32 v17, 0x4f800000, v16
	v_cmp_gt_f32_e32 vcc, s36, v16
	s_nop 1
	v_cndmask_b32_e32 v16, v16, v17, vcc
	v_sqrt_f32_e32 v17, v16
	s_nop 0
	v_add_u32_e32 v19, -1, v17
	v_fma_f32 v20, -v19, v17, v16
	v_cmp_ge_f32_e64 s[4:5], 0, v20
	v_add_u32_e32 v20, 1, v17
	s_nop 0
	v_cndmask_b32_e64 v19, v17, v19, s[4:5]
	v_fma_f32 v17, -v20, v17, v16
	v_cmp_lt_f32_e64 s[4:5], 0, v17
	s_nop 1
	v_cndmask_b32_e64 v17, v19, v20, s[4:5]
	v_mul_f32_e32 v19, 0x37800000, v17
	v_cndmask_b32_e32 v17, v17, v19, vcc
	v_cmp_class_f32_e32 vcc, v16, v229
	s_nop 1
	v_cndmask_b32_e32 v16, v17, v16, vcc
	v_div_scale_f32 v17, s[0:1], v16, v16, v18
	v_rcp_f32_e32 v19, v17
	s_nop 0
	v_fma_f32 v20, -v17, v19, 1.0
	v_fmac_f32_e32 v19, v20, v19
	v_div_scale_f32 v20, vcc, v18, v16, v18
	v_mul_f32_e32 v21, v20, v19
	v_fma_f32 v22, -v17, v21, v20
	v_fmac_f32_e32 v21, v22, v19
	v_fma_f32 v17, -v17, v21, v20
	v_div_fmas_f32 v17, v17, v19, v21
	v_div_fixup_f32 v16, v17, v16, v18
	v_pk_mul_f32 v[12:13], v[12:13], v[16:17] op_sel_hi:[1,0]
	v_pk_mul_f32 v[8:9], v[8:9], v[16:17] op_sel_hi:[1,0]
	v_pk_mul_f32 v[10:11], v[10:11], v[16:17] op_sel_hi:[1,0]
	v_pk_mul_f32 v[14:15], v[14:15], v[16:17] op_sel_hi:[1,0]
	v_pk_mul_f32 v[12:13], v[136:137], v[12:13]
	v_pk_mul_f32 v[16:17], v[134:135], v[10:11]
	v_pk_mul_f32 v[10:11], v[132:133], v[8:9]
	v_pk_mul_f32 v[14:15], v[138:139], v[14:15]
	v_cvt_pk_bf16_f32 v8, v12, v13
	s_nop 0
	v_cvt_pk_bf16_f32 v9, v14, v15
	v_cvt_pk_bf16_f32 v10, v10, v11
	v_cvt_pk_bf16_f32 v11, v16, v17
	ds_read_b64 v[12:13], v195 offset:16
	s_waitcnt lgkmcnt(0)
	v_add_f32_e32 v12, v12, v13
	v_fmamk_f32 v12, v12, 0x3c800000, v228
	v_mul_f32_e32 v13, 0x4f800000, v12
	v_cmp_gt_f32_e32 vcc, s36, v12
	s_nop 1
	v_cndmask_b32_e32 v14, v12, v13, vcc
	v_sqrt_f32_e32 v15, v14
	v_add_u32_e32 v12, s20, v178
	v_ashrrev_i32_e32 v13, 31, v12
	v_lshlrev_b64 v[12:13], 11, v[12:13]
	v_add_u32_e32 v16, -1, v15
	v_fma_f32 v17, -v16, v15, v14
	v_cmp_ge_f32_e64 s[4:5], 0, v17
	v_add_u32_e32 v17, 1, v15
	v_lshl_add_u64 v[12:13], v[124:125], 0, v[12:13]
	v_cndmask_b32_e64 v16, v15, v16, s[4:5]
	v_fma_f32 v15, -v17, v15, v14
	v_cmp_lt_f32_e64 s[4:5], 0, v15
	global_store_dwordx4 v[12:13], v[8:11], off sc1
	s_nop 0
	v_cndmask_b32_e64 v15, v16, v17, s[4:5]
	v_mul_f32_e32 v16, 0x37800000, v15
	v_cndmask_b32_e32 v15, v15, v16, vcc
	v_cmp_class_f32_e32 vcc, v14, v229
	s_nop 1
	v_cndmask_b32_e32 v14, v15, v14, vcc
	v_div_scale_f32 v15, s[0:1], v14, v14, v18
	v_rcp_f32_e32 v16, v15
	s_nop 0
	v_fma_f32 v8, -v15, v16, 1.0
	v_fmac_f32_e32 v16, v8, v16
	v_div_scale_f32 v8, vcc, v18, v14, v18
	v_mul_f32_e32 v9, v8, v16
	v_fma_f32 v10, -v15, v9, v8
	v_fmac_f32_e32 v9, v10, v16
	v_fma_f32 v8, -v15, v9, v8
	v_div_fmas_f32 v8, v8, v16, v9
	v_div_fixup_f32 v8, v8, v14, v18
	v_pk_mul_f32 v[0:1], v[0:1], v[8:9] op_sel_hi:[1,0]
	v_pk_mul_f32 v[2:3], v[2:3], v[8:9] op_sel_hi:[1,0]
	v_pk_mul_f32 v[4:5], v[4:5], v[8:9] op_sel_hi:[1,0]
	v_pk_mul_f32 v[6:7], v[6:7], v[8:9] op_sel_hi:[1,0]
	v_pk_mul_f32 v[8:9], v[134:135], v[2:3]
	v_pk_mul_f32 v[2:3], v[132:133], v[0:1]
	v_pk_mul_f32 v[6:7], v[138:139], v[6:7]
	v_pk_mul_f32 v[4:5], v[136:137], v[4:5]
	s_nop 0
	v_cvt_pk_bf16_f32 v0, v4, v5
	v_cvt_pk_bf16_f32 v1, v6, v7
	v_cvt_pk_bf16_f32 v2, v2, v3
	v_cvt_pk_bf16_f32 v3, v8, v9
	global_store_dwordx4 v[12:13], v[0:3], off offset:256 sc1
	s_andn2_b64 vcc, exec, s[40:41]
	s_mov_b64 s[0:1], -1
	s_cbranch_vccnz .LBB0_216

; __device__ __forceinline__ unsigned cvt_pk_bf16(float lo, float hi) { unsigned r; asm volatile("v_cvt_pk_bf16_f32 %0, %1, %2" : "=v"(r) : "v"(lo), "v"(hi)); return r; }
;     __device__ __forceinline__ void operator()(const f32x4 (&acc)[2][2][4][2], const Unit& u, int wr, int wc, int fr, int fq) const {
;     ...
;         for (int ai = 0; ai < 2; ++ai)
; #pragma unroll
;             for (int m = 0; m < 4; ++m) { const int row = row0 + ai * HALF + m * 16; bf16_t* rowp = base + (size_t)row * ldc + col0; float s1 = 0.f, s2 = 0.f;
;                 const float rs = rsv[ai][m];
; #pragma unroll
;                 for (int bj = 0; bj < 2; ++bj) { f32x4 v0 = acc[ai][bj][m][0] * rs, v1 = acc[ai][bj][m][1] * rs;
;                     if (ACT == 1) {
; #pragma unroll
;                         for (int e = 0; e < 4; ++e) { v0[e] = gelu_tanh(v0[e]); v1[e] = gelu_tanh(v1[e]); }
;                         s1 += ((v0[0] + v0[1]) + (v0[2] + v0[3])) + ((v1[0] + v1[1]) + (v1[2] + v1[3]));
;                         s2 += ((v0[0] * v0[0] + v0[1] * v0[1]) + (v0[2] * v0[2] + v0[3] * v0[3])) + ((v1[0] * v1[0] + v1[1] * v1[1]) + (v1[2] * v1[2] + v1[3] * v1[3]));
;                     }
;                     if (ACT == 2) {
; #pragma unroll
;                         for (int e = 0; e < 4; ++e) { const float a = __builtin_fmaxf(v0[e], 0.f), b = __builtin_fmaxf(v1[e], 0.f); v0[e] = a * a; v1[e] = b * b; }
;                     }
;                     u32x4 w; w.x = cvt_pk_bf16(v0[0], v0[1]); w.y = cvt_pk_bf16(v0[2], v0[3]); w.z = cvt_pk_bf16(v1[0], v1[1]); w.w = cvt_pk_bf16(v1[2], v1[3]);
;                     *(u32x4*)(rowp + bj * HALF) = w; }
.LBB0_620:
	v_pk_mul_f32 v[128:129], v[128:129], v[174:175] op_sel_hi:[1,0]
	v_pk_mul_f32 v[142:143], v[126:127], v[174:175] op_sel_hi:[1,0]
	v_pk_mul_f32 v[126:127], v[124:125], v[174:175] op_sel_hi:[1,0]
	v_mul_f32_e32 v124, 0x3d372713, v128
	v_fma_f32 v124, v128, v124, 1.0
	v_mul_f32_e32 v124, v128, v124
	v_mul_f32_e32 v124, 0xc0135761, v124
	v_exp_f32_e32 v124, v124
	v_pk_mul_f32 v[130:131], v[130:131], v[174:175] op_sel_hi:[1,0]
	v_mul_f32_e32 v125, 0x3d372713, v126
	v_fma_f32 v125, v126, v125, 1.0
	v_add_f32_e32 v124, 1.0, v124
	v_rcp_f32_e32 v124, v124
	v_mul_f32_e32 v125, v126, v125
	v_mul_f32_e32 v125, 0xc0135761, v125
	v_exp_f32_e32 v125, v125
	v_mul_f32_e32 v124, v128, v124
	v_mul_f32_e32 v128, 0x3d372713, v127
	v_fma_f32 v128, v127, v128, 1.0
	v_mul_f32_e32 v128, v127, v128
	v_mul_f32_e32 v128, 0xc0135761, v128
	v_exp_f32_e32 v128, v128
	v_add_f32_e32 v125, 1.0, v125
	v_rcp_f32_e32 v125, v125
	v_pk_mul_f32 v[120:121], v[120:121], v[174:175] op_sel_hi:[1,0]
	v_add_f32_e32 v128, 1.0, v128
	v_rcp_f32_e32 v128, v128
	v_mul_f32_e32 v125, v126, v125
	v_mul_f32_e32 v126, 0x3d372713, v129
	v_fma_f32 v126, v129, v126, 1.0
	v_mul_f32_e32 v127, v127, v128
	v_mul_f32_e32 v128, 0x3d372713, v130
	v_fma_f32 v128, v130, v128, 1.0
	v_mul_f32_e32 v128, v130, v128
	v_mul_f32_e32 v128, 0xc0135761, v128
	v_exp_f32_e32 v128, v128
	v_mul_f32_e32 v126, v129, v126
	v_mul_f32_e32 v126, 0xc0135761, v126
	v_exp_f32_e32 v126, v126
	v_add_f32_e32 v128, 1.0, v128
	v_rcp_f32_e32 v128, v128
	v_pk_mul_f32 v[122:123], v[122:123], v[174:175] op_sel_hi:[1,0]
	v_add_f32_e32 v126, 1.0, v126
	v_rcp_f32_e32 v126, v126
	v_mul_f32_e32 v128, v130, v128
	v_mul_f32_e32 v130, 0x3d372713, v131
	v_fma_f32 v130, v131, v130, 1.0
	v_mul_f32_e32 v130, v131, v130
	v_mul_f32_e32 v130, 0xc0135761, v130
	v_exp_f32_e32 v130, v130
	v_mul_f32_e32 v126, v129, v126
	v_mul_f32_e32 v129, 0x3d372713, v142
	v_fma_f32 v129, v142, v129, 1.0
	v_add_f32_e32 v130, 1.0, v130
	v_rcp_f32_e32 v130, v130
	v_mul_f32_e32 v129, v142, v129
	v_mul_f32_e32 v129, 0xc0135761, v129
	v_exp_f32_e32 v129, v129
	v_mul_f32_e32 v130, v131, v130
	v_mul_f32_e32 v131, 0x3d372713, v143
	v_fma_f32 v131, v143, v131, 1.0
	v_mul_f32_e32 v131, v143, v131
	v_mul_f32_e32 v131, 0xc0135761, v131
	v_exp_f32_e32 v131, v131
	v_add_f32_e32 v129, 1.0, v129
	v_rcp_f32_e32 v129, v129
	v_lshl_or_b32 v134, s60, 8, v177
	v_add_f32_e32 v131, 1.0, v131
	v_rcp_f32_e32 v131, v131
	v_mul_f32_e32 v129, v142, v129
	v_ashrrev_i32_e32 v135, 31, v134
	s_cmp_gt_i32 s60, 7
	v_mul_f32_e32 v131, v143, v131
	v_pk_mul_f32 v[142:143], v[118:119], v[174:175] op_sel_hi:[1,0]
	v_pk_mul_f32 v[118:119], v[116:117], v[174:175] op_sel_hi:[1,0]
	v_mul_f32_e32 v116, 0x3d372713, v120
	v_fma_f32 v116, v120, v116, 1.0
	v_mul_f32_e32 v116, v120, v116
	v_mul_f32_e32 v116, 0xc0135761, v116
	v_exp_f32_e32 v116, v116
	v_mul_f32_e32 v117, 0x3d372713, v118
	v_fma_f32 v117, v118, v117, 1.0
	v_mul_f32_e32 v117, v118, v117
	v_add_f32_e32 v116, 1.0, v116
	v_rcp_f32_e32 v116, v116
	v_mul_f32_e32 v117, 0xc0135761, v117
	v_exp_f32_e32 v117, v117
	v_lshl_add_u64 v[134:135], v[134:135], 1, s[42:43]
	v_mul_f32_e32 v116, v120, v116
	v_mul_f32_e32 v120, 0x3d372713, v119
	v_fma_f32 v120, v119, v120, 1.0
	v_mul_f32_e32 v120, v119, v120
	v_mul_f32_e32 v120, 0xc0135761, v120
	v_exp_f32_e32 v120, v120
	v_add_f32_e32 v117, 1.0, v117
	v_rcp_f32_e32 v117, v117
	v_lshlrev_b64 v[138:139], 13, v[164:165]
	v_add_f32_e32 v120, 1.0, v120
	v_rcp_f32_e32 v120, v120
	v_mul_f32_e32 v117, v118, v117
	v_mul_f32_e32 v118, 0x3d372713, v121
	v_fma_f32 v118, v121, v118, 1.0
	v_mul_f32_e32 v119, v119, v120
	v_mul_f32_e32 v120, 0x3d372713, v122
	v_fma_f32 v120, v122, v120, 1.0
	v_mul_f32_e32 v120, v122, v120
	v_mul_f32_e32 v120, 0xc0135761, v120
	v_exp_f32_e32 v120, v120
	v_mul_f32_e32 v118, v121, v118
	v_mul_f32_e32 v118, 0xc0135761, v118
	v_exp_f32_e32 v118, v118
	v_add_f32_e32 v120, 1.0, v120
	v_rcp_f32_e32 v120, v120
	s_cselect_b64 s[0:1], -1, 0
	v_add_f32_e32 v118, 1.0, v118
	v_rcp_f32_e32 v118, v118
	v_mul_f32_e32 v120, v122, v120
	v_mul_f32_e32 v122, 0x3d372713, v123
	v_fma_f32 v122, v123, v122, 1.0
	v_mul_f32_e32 v122, v123, v122
	v_mul_f32_e32 v122, 0xc0135761, v122
	v_exp_f32_e32 v122, v122
	v_mul_f32_e32 v118, v121, v118
	v_mul_f32_e32 v121, 0x3d372713, v142
	v_fma_f32 v121, v142, v121, 1.0
	v_add_f32_e32 v122, 1.0, v122
	v_rcp_f32_e32 v122, v122
	v_mul_f32_e32 v121, v142, v121
	v_mul_f32_e32 v121, 0xc0135761, v121
	v_exp_f32_e32 v121, v121
	v_mul_f32_e32 v122, v123, v122
	v_mul_f32_e32 v123, 0x3d372713, v143
	v_fma_f32 v123, v143, v123, 1.0
	v_mul_f32_e32 v123, v143, v123
	v_mul_f32_e32 v123, 0xc0135761, v123
	v_exp_f32_e32 v123, v123
	v_add_f32_e32 v121, 1.0, v121
	v_rcp_f32_e32 v121, v121
	s_cmp_lt_i32 s60, 8
	v_add_f32_e32 v123, 1.0, v123
	v_rcp_f32_e32 v123, v123
	v_lshl_add_u64 v[138:139], v[134:135], 0, v[138:139]
	v_cvt_pk_bf16_f32 v180, v124, v126
	v_cvt_pk_bf16_f32 v181, v128, v130
	v_cvt_pk_bf16_f32 v182, v125, v127
	v_cvt_pk_bf16_f32 v183, v129, v131
	v_mul_f32_e32 v121, v142, v121
	v_mul_f32_e32 v123, v143, v123
	global_store_dwordx4 v[138:139], v[180:183], off sc1
	s_nop 1
	v_cvt_pk_bf16_f32 v180, v116, v118
	v_cvt_pk_bf16_f32 v181, v120, v122
	v_cvt_pk_bf16_f32 v182, v117, v119
	v_cvt_pk_bf16_f32 v183, v121, v123
	global_store_dwordx4 v[138:139], v[180:183], off offset:256 sc1
	s_cbranch_scc1 .LBB0_624
; #define stats ((float*)(KWS(F) + WS_STATS))
;     __device__ __forceinline__ void operator()(const f32x4 (&acc)[2][2][4][2], const Unit& u, int wr, int wc, int fr, int fq) const {
;     ...
;                         s1 += ((v0[0] + v0[1]) + (v0[2] + v0[3])) + ((v1[0] + v1[1]) + (v1[2] + v1[3]));
;                         s2 += ((v0[0] * v0[0] + v0[1] * v0[1]) + (v0[2] * v0[2] + v0[3] * v0[3])) + ((v1[0] * v1[0] + v1[1] * v1[1]) + (v1[2] * v1[2] + v1[3] * v1[3]));
;     ...
;                 if (ACT == 1) { if (do_stats) {
;                     s1 = fq_sum(s1); s2 = fq_sum(s2);
;                     if (fq == 0) *(f32x2*)(stats + ((size_t)row * 32 + (u.pn - stats_pn0) * 4 + wc) * 2) = (f32x2){s1, s2}; } }
	v_mul_f32_e32 v133, v126, v126
	v_mul_f32_e32 v137, v130, v130
	v_fmac_f32_e32 v133, v124, v124
	v_fmac_f32_e32 v137, v128, v128
	v_add_f32_e32 v133, v133, v137
	v_mul_f32_e32 v137, v127, v127
	v_mul_f32_e32 v138, v131, v131
	v_fmac_f32_e32 v137, v125, v125
	v_fmac_f32_e32 v138, v129, v129
	v_add_f32_e32 v137, v137, v138
	v_add_f32_e32 v133, v133, v137
	v_mul_f32_e32 v137, v118, v118
	v_mul_f32_e32 v138, v122, v122
	v_fmac_f32_e32 v137, v116, v116
	v_fmac_f32_e32 v138, v120, v120
	v_add_f32_e32 v124, v124, v126
	v_add_f32_e32 v126, v128, v130
	v_add_f32_e32 v137, v137, v138
	v_mul_f32_e32 v138, v119, v119
	v_add_f32_e32 v124, v124, v126
	v_add_f32_e32 v125, v125, v127
	v_add_f32_e32 v126, v129, v131
	v_add_f32_e32 v116, v116, v118
	v_add_f32_e32 v118, v120, v122
	v_fmac_f32_e32 v138, v117, v117
	v_add_f32_e32 v125, v125, v126
	v_add_f32_e32 v116, v116, v118
	v_add_f32_e32 v117, v117, v119
	v_add_f32_e32 v118, v121, v123
	v_mul_f32_e32 v139, v123, v123
	v_add_f32_e32 v124, v124, v125
	v_add_f32_e32 v117, v117, v118
	v_fmac_f32_e32 v139, v121, v121
	v_add_f32_e32 v124, 0, v124
	v_add_f32_e32 v116, v116, v117
	v_add_f32_e32 v138, v138, v139
	v_add_f32_e32 v116, v116, v124
	v_add_f32_e32 v137, v137, v138
	v_mov_b32_e32 v117, v116
	v_add_f32_e32 v133, v133, v137
	s_nop 0
	v_permlane16_swap_b32_e32 v116, v117
	v_add_f32_e32 v116, v116, v117
	v_mov_b32_e32 v117, v133
	s_nop 1
	v_permlane16_swap_b32_e32 v133, v117
	v_add_f32_e32 v117, v133, v117
	v_mov_b32_e32 v118, v116
	v_mov_b32_e32 v119, v117
	s_nop 0
	v_permlane32_swap_b32_e32 v116, v118
	v_permlane32_swap_b32_e32 v117, v119
	s_and_saveexec_b64 s[4:5], s[38:39]
	s_cbranch_execz .LBB0_623
	s_lshl_b32 s20, s60, 2
	v_pk_add_f32 v[116:117], v[116:117], v[118:119]
	v_lshlrev_b64 v[118:119], 5, v[164:165]
	s_sub_i32 s48, s20, 32
	v_lshl_add_u64 v[118:119], v[118:119], 0, s[48:49]
	v_or_b32_e32 v118, s15, v118
	v_lshl_add_u64 v[118:119], v[118:119], 3, s[44:45]
	global_store_dwordx2 v[118:119], v[116:117], off

; __device__ __forceinline__ unsigned cvt_pk_bf16(float lo, float hi) { unsigned r; asm volatile("v_cvt_pk_bf16_f32 %0, %1, %2" : "=v"(r) : "v"(lo), "v"(hi)); return r; }
;     __device__ __forceinline__ void operator()(const f32x4 (&acc)[2][2][4][2], const Unit& u, int wr, int wc, int fr, int fq) const {
;     ...
;         for (int ai = 0; ai < 2; ++ai)
; #pragma unroll
;             for (int m = 0; m < 4; ++m) { const int row = row0 + ai * HALF + m * 16; bf16_t* rowp = base + (size_t)row * ldc + col0; float s1 = 0.f, s2 = 0.f;
;                 const float rs = rsv[ai][m];
; #pragma unroll
;                 for (int bj = 0; bj < 2; ++bj) { f32x4 v0 = acc[ai][bj][m][0] * rs, v1 = acc[ai][bj][m][1] * rs;
;                     if (ACT == 1) {
; #pragma unroll
;                         for (int e = 0; e < 4; ++e) { v0[e] = gelu_tanh(v0[e]); v1[e] = gelu_tanh(v1[e]); }
;                         s1 += ((v0[0] + v0[1]) + (v0[2] + v0[3])) + ((v1[0] + v1[1]) + (v1[2] + v1[3]));
;                         s2 += ((v0[0] * v0[0] + v0[1] * v0[1]) + (v0[2] * v0[2] + v0[3] * v0[3])) + ((v1[0] * v1[0] + v1[1] * v1[1]) + (v1[2] * v1[2] + v1[3] * v1[3]));
;                     }
;                     if (ACT == 2) {
; #pragma unroll
;                         for (int e = 0; e < 4; ++e) { const float a = __builtin_fmaxf(v0[e], 0.f), b = __builtin_fmaxf(v1[e], 0.f); v0[e] = a * a; v1[e] = b * b; }
;                     }
;                     u32x4 w; w.x = cvt_pk_bf16(v0[0], v0[1]); w.y = cvt_pk_bf16(v0[2], v0[3]); w.z = cvt_pk_bf16(v1[0], v1[1]); w.w = cvt_pk_bf16(v1[2], v1[3]);
;                     *(u32x4*)(rowp + bj * HALF) = w; }
.LBB0_624:
	v_pk_mul_f32 v[108:109], v[108:109], v[172:173] op_sel_hi:[1,0]
	v_pk_mul_f32 v[118:119], v[106:107], v[172:173] op_sel_hi:[1,0]
	v_pk_mul_f32 v[106:107], v[104:105], v[172:173] op_sel_hi:[1,0]
	v_mul_f32_e32 v104, 0x3d372713, v108
	v_fma_f32 v104, v108, v104, 1.0
	v_mul_f32_e32 v104, v108, v104
	v_mul_f32_e32 v104, 0xc0135761, v104
	v_exp_f32_e32 v104, v104
	v_pk_mul_f32 v[110:111], v[110:111], v[172:173] op_sel_hi:[1,0]
	v_mul_f32_e32 v105, 0x3d372713, v106
	v_fma_f32 v105, v106, v105, 1.0
	v_add_f32_e32 v104, 1.0, v104
	v_rcp_f32_e32 v104, v104
	v_mul_f32_e32 v105, v106, v105
	v_mul_f32_e32 v105, 0xc0135761, v105
	v_exp_f32_e32 v105, v105
	v_mul_f32_e32 v104, v108, v104
	v_mul_f32_e32 v108, 0x3d372713, v107
	v_fma_f32 v108, v107, v108, 1.0
	v_mul_f32_e32 v108, v107, v108
	v_mul_f32_e32 v108, 0xc0135761, v108
	v_exp_f32_e32 v108, v108
	v_add_f32_e32 v105, 1.0, v105
	v_rcp_f32_e32 v105, v105
	v_lshlrev_b64 v[116:117], 13, v[170:171]
	v_add_f32_e32 v108, 1.0, v108
	v_rcp_f32_e32 v108, v108
	v_mul_f32_e32 v105, v106, v105
	v_mul_f32_e32 v106, 0x3d372713, v109
	v_fma_f32 v106, v109, v106, 1.0
	v_mul_f32_e32 v107, v107, v108
	v_mul_f32_e32 v108, 0x3d372713, v110
	v_fma_f32 v108, v110, v108, 1.0
	v_mul_f32_e32 v108, v110, v108
	v_mul_f32_e32 v108, 0xc0135761, v108
	v_exp_f32_e32 v108, v108
	v_mul_f32_e32 v106, v109, v106
	v_mul_f32_e32 v106, 0xc0135761, v106
	v_exp_f32_e32 v106, v106
	v_add_f32_e32 v108, 1.0, v108
	v_rcp_f32_e32 v108, v108
	v_lshl_add_u64 v[116:117], v[134:135], 0, v[116:117]
	v_add_f32_e32 v106, 1.0, v106
	v_rcp_f32_e32 v106, v106
	v_mul_f32_e32 v108, v110, v108
	v_mul_f32_e32 v110, 0x3d372713, v111
	v_fma_f32 v110, v111, v110, 1.0
	v_mul_f32_e32 v110, v111, v110
	v_mul_f32_e32 v110, 0xc0135761, v110
	v_exp_f32_e32 v110, v110
	v_mul_f32_e32 v106, v109, v106
	v_mul_f32_e32 v109, 0x3d372713, v118
	v_fma_f32 v109, v118, v109, 1.0
	v_add_f32_e32 v110, 1.0, v110
	v_rcp_f32_e32 v110, v110
	v_mul_f32_e32 v109, v118, v109
	v_mul_f32_e32 v109, 0xc0135761, v109
	v_exp_f32_e32 v109, v109
	v_mul_f32_e32 v110, v111, v110
	v_mul_f32_e32 v111, 0x3d372713, v119
	v_fma_f32 v111, v119, v111, 1.0
	v_mul_f32_e32 v111, v119, v111
	v_mul_f32_e32 v111, 0xc0135761, v111
	v_exp_f32_e32 v111, v111
	v_add_f32_e32 v109, 1.0, v109
	v_rcp_f32_e32 v109, v109
	v_pk_mul_f32 v[100:101], v[100:101], v[172:173] op_sel_hi:[1,0]
	v_add_f32_e32 v111, 1.0, v111
	v_rcp_f32_e32 v111, v111
	v_mul_f32_e32 v109, v118, v109
	v_cvt_pk_bf16_f32 v118, v104, v106
	v_pk_mul_f32 v[102:103], v[102:103], v[172:173] op_sel_hi:[1,0]
	v_mul_f32_e32 v111, v119, v111
	v_cvt_pk_bf16_f32 v119, v108, v110
	v_cvt_pk_bf16_f32 v120, v105, v107
	v_cvt_pk_bf16_f32 v121, v109, v111
	global_store_dwordx4 v[116:117], v[118:121], off sc1
	s_andn2_b64 vcc, exec, s[0:1]
	s_nop 0
	v_pk_mul_f32 v[118:119], v[98:99], v[172:173] op_sel_hi:[1,0]
	v_pk_mul_f32 v[98:99], v[96:97], v[172:173] op_sel_hi:[1,0]
	v_mul_f32_e32 v96, 0x3d372713, v100
	v_fma_f32 v96, v100, v96, 1.0
	v_mul_f32_e32 v96, v100, v96
	v_mul_f32_e32 v96, 0xc0135761, v96
	v_exp_f32_e32 v96, v96
	v_mul_f32_e32 v97, 0x3d372713, v98
	v_fma_f32 v97, v98, v97, 1.0
	v_mul_f32_e32 v97, v98, v97
	v_add_f32_e32 v96, 1.0, v96
	v_rcp_f32_e32 v96, v96
	v_mul_f32_e32 v97, 0xc0135761, v97
	v_exp_f32_e32 v97, v97
	v_mul_f32_e32 v96, v100, v96
	v_mul_f32_e32 v100, 0x3d372713, v99
	v_fma_f32 v100, v99, v100, 1.0
	v_mul_f32_e32 v100, v99, v100
	v_mul_f32_e32 v100, 0xc0135761, v100
	v_exp_f32_e32 v100, v100
	v_add_f32_e32 v97, 1.0, v97
	v_rcp_f32_e32 v97, v97
	v_add_f32_e32 v100, 1.0, v100
	v_rcp_f32_e32 v100, v100
	v_mul_f32_e32 v97, v98, v97
	v_mul_f32_e32 v98, 0x3d372713, v101
	v_fma_f32 v98, v101, v98, 1.0
	v_mul_f32_e32 v99, v99, v100
	v_mul_f32_e32 v100, 0x3d372713, v102
	v_fma_f32 v100, v102, v100, 1.0
	v_mul_f32_e32 v100, v102, v100
	v_mul_f32_e32 v100, 0xc0135761, v100
	v_exp_f32_e32 v100, v100
	v_mul_f32_e32 v98, v101, v98
	v_mul_f32_e32 v98, 0xc0135761, v98
	v_exp_f32_e32 v98, v98
	v_add_f32_e32 v100, 1.0, v100
	v_rcp_f32_e32 v100, v100
	v_add_f32_e32 v98, 1.0, v98
	v_rcp_f32_e32 v98, v98
	v_mul_f32_e32 v100, v102, v100
	v_mul_f32_e32 v102, 0x3d372713, v103
	v_fma_f32 v102, v103, v102, 1.0
	v_mul_f32_e32 v102, v103, v102
	v_mul_f32_e32 v102, 0xc0135761, v102
	v_exp_f32_e32 v102, v102
	v_mul_f32_e32 v98, v101, v98
	v_mul_f32_e32 v101, 0x3d372713, v118
	v_fma_f32 v101, v118, v101, 1.0
	v_add_f32_e32 v102, 1.0, v102
	v_rcp_f32_e32 v102, v102
	v_mul_f32_e32 v101, v118, v101
	v_mul_f32_e32 v101, 0xc0135761, v101
	v_exp_f32_e32 v101, v101
	v_mul_f32_e32 v102, v103, v102
	v_mul_f32_e32 v103, 0x3d372713, v119
	v_fma_f32 v103, v119, v103, 1.0
	v_mul_f32_e32 v103, v119, v103
	v_mul_f32_e32 v103, 0xc0135761, v103
	v_exp_f32_e32 v103, v103
	v_add_f32_e32 v101, 1.0, v101
	v_rcp_f32_e32 v101, v101
	v_add_f32_e32 v103, 1.0, v103
	v_rcp_f32_e32 v103, v103
	v_mul_f32_e32 v101, v118, v101
	v_cvt_pk_bf16_f32 v118, v96, v98
	v_mul_f32_e32 v103, v119, v103
	v_cvt_pk_bf16_f32 v119, v100, v102
	v_cvt_pk_bf16_f32 v120, v97, v99
	v_cvt_pk_bf16_f32 v121, v101, v103
	global_store_dwordx4 v[116:117], v[118:121], off offset:256 sc1
	v_cndmask_b32_e64 v116, 0, 1, s[0:1]
	v_cmp_ne_u32_e64 s[4:5], 1, v116
	s_cbranch_vccnz .LBB0_628
; #define stats ((float*)(KWS(F) + WS_STATS))
;     __device__ __forceinline__ void operator()(const f32x4 (&acc)[2][2][4][2], const Unit& u, int wr, int wc, int fr, int fq) const {
;     ...
;                         s1 += ((v0[0] + v0[1]) + (v0[2] + v0[3])) + ((v1[0] + v1[1]) + (v1[2] + v1[3]));
;                         s2 += ((v0[0] * v0[0] + v0[1] * v0[1]) + (v0[2] * v0[2] + v0[3] * v0[3])) + ((v1[0] * v1[0] + v1[1] * v1[1]) + (v1[2] * v1[2] + v1[3] * v1[3]));
;     ...
;                 if (ACT == 1) { if (do_stats) {
;                     s1 = fq_sum(s1); s2 = fq_sum(s2);
;                     if (fq == 0) *(f32x2*)(stats + ((size_t)row * 32 + (u.pn - stats_pn0) * 4 + wc) * 2) = (f32x2){s1, s2}; } }
	v_mul_f32_e32 v116, v106, v106
	v_mul_f32_e32 v117, v110, v110
	v_fmac_f32_e32 v116, v104, v104
	v_fmac_f32_e32 v117, v108, v108
	v_add_f32_e32 v116, v116, v117
	v_mul_f32_e32 v117, v107, v107
	v_mul_f32_e32 v118, v111, v111
	v_fmac_f32_e32 v117, v105, v105
	v_fmac_f32_e32 v118, v109, v109
	v_add_f32_e32 v117, v117, v118
	v_add_f32_e32 v116, v116, v117
	v_mul_f32_e32 v117, v98, v98
	v_mul_f32_e32 v118, v102, v102
	v_fmac_f32_e32 v117, v96, v96
	v_fmac_f32_e32 v118, v100, v100
	v_add_f32_e32 v104, v104, v106
	v_add_f32_e32 v106, v108, v110
	v_add_f32_e32 v117, v117, v118
	v_mul_f32_e32 v118, v99, v99
	v_add_f32_e32 v104, v104, v106
	v_add_f32_e32 v105, v105, v107
	v_add_f32_e32 v106, v109, v111
	v_add_f32_e32 v96, v96, v98
	v_add_f32_e32 v98, v100, v102
	v_fmac_f32_e32 v118, v97, v97
	v_add_f32_e32 v105, v105, v106
	v_add_f32_e32 v96, v96, v98
	v_add_f32_e32 v97, v97, v99
	v_add_f32_e32 v98, v101, v103
	v_mul_f32_e32 v119, v103, v103
	v_add_f32_e32 v104, v104, v105
	v_add_f32_e32 v97, v97, v98
	v_fmac_f32_e32 v119, v101, v101
	v_add_f32_e32 v104, 0, v104
	v_add_f32_e32 v96, v96, v97
	v_add_f32_e32 v118, v118, v119
	v_add_f32_e32 v96, v96, v104
	v_add_f32_e32 v117, v117, v118
	v_mov_b32_e32 v97, v96
	v_add_f32_e32 v116, v116, v117
	s_nop 0
	v_permlane16_swap_b32_e32 v96, v97
	v_add_f32_e32 v96, v96, v97
	v_mov_b32_e32 v97, v116
	s_nop 1
	v_permlane16_swap_b32_e32 v116, v97
	v_add_f32_e32 v97, v116, v97
	v_mov_b32_e32 v98, v96
	v_mov_b32_e32 v99, v97
	s_nop 0
	v_permlane32_swap_b32_e32 v96, v98
	v_permlane32_swap_b32_e32 v97, v99
	s_and_saveexec_b64 s[0:1], s[38:39]
	s_cbranch_execz .LBB0_627
	s_lshl_b32 s20, s60, 2
	v_pk_add_f32 v[96:97], v[96:97], v[98:99]
	v_lshlrev_b64 v[98:99], 5, v[170:171]
	s_sub_i32 s48, s20, 32
	v_lshl_add_u64 v[98:99], v[98:99], 0, s[48:49]
	v_or_b32_e32 v98, s15, v98
	v_lshl_add_u64 v[98:99], v[98:99], 3, s[44:45]
	global_store_dwordx2 v[98:99], v[96:97], off

; __device__ __forceinline__ unsigned cvt_pk_bf16(float lo, float hi) { unsigned r; asm volatile("v_cvt_pk_bf16_f32 %0, %1, %2" : "=v"(r) : "v"(lo), "v"(hi)); return r; }
; #define stats ((float*)(KWS(F) + WS_STATS))
;     __device__ __forceinline__ void operator()(const f32x4 (&acc)[2][2][4][2], const Unit& u, int wr, int wc, int fr, int fq) const {
;     ...
;         for (int ai = 0; ai < 2; ++ai)
; #pragma unroll
;             for (int m = 0; m < 4; ++m) { const int row = row0 + ai * HALF + m * 16; bf16_t* rowp = base + (size_t)row * ldc + col0; float s1 = 0.f, s2 = 0.f;
;                 const float rs = rsv[ai][m];
; #pragma unroll
;                 for (int bj = 0; bj < 2; ++bj) { f32x4 v0 = acc[ai][bj][m][0] * rs, v1 = acc[ai][bj][m][1] * rs;
;                     if (ACT == 1) {
; #pragma unroll
;                         for (int e = 0; e < 4; ++e) { v0[e] = gelu_tanh(v0[e]); v1[e] = gelu_tanh(v1[e]); }
;                         s1 += ((v0[0] + v0[1]) + (v0[2] + v0[3])) + ((v1[0] + v1[1]) + (v1[2] + v1[3]));
;                         s2 += ((v0[0] * v0[0] + v0[1] * v0[1]) + (v0[2] * v0[2] + v0[3] * v0[3])) + ((v1[0] * v1[0] + v1[1] * v1[1]) + (v1[2] * v1[2] + v1[3] * v1[3]));
;                     }
;                     if (ACT == 2) {
; #pragma unroll
;                         for (int e = 0; e < 4; ++e) { const float a = __builtin_fmaxf(v0[e], 0.f), b = __builtin_fmaxf(v1[e], 0.f); v0[e] = a * a; v1[e] = b * b; }
;                     }
;                     u32x4 w; w.x = cvt_pk_bf16(v0[0], v0[1]); w.y = cvt_pk_bf16(v0[2], v0[3]); w.z = cvt_pk_bf16(v1[0], v1[1]); w.w = cvt_pk_bf16(v1[2], v1[3]);
;                     *(u32x4*)(rowp + bj * HALF) = w; }
;                 if (ACT == 1) { if (do_stats) {
;                     s1 = fq_sum(s1); s2 = fq_sum(s2);
;                     if (fq == 0) *(f32x2*)(stats + ((size_t)row * 32 + (u.pn - stats_pn0) * 4 + wc) * 2) = (f32x2){s1, s2}; } }
.LBB0_628:
	v_pk_mul_f32 v[92:93], v[92:93], v[152:153] op_sel_hi:[1,0]
	v_pk_mul_f32 v[98:99], v[90:91], v[152:153] op_sel_hi:[1,0]
	v_pk_mul_f32 v[90:91], v[88:89], v[152:153] op_sel_hi:[1,0]
	v_mul_f32_e32 v88, 0x3d372713, v92
	v_fma_f32 v88, v92, v88, 1.0
	v_mul_f32_e32 v88, v92, v88
	v_mul_f32_e32 v88, 0xc0135761, v88
	v_exp_f32_e32 v88, v88
	v_pk_mul_f32 v[94:95], v[94:95], v[152:153] op_sel_hi:[1,0]
	v_mul_f32_e32 v89, 0x3d372713, v90
	v_fma_f32 v89, v90, v89, 1.0
	v_add_f32_e32 v88, 1.0, v88
	v_rcp_f32_e32 v88, v88
	v_mul_f32_e32 v89, v90, v89
	v_mul_f32_e32 v89, 0xc0135761, v89
	v_exp_f32_e32 v89, v89
	v_mul_f32_e32 v88, v92, v88
	v_mul_f32_e32 v92, 0x3d372713, v91
	v_fma_f32 v92, v91, v92, 1.0
	v_mul_f32_e32 v92, v91, v92
	v_mul_f32_e32 v92, 0xc0135761, v92
	v_exp_f32_e32 v92, v92
	v_add_f32_e32 v89, 1.0, v89
	v_rcp_f32_e32 v89, v89
	v_lshlrev_b64 v[96:97], 13, v[168:169]
	v_add_f32_e32 v92, 1.0, v92
	v_rcp_f32_e32 v92, v92
	v_mul_f32_e32 v89, v90, v89
	v_mul_f32_e32 v90, 0x3d372713, v93
	v_fma_f32 v90, v93, v90, 1.0
	v_mul_f32_e32 v91, v91, v92
	v_mul_f32_e32 v92, 0x3d372713, v94
	v_fma_f32 v92, v94, v92, 1.0
	v_mul_f32_e32 v92, v94, v92
	v_mul_f32_e32 v92, 0xc0135761, v92
	v_exp_f32_e32 v92, v92
	v_mul_f32_e32 v90, v93, v90
	v_mul_f32_e32 v90, 0xc0135761, v90
	v_exp_f32_e32 v90, v90
	v_add_f32_e32 v92, 1.0, v92
	v_rcp_f32_e32 v92, v92
	v_lshl_add_u64 v[96:97], v[134:135], 0, v[96:97]
	v_add_f32_e32 v90, 1.0, v90
	v_rcp_f32_e32 v90, v90
	v_mul_f32_e32 v92, v94, v92
	v_mul_f32_e32 v94, 0x3d372713, v95
	v_fma_f32 v94, v95, v94, 1.0
	v_mul_f32_e32 v94, v95, v94
	v_mul_f32_e32 v94, 0xc0135761, v94
	v_exp_f32_e32 v94, v94
	v_mul_f32_e32 v90, v93, v90
	v_mul_f32_e32 v93, 0x3d372713, v98
	v_fma_f32 v93, v98, v93, 1.0
	v_add_f32_e32 v94, 1.0, v94
	v_rcp_f32_e32 v94, v94
	v_mul_f32_e32 v93, v98, v93
	v_mul_f32_e32 v93, 0xc0135761, v93
	v_exp_f32_e32 v93, v93
	v_mul_f32_e32 v94, v95, v94
	v_mul_f32_e32 v95, 0x3d372713, v99
	v_fma_f32 v95, v99, v95, 1.0
	v_mul_f32_e32 v95, v99, v95
	v_mul_f32_e32 v95, 0xc0135761, v95
	v_exp_f32_e32 v95, v95
	v_add_f32_e32 v93, 1.0, v93
	v_rcp_f32_e32 v93, v93
	v_pk_mul_f32 v[84:85], v[84:85], v[152:153] op_sel_hi:[1,0]
	v_add_f32_e32 v95, 1.0, v95
	v_rcp_f32_e32 v95, v95
	v_mul_f32_e32 v93, v98, v93
	v_cvt_pk_bf16_f32 v98, v88, v90
	v_pk_mul_f32 v[86:87], v[86:87], v[152:153] op_sel_hi:[1,0]
	v_mul_f32_e32 v95, v99, v95
	v_cvt_pk_bf16_f32 v99, v92, v94
	v_cvt_pk_bf16_f32 v100, v89, v91
	v_cvt_pk_bf16_f32 v101, v93, v95
	global_store_dwordx4 v[96:97], v[98:101], off sc1
	s_and_b64 vcc, exec, s[4:5]
	s_nop 0
	v_pk_mul_f32 v[98:99], v[82:83], v[152:153] op_sel_hi:[1,0]
	v_pk_mul_f32 v[82:83], v[80:81], v[152:153] op_sel_hi:[1,0]
	v_mul_f32_e32 v80, 0x3d372713, v84
	v_fma_f32 v80, v84, v80, 1.0
	v_mul_f32_e32 v80, v84, v80
	v_mul_f32_e32 v80, 0xc0135761, v80
	v_exp_f32_e32 v80, v80
	v_mul_f32_e32 v81, 0x3d372713, v82
	v_fma_f32 v81, v82, v81, 1.0
	v_mul_f32_e32 v81, v82, v81
	v_add_f32_e32 v80, 1.0, v80
	v_rcp_f32_e32 v80, v80
	v_mul_f32_e32 v81, 0xc0135761, v81
	v_exp_f32_e32 v81, v81
	v_mul_f32_e32 v80, v84, v80
	v_mul_f32_e32 v84, 0x3d372713, v83
	v_fma_f32 v84, v83, v84, 1.0
	v_mul_f32_e32 v84, v83, v84
	v_mul_f32_e32 v84, 0xc0135761, v84
	v_exp_f32_e32 v84, v84
	v_add_f32_e32 v81, 1.0, v81
	v_rcp_f32_e32 v81, v81
	v_add_f32_e32 v84, 1.0, v84
	v_rcp_f32_e32 v84, v84
	v_mul_f32_e32 v81, v82, v81
	v_mul_f32_e32 v82, 0x3d372713, v85
	v_fma_f32 v82, v85, v82, 1.0
	v_mul_f32_e32 v83, v83, v84
	v_mul_f32_e32 v84, 0x3d372713, v86
	v_fma_f32 v84, v86, v84, 1.0
	v_mul_f32_e32 v84, v86, v84
	v_mul_f32_e32 v84, 0xc0135761, v84
	v_exp_f32_e32 v84, v84
	v_mul_f32_e32 v82, v85, v82
	v_mul_f32_e32 v82, 0xc0135761, v82
	v_exp_f32_e32 v82, v82
	v_add_f32_e32 v84, 1.0, v84
	v_rcp_f32_e32 v84, v84
	v_add_f32_e32 v82, 1.0, v82
	v_rcp_f32_e32 v82, v82
	v_mul_f32_e32 v84, v86, v84
	v_mul_f32_e32 v86, 0x3d372713, v87
	v_fma_f32 v86, v87, v86, 1.0
	v_mul_f32_e32 v86, v87, v86
	v_mul_f32_e32 v86, 0xc0135761, v86
	v_exp_f32_e32 v86, v86
	v_mul_f32_e32 v82, v85, v82
	v_mul_f32_e32 v85, 0x3d372713, v98
	v_fma_f32 v85, v98, v85, 1.0
	v_add_f32_e32 v86, 1.0, v86
	v_rcp_f32_e32 v86, v86
	v_mul_f32_e32 v85, v98, v85
	v_mul_f32_e32 v85, 0xc0135761, v85
	v_exp_f32_e32 v85, v85
	v_mul_f32_e32 v86, v87, v86
	v_mul_f32_e32 v87, 0x3d372713, v99
	v_fma_f32 v87, v99, v87, 1.0
	v_mul_f32_e32 v87, v99, v87
	v_mul_f32_e32 v87, 0xc0135761, v87
	v_exp_f32_e32 v87, v87
	v_add_f32_e32 v85, 1.0, v85
	v_rcp_f32_e32 v85, v85
	v_add_f32_e32 v87, 1.0, v87
	v_rcp_f32_e32 v87, v87
	v_mul_f32_e32 v85, v98, v85
	v_cvt_pk_bf16_f32 v98, v80, v82
	v_mul_f32_e32 v87, v99, v87
	v_cvt_pk_bf16_f32 v99, v84, v86
	v_cvt_pk_bf16_f32 v100, v81, v83
	v_cvt_pk_bf16_f32 v101, v85, v87
	global_store_dwordx4 v[96:97], v[98:101], off offset:256 sc1
	s_cbranch_vccnz .LBB0_632
	v_mul_f32_e32 v96, v90, v90
	v_mul_f32_e32 v97, v94, v94
	v_fmac_f32_e32 v96, v88, v88
	v_fmac_f32_e32 v97, v92, v92
	v_add_f32_e32 v96, v96, v97
	v_mul_f32_e32 v97, v91, v91
	v_mul_f32_e32 v98, v95, v95
	v_fmac_f32_e32 v97, v89, v89
	v_fmac_f32_e32 v98, v93, v93
	v_add_f32_e32 v97, v97, v98
	v_add_f32_e32 v96, v96, v97
	v_mul_f32_e32 v97, v82, v82
	v_mul_f32_e32 v98, v86, v86
	v_fmac_f32_e32 v97, v80, v80
	v_fmac_f32_e32 v98, v84, v84
	v_add_f32_e32 v88, v88, v90
	v_add_f32_e32 v90, v92, v94
	v_add_f32_e32 v97, v97, v98
	v_mul_f32_e32 v98, v83, v83
	v_add_f32_e32 v88, v88, v90
	v_add_f32_e32 v89, v89, v91
	v_add_f32_e32 v90, v93, v95
	v_add_f32_e32 v80, v80, v82
	v_add_f32_e32 v82, v84, v86
	v_fmac_f32_e32 v98, v81, v81
	v_add_f32_e32 v89, v89, v90
	v_add_f32_e32 v80, v80, v82
	v_add_f32_e32 v81, v81, v83
	v_add_f32_e32 v82, v85, v87
	v_mul_f32_e32 v99, v87, v87
	v_add_f32_e32 v88, v88, v89
	v_add_f32_e32 v81, v81, v82
	v_fmac_f32_e32 v99, v85, v85
	v_add_f32_e32 v88, 0, v88
	v_add_f32_e32 v80, v80, v81
	v_add_f32_e32 v98, v98, v99
	v_add_f32_e32 v80, v80, v88
	v_add_f32_e32 v97, v97, v98
	v_mov_b32_e32 v81, v80
	v_add_f32_e32 v96, v96, v97
	s_nop 0
	v_permlane16_swap_b32_e32 v80, v81
	v_add_f32_e32 v80, v80, v81
	v_mov_b32_e32 v81, v96
	s_nop 1
	v_permlane16_swap_b32_e32 v96, v81
	v_add_f32_e32 v81, v96, v81
	v_mov_b32_e32 v82, v80
	v_mov_b32_e32 v83, v81
	s_nop 0
	v_permlane32_swap_b32_e32 v80, v82
	v_permlane32_swap_b32_e32 v81, v83
	s_and_saveexec_b64 s[0:1], s[38:39]
	s_cbranch_execz .LBB0_631
	s_lshl_b32 s20, s60, 2
	v_pk_add_f32 v[80:81], v[80:81], v[82:83]
	v_lshlrev_b64 v[82:83], 5, v[168:169]
	s_sub_i32 s48, s20, 32
	v_lshl_add_u64 v[82:83], v[82:83], 0, s[48:49]
	v_or_b32_e32 v82, s15, v82
	v_lshl_add_u64 v[82:83], v[82:83], 3, s[44:45]
	global_store_dwordx2 v[82:83], v[80:81], off

; __device__ __forceinline__ unsigned cvt_pk_bf16(float lo, float hi) { unsigned r; asm volatile("v_cvt_pk_bf16_f32 %0, %1, %2" : "=v"(r) : "v"(lo), "v"(hi)); return r; }
; #define stats ((float*)(KWS(F) + WS_STATS))
;     __device__ __forceinline__ void operator()(const f32x4 (&acc)[2][2][4][2], const Unit& u, int wr, int wc, int fr, int fq) const {
;     ...
;         for (int ai = 0; ai < 2; ++ai)
; #pragma unroll
;             for (int m = 0; m < 4; ++m) { const int row = row0 + ai * HALF + m * 16; bf16_t* rowp = base + (size_t)row * ldc + col0; float s1 = 0.f, s2 = 0.f;
;                 const float rs = rsv[ai][m];
; #pragma unroll
;                 for (int bj = 0; bj < 2; ++bj) { f32x4 v0 = acc[ai][bj][m][0] * rs, v1 = acc[ai][bj][m][1] * rs;
;                     if (ACT == 1) {
; #pragma unroll
;                         for (int e = 0; e < 4; ++e) { v0[e] = gelu_tanh(v0[e]); v1[e] = gelu_tanh(v1[e]); }
;                         s1 += ((v0[0] + v0[1]) + (v0[2] + v0[3])) + ((v1[0] + v1[1]) + (v1[2] + v1[3]));
;                         s2 += ((v0[0] * v0[0] + v0[1] * v0[1]) + (v0[2] * v0[2] + v0[3] * v0[3])) + ((v1[0] * v1[0] + v1[1] * v1[1]) + (v1[2] * v1[2] + v1[3] * v1[3]));
;                     }
;                     if (ACT == 2) {
; #pragma unroll
;                         for (int e = 0; e < 4; ++e) { const float a = __builtin_fmaxf(v0[e], 0.f), b = __builtin_fmaxf(v1[e], 0.f); v0[e] = a * a; v1[e] = b * b; }
;                     }
;                     u32x4 w; w.x = cvt_pk_bf16(v0[0], v0[1]); w.y = cvt_pk_bf16(v0[2], v0[3]); w.z = cvt_pk_bf16(v1[0], v1[1]); w.w = cvt_pk_bf16(v1[2], v1[3]);
;                     *(u32x4*)(rowp + bj * HALF) = w; }
;                 if (ACT == 1) { if (do_stats) {
;                     s1 = fq_sum(s1); s2 = fq_sum(s2);
;                     if (fq == 0) *(f32x2*)(stats + ((size_t)row * 32 + (u.pn - stats_pn0) * 4 + wc) * 2) = (f32x2){s1, s2}; } }
.LBB0_632:
	v_pk_mul_f32 v[76:77], v[76:77], v[148:149] op_sel_hi:[1,0]
	v_pk_mul_f32 v[82:83], v[74:75], v[148:149] op_sel_hi:[1,0]
	v_pk_mul_f32 v[74:75], v[72:73], v[148:149] op_sel_hi:[1,0]
	v_mul_f32_e32 v72, 0x3d372713, v76
	v_fma_f32 v72, v76, v72, 1.0
	v_mul_f32_e32 v72, v76, v72
	v_mul_f32_e32 v72, 0xc0135761, v72
	v_exp_f32_e32 v72, v72
	v_pk_mul_f32 v[78:79], v[78:79], v[148:149] op_sel_hi:[1,0]
	v_mul_f32_e32 v73, 0x3d372713, v74
	v_fma_f32 v73, v74, v73, 1.0
	v_add_f32_e32 v72, 1.0, v72
	v_rcp_f32_e32 v72, v72
	v_mul_f32_e32 v73, v74, v73
	v_mul_f32_e32 v73, 0xc0135761, v73
	v_exp_f32_e32 v73, v73
	v_mul_f32_e32 v72, v76, v72
	v_mul_f32_e32 v76, 0x3d372713, v75
	v_fma_f32 v76, v75, v76, 1.0
	v_mul_f32_e32 v76, v75, v76
	v_mul_f32_e32 v76, 0xc0135761, v76
	v_exp_f32_e32 v76, v76
	v_add_f32_e32 v73, 1.0, v73
	v_rcp_f32_e32 v73, v73
	v_lshlrev_b64 v[80:81], 13, v[166:167]
	v_add_f32_e32 v76, 1.0, v76
	v_rcp_f32_e32 v76, v76
	v_mul_f32_e32 v73, v74, v73
	v_mul_f32_e32 v74, 0x3d372713, v77
	v_fma_f32 v74, v77, v74, 1.0
	v_mul_f32_e32 v75, v75, v76
	v_mul_f32_e32 v76, 0x3d372713, v78
	v_fma_f32 v76, v78, v76, 1.0
	v_mul_f32_e32 v76, v78, v76
	v_mul_f32_e32 v76, 0xc0135761, v76
	v_exp_f32_e32 v76, v76
	v_mul_f32_e32 v74, v77, v74
	v_mul_f32_e32 v74, 0xc0135761, v74
	v_exp_f32_e32 v74, v74
	v_add_f32_e32 v76, 1.0, v76
	v_rcp_f32_e32 v76, v76
	v_lshl_add_u64 v[80:81], v[134:135], 0, v[80:81]
	v_add_f32_e32 v74, 1.0, v74
	v_rcp_f32_e32 v74, v74
	v_mul_f32_e32 v76, v78, v76
	v_mul_f32_e32 v78, 0x3d372713, v79
	v_fma_f32 v78, v79, v78, 1.0
	v_mul_f32_e32 v78, v79, v78
	v_mul_f32_e32 v78, 0xc0135761, v78
	v_exp_f32_e32 v78, v78
	v_mul_f32_e32 v74, v77, v74
	v_mul_f32_e32 v77, 0x3d372713, v82
	v_fma_f32 v77, v82, v77, 1.0
	v_add_f32_e32 v78, 1.0, v78
	v_rcp_f32_e32 v78, v78
	v_mul_f32_e32 v77, v82, v77
	v_mul_f32_e32 v77, 0xc0135761, v77
	v_exp_f32_e32 v77, v77
	v_mul_f32_e32 v78, v79, v78
	v_mul_f32_e32 v79, 0x3d372713, v83
	v_fma_f32 v79, v83, v79, 1.0
	v_mul_f32_e32 v79, v83, v79
	v_mul_f32_e32 v79, 0xc0135761, v79
	v_exp_f32_e32 v79, v79
	v_add_f32_e32 v77, 1.0, v77
	v_rcp_f32_e32 v77, v77
	v_pk_mul_f32 v[68:69], v[68:69], v[148:149] op_sel_hi:[1,0]
	v_add_f32_e32 v79, 1.0, v79
	v_rcp_f32_e32 v79, v79
	v_mul_f32_e32 v77, v82, v77
	v_cvt_pk_bf16_f32 v82, v72, v74
	v_pk_mul_f32 v[70:71], v[70:71], v[148:149] op_sel_hi:[1,0]
	v_mul_f32_e32 v79, v83, v79
	v_cvt_pk_bf16_f32 v83, v76, v78
	v_cvt_pk_bf16_f32 v84, v73, v75
	v_cvt_pk_bf16_f32 v85, v77, v79
	global_store_dwordx4 v[80:81], v[82:85], off sc1
	s_and_b64 vcc, exec, s[4:5]
	s_nop 0
	v_pk_mul_f32 v[82:83], v[66:67], v[148:149] op_sel_hi:[1,0]
	v_pk_mul_f32 v[66:67], v[64:65], v[148:149] op_sel_hi:[1,0]
	v_mul_f32_e32 v64, 0x3d372713, v68
	v_fma_f32 v64, v68, v64, 1.0
	v_mul_f32_e32 v64, v68, v64
	v_mul_f32_e32 v64, 0xc0135761, v64
	v_exp_f32_e32 v64, v64
	v_mul_f32_e32 v65, 0x3d372713, v66
	v_fma_f32 v65, v66, v65, 1.0
	v_mul_f32_e32 v65, v66, v65
	v_add_f32_e32 v64, 1.0, v64
	v_rcp_f32_e32 v64, v64
	v_mul_f32_e32 v65, 0xc0135761, v65
	v_exp_f32_e32 v65, v65
	v_mul_f32_e32 v64, v68, v64
	v_mul_f32_e32 v68, 0x3d372713, v67
	v_fma_f32 v68, v67, v68, 1.0
	v_mul_f32_e32 v68, v67, v68
	v_mul_f32_e32 v68, 0xc0135761, v68
	v_exp_f32_e32 v68, v68
	v_add_f32_e32 v65, 1.0, v65
	v_rcp_f32_e32 v65, v65
	v_add_f32_e32 v68, 1.0, v68
	v_rcp_f32_e32 v68, v68
	v_mul_f32_e32 v65, v66, v65
	v_mul_f32_e32 v66, 0x3d372713, v69
	v_fma_f32 v66, v69, v66, 1.0
	v_mul_f32_e32 v67, v67, v68
	v_mul_f32_e32 v68, 0x3d372713, v70
	v_fma_f32 v68, v70, v68, 1.0
	v_mul_f32_e32 v68, v70, v68
	v_mul_f32_e32 v68, 0xc0135761, v68
	v_exp_f32_e32 v68, v68
	v_mul_f32_e32 v66, v69, v66
	v_mul_f32_e32 v66, 0xc0135761, v66
	v_exp_f32_e32 v66, v66
	v_add_f32_e32 v68, 1.0, v68
	v_rcp_f32_e32 v68, v68
	v_add_f32_e32 v66, 1.0, v66
	v_rcp_f32_e32 v66, v66
	v_mul_f32_e32 v68, v70, v68
	v_mul_f32_e32 v70, 0x3d372713, v71
	v_fma_f32 v70, v71, v70, 1.0
	v_mul_f32_e32 v70, v71, v70
	v_mul_f32_e32 v70, 0xc0135761, v70
	v_exp_f32_e32 v70, v70
	v_mul_f32_e32 v66, v69, v66
	v_mul_f32_e32 v69, 0x3d372713, v82
	v_fma_f32 v69, v82, v69, 1.0
	v_add_f32_e32 v70, 1.0, v70
	v_rcp_f32_e32 v70, v70
	v_mul_f32_e32 v69, v82, v69
	v_mul_f32_e32 v69, 0xc0135761, v69
	v_exp_f32_e32 v69, v69
	v_mul_f32_e32 v70, v71, v70
	v_mul_f32_e32 v71, 0x3d372713, v83
	v_fma_f32 v71, v83, v71, 1.0
	v_mul_f32_e32 v71, v83, v71
	v_mul_f32_e32 v71, 0xc0135761, v71
	v_exp_f32_e32 v71, v71
	v_add_f32_e32 v69, 1.0, v69
	v_rcp_f32_e32 v69, v69
	v_add_f32_e32 v71, 1.0, v71
	v_rcp_f32_e32 v71, v71
	v_mul_f32_e32 v69, v82, v69
	v_cvt_pk_bf16_f32 v82, v64, v66
	v_mul_f32_e32 v71, v83, v71
	v_cvt_pk_bf16_f32 v83, v68, v70
	v_cvt_pk_bf16_f32 v84, v65, v67
	v_cvt_pk_bf16_f32 v85, v69, v71
	global_store_dwordx4 v[80:81], v[82:85], off offset:256 sc1
	s_cbranch_vccnz .LBB0_636
	v_mul_f32_e32 v80, v74, v74
	v_mul_f32_e32 v81, v78, v78
	v_fmac_f32_e32 v80, v72, v72
	v_fmac_f32_e32 v81, v76, v76
	v_add_f32_e32 v80, v80, v81
	v_mul_f32_e32 v81, v75, v75
	v_mul_f32_e32 v82, v79, v79
	v_fmac_f32_e32 v81, v73, v73
	v_fmac_f32_e32 v82, v77, v77
	v_add_f32_e32 v81, v81, v82
	v_add_f32_e32 v80, v80, v81
	v_mul_f32_e32 v81, v66, v66
	v_mul_f32_e32 v82, v70, v70
	v_fmac_f32_e32 v81, v64, v64
	v_fmac_f32_e32 v82, v68, v68
	v_add_f32_e32 v72, v72, v74
	v_add_f32_e32 v74, v76, v78
	v_add_f32_e32 v81, v81, v82
	v_mul_f32_e32 v82, v67, v67
	v_add_f32_e32 v72, v72, v74
	v_add_f32_e32 v73, v73, v75
	v_add_f32_e32 v74, v77, v79
	v_add_f32_e32 v64, v64, v66
	v_add_f32_e32 v66, v68, v70
	v_fmac_f32_e32 v82, v65, v65
	v_add_f32_e32 v73, v73, v74
	v_add_f32_e32 v64, v64, v66
	v_add_f32_e32 v65, v65, v67
	v_add_f32_e32 v66, v69, v71
	v_mul_f32_e32 v83, v71, v71
	v_add_f32_e32 v72, v72, v73
	v_add_f32_e32 v65, v65, v66
	v_fmac_f32_e32 v83, v69, v69
	v_add_f32_e32 v72, 0, v72
	v_add_f32_e32 v64, v64, v65
	v_add_f32_e32 v82, v82, v83
	v_add_f32_e32 v64, v64, v72
	v_add_f32_e32 v81, v81, v82
	v_mov_b32_e32 v65, v64
	v_add_f32_e32 v80, v80, v81
	s_nop 0
	v_permlane16_swap_b32_e32 v64, v65
	v_add_f32_e32 v64, v64, v65
	v_mov_b32_e32 v65, v80
	s_nop 1
	v_permlane16_swap_b32_e32 v80, v65
	v_add_f32_e32 v65, v80, v65
	v_mov_b32_e32 v66, v64
	v_mov_b32_e32 v67, v65
	s_nop 0
	v_permlane32_swap_b32_e32 v64, v66
	v_permlane32_swap_b32_e32 v65, v67
	s_and_saveexec_b64 s[0:1], s[38:39]
	s_cbranch_execz .LBB0_635
	s_lshl_b32 s20, s60, 2
	v_pk_add_f32 v[64:65], v[64:65], v[66:67]
	v_lshlrev_b64 v[66:67], 5, v[166:167]
	s_sub_i32 s48, s20, 32
	v_lshl_add_u64 v[66:67], v[66:67], 0, s[48:49]
	v_or_b32_e32 v66, s15, v66
	v_lshl_add_u64 v[66:67], v[66:67], 3, s[44:45]
	global_store_dwordx2 v[66:67], v[64:65], off

; __device__ __forceinline__ unsigned cvt_pk_bf16(float lo, float hi) { unsigned r; asm volatile("v_cvt_pk_bf16_f32 %0, %1, %2" : "=v"(r) : "v"(lo), "v"(hi)); return r; }
; #define stats ((float*)(KWS(F) + WS_STATS))
;     __device__ __forceinline__ void operator()(const f32x4 (&acc)[2][2][4][2], const Unit& u, int wr, int wc, int fr, int fq) const {
;     ...
;         for (int ai = 0; ai < 2; ++ai)
; #pragma unroll
;             for (int m = 0; m < 4; ++m) { const int row = row0 + ai * HALF + m * 16; bf16_t* rowp = base + (size_t)row * ldc + col0; float s1 = 0.f, s2 = 0.f;
;                 const float rs = rsv[ai][m];
; #pragma unroll
;                 for (int bj = 0; bj < 2; ++bj) { f32x4 v0 = acc[ai][bj][m][0] * rs, v1 = acc[ai][bj][m][1] * rs;
;                     if (ACT == 1) {
; #pragma unroll
;                         for (int e = 0; e < 4; ++e) { v0[e] = gelu_tanh(v0[e]); v1[e] = gelu_tanh(v1[e]); }
;                         s1 += ((v0[0] + v0[1]) + (v0[2] + v0[3])) + ((v1[0] + v1[1]) + (v1[2] + v1[3]));
;                         s2 += ((v0[0] * v0[0] + v0[1] * v0[1]) + (v0[2] * v0[2] + v0[3] * v0[3])) + ((v1[0] * v1[0] + v1[1] * v1[1]) + (v1[2] * v1[2] + v1[3] * v1[3]));
;                     }
;                     if (ACT == 2) {
; #pragma unroll
;                         for (int e = 0; e < 4; ++e) { const float a = __builtin_fmaxf(v0[e], 0.f), b = __builtin_fmaxf(v1[e], 0.f); v0[e] = a * a; v1[e] = b * b; }
;                     }
;                     u32x4 w; w.x = cvt_pk_bf16(v0[0], v0[1]); w.y = cvt_pk_bf16(v0[2], v0[3]); w.z = cvt_pk_bf16(v1[0], v1[1]); w.w = cvt_pk_bf16(v1[2], v1[3]);
;                     *(u32x4*)(rowp + bj * HALF) = w; }
;                 if (ACT == 1) { if (do_stats) {
;                     s1 = fq_sum(s1); s2 = fq_sum(s2);
;                     if (fq == 0) *(f32x2*)(stats + ((size_t)row * 32 + (u.pn - stats_pn0) * 4 + wc) * 2) = (f32x2){s1, s2}; } }
.LBB0_636:
	v_pk_mul_f32 v[60:61], v[60:61], v[144:145] op_sel_hi:[1,0]
	v_pk_mul_f32 v[68:69], v[58:59], v[144:145] op_sel_hi:[1,0]
	v_pk_mul_f32 v[58:59], v[56:57], v[144:145] op_sel_hi:[1,0]
	v_mul_f32_e32 v56, 0x3d372713, v60
	v_fma_f32 v56, v60, v56, 1.0
	v_mul_f32_e32 v56, v60, v56
	v_mul_f32_e32 v56, 0xc0135761, v56
	v_exp_f32_e32 v56, v56
	v_pk_mul_f32 v[62:63], v[62:63], v[144:145] op_sel_hi:[1,0]
	v_mul_f32_e32 v57, 0x3d372713, v58
	v_fma_f32 v57, v58, v57, 1.0
	v_add_f32_e32 v56, 1.0, v56
	v_rcp_f32_e32 v56, v56
	v_mul_f32_e32 v57, v58, v57
	v_mul_f32_e32 v57, 0xc0135761, v57
	v_exp_f32_e32 v57, v57
	v_mul_f32_e32 v56, v60, v56
	v_mul_f32_e32 v60, 0x3d372713, v59
	v_fma_f32 v60, v59, v60, 1.0
	v_mul_f32_e32 v60, v59, v60
	v_mul_f32_e32 v60, 0xc0135761, v60
	v_exp_f32_e32 v60, v60
	v_add_f32_e32 v57, 1.0, v57
	v_rcp_f32_e32 v57, v57
	v_add_u32_e32 v64, 0x80, v164
	v_add_f32_e32 v60, 1.0, v60
	v_rcp_f32_e32 v60, v60
	v_mul_f32_e32 v57, v58, v57
	v_mul_f32_e32 v58, 0x3d372713, v61
	v_fma_f32 v58, v61, v58, 1.0
	v_mul_f32_e32 v59, v59, v60
	v_mul_f32_e32 v60, 0x3d372713, v62
	v_fma_f32 v60, v62, v60, 1.0
	v_mul_f32_e32 v60, v62, v60
	v_mul_f32_e32 v60, 0xc0135761, v60
	v_exp_f32_e32 v60, v60
	v_mul_f32_e32 v58, v61, v58
	v_mul_f32_e32 v58, 0xc0135761, v58
	v_exp_f32_e32 v58, v58
	v_add_f32_e32 v60, 1.0, v60
	v_rcp_f32_e32 v60, v60
	v_ashrrev_i32_e32 v65, 31, v64
	v_add_f32_e32 v58, 1.0, v58
	v_rcp_f32_e32 v58, v58
	v_mul_f32_e32 v60, v62, v60
	v_mul_f32_e32 v62, 0x3d372713, v63
	v_fma_f32 v62, v63, v62, 1.0
	v_mul_f32_e32 v62, v63, v62
	v_mul_f32_e32 v62, 0xc0135761, v62
	v_exp_f32_e32 v62, v62
	v_mul_f32_e32 v58, v61, v58
	v_mul_f32_e32 v61, 0x3d372713, v68
	v_fma_f32 v61, v68, v61, 1.0
	v_add_f32_e32 v62, 1.0, v62
	v_rcp_f32_e32 v62, v62
	v_mul_f32_e32 v61, v68, v61
	v_mul_f32_e32 v61, 0xc0135761, v61
	v_exp_f32_e32 v61, v61
	v_mul_f32_e32 v62, v63, v62
	v_mul_f32_e32 v63, 0x3d372713, v69
	v_fma_f32 v63, v69, v63, 1.0
	v_mul_f32_e32 v63, v69, v63
	v_mul_f32_e32 v63, 0xc0135761, v63
	v_exp_f32_e32 v63, v63
	v_add_f32_e32 v61, 1.0, v61
	v_rcp_f32_e32 v61, v61
	v_lshlrev_b64 v[66:67], 13, v[64:65]
	v_add_f32_e32 v63, 1.0, v63
	v_rcp_f32_e32 v63, v63
	v_lshl_add_u64 v[66:67], v[134:135], 0, v[66:67]
	v_mul_f32_e32 v61, v68, v61
	v_cvt_pk_bf16_f32 v68, v56, v58
	v_mul_f32_e32 v63, v69, v63
	v_cvt_pk_bf16_f32 v69, v60, v62
	v_pk_mul_f32 v[52:53], v[52:53], v[144:145] op_sel_hi:[1,0]
	v_cvt_pk_bf16_f32 v70, v57, v59
	v_cvt_pk_bf16_f32 v71, v61, v63
	global_store_dwordx4 v[66:67], v[68:71], off sc1
	v_pk_mul_f32 v[54:55], v[54:55], v[144:145] op_sel_hi:[1,0]
	s_and_b64 vcc, exec, s[4:5]
	v_pk_mul_f32 v[68:69], v[50:51], v[144:145] op_sel_hi:[1,0]
	v_pk_mul_f32 v[50:51], v[48:49], v[144:145] op_sel_hi:[1,0]
	v_mul_f32_e32 v48, 0x3d372713, v52
	v_fma_f32 v48, v52, v48, 1.0
	v_mul_f32_e32 v48, v52, v48
	v_mul_f32_e32 v48, 0xc0135761, v48
	v_exp_f32_e32 v48, v48
	v_mul_f32_e32 v49, 0x3d372713, v50
	v_fma_f32 v49, v50, v49, 1.0
	v_mul_f32_e32 v49, v50, v49
	v_add_f32_e32 v48, 1.0, v48
	v_rcp_f32_e32 v48, v48
	v_mul_f32_e32 v49, 0xc0135761, v49
	v_exp_f32_e32 v49, v49
	v_mul_f32_e32 v48, v52, v48
	v_mul_f32_e32 v52, 0x3d372713, v51
	v_fma_f32 v52, v51, v52, 1.0
	v_mul_f32_e32 v52, v51, v52
	v_mul_f32_e32 v52, 0xc0135761, v52
	v_exp_f32_e32 v52, v52
	v_add_f32_e32 v49, 1.0, v49
	v_rcp_f32_e32 v49, v49
	v_add_f32_e32 v52, 1.0, v52
	v_rcp_f32_e32 v52, v52
	v_mul_f32_e32 v49, v50, v49
	v_mul_f32_e32 v50, 0x3d372713, v53
	v_fma_f32 v50, v53, v50, 1.0
	v_mul_f32_e32 v51, v51, v52
	v_mul_f32_e32 v52, 0x3d372713, v54
	v_fma_f32 v52, v54, v52, 1.0
	v_mul_f32_e32 v52, v54, v52
	v_mul_f32_e32 v52, 0xc0135761, v52
	v_exp_f32_e32 v52, v52
	v_mul_f32_e32 v50, v53, v50
	v_mul_f32_e32 v50, 0xc0135761, v50
	v_exp_f32_e32 v50, v50
	v_add_f32_e32 v52, 1.0, v52
	v_rcp_f32_e32 v52, v52
	v_add_f32_e32 v50, 1.0, v50
	v_rcp_f32_e32 v50, v50
	v_mul_f32_e32 v52, v54, v52
	v_mul_f32_e32 v54, 0x3d372713, v55
	v_fma_f32 v54, v55, v54, 1.0
	v_mul_f32_e32 v54, v55, v54
	v_mul_f32_e32 v54, 0xc0135761, v54
	v_exp_f32_e32 v54, v54
	v_mul_f32_e32 v50, v53, v50
	v_mul_f32_e32 v53, 0x3d372713, v68
	v_fma_f32 v53, v68, v53, 1.0
	v_add_f32_e32 v54, 1.0, v54
	v_rcp_f32_e32 v54, v54
	v_mul_f32_e32 v53, v68, v53
	v_mul_f32_e32 v53, 0xc0135761, v53
	v_exp_f32_e32 v53, v53
	v_mul_f32_e32 v54, v55, v54
	v_mul_f32_e32 v55, 0x3d372713, v69
	v_fma_f32 v55, v69, v55, 1.0
	v_mul_f32_e32 v55, v69, v55
	v_mul_f32_e32 v55, 0xc0135761, v55
	v_exp_f32_e32 v55, v55
	v_add_f32_e32 v53, 1.0, v53
	v_rcp_f32_e32 v53, v53
	v_add_f32_e32 v55, 1.0, v55
	v_rcp_f32_e32 v55, v55
	v_mul_f32_e32 v53, v68, v53
	v_cvt_pk_bf16_f32 v68, v48, v50
	v_mul_f32_e32 v55, v69, v55
	v_cvt_pk_bf16_f32 v69, v52, v54
	v_cvt_pk_bf16_f32 v70, v49, v51
	v_cvt_pk_bf16_f32 v71, v53, v55
	global_store_dwordx4 v[66:67], v[68:71], off offset:256 sc1
	s_cbranch_vccnz .LBB0_640
	v_mul_f32_e32 v66, v58, v58
	v_mul_f32_e32 v67, v62, v62
	v_fmac_f32_e32 v66, v56, v56
	v_fmac_f32_e32 v67, v60, v60
	v_add_f32_e32 v66, v66, v67
	v_mul_f32_e32 v67, v59, v59
	v_mul_f32_e32 v68, v63, v63
	v_fmac_f32_e32 v67, v57, v57
	v_fmac_f32_e32 v68, v61, v61
	v_add_f32_e32 v67, v67, v68
	v_add_f32_e32 v66, v66, v67
	v_mul_f32_e32 v67, v50, v50
	v_mul_f32_e32 v68, v54, v54
	v_fmac_f32_e32 v67, v48, v48
	v_fmac_f32_e32 v68, v52, v52
	v_add_f32_e32 v56, v56, v58
	v_add_f32_e32 v58, v60, v62
	v_add_f32_e32 v67, v67, v68
	v_mul_f32_e32 v68, v51, v51
	v_add_f32_e32 v56, v56, v58
	v_add_f32_e32 v57, v57, v59
	v_add_f32_e32 v58, v61, v63
	v_add_f32_e32 v48, v48, v50
	v_add_f32_e32 v50, v52, v54
	v_fmac_f32_e32 v68, v49, v49
	v_add_f32_e32 v57, v57, v58
	v_add_f32_e32 v48, v48, v50
	v_add_f32_e32 v49, v49, v51
	v_add_f32_e32 v50, v53, v55
	v_mul_f32_e32 v69, v55, v55
	v_add_f32_e32 v56, v56, v57
	v_add_f32_e32 v49, v49, v50
	v_fmac_f32_e32 v69, v53, v53
	v_add_f32_e32 v56, 0, v56
	v_add_f32_e32 v48, v48, v49
	v_add_f32_e32 v68, v68, v69
	v_add_f32_e32 v48, v48, v56
	v_add_f32_e32 v67, v67, v68
	v_mov_b32_e32 v49, v48
	v_add_f32_e32 v66, v66, v67
	s_nop 0
	v_permlane16_swap_b32_e32 v48, v49
	v_add_f32_e32 v48, v48, v49
	v_mov_b32_e32 v49, v66
	s_nop 1
	v_permlane16_swap_b32_e32 v66, v49
	v_add_f32_e32 v49, v66, v49
	v_mov_b32_e32 v50, v48
	v_mov_b32_e32 v51, v49
	s_nop 0
	v_permlane32_swap_b32_e32 v48, v50
	v_permlane32_swap_b32_e32 v49, v51
	s_and_saveexec_b64 s[0:1], s[38:39]
	s_cbranch_execz .LBB0_639
	s_lshl_b32 s20, s60, 2
	v_pk_add_f32 v[48:49], v[48:49], v[50:51]
	v_lshlrev_b64 v[50:51], 5, v[64:65]
	s_sub_i32 s48, s20, 32
	v_lshl_add_u64 v[50:51], v[50:51], 0, s[48:49]
	v_or_b32_e32 v50, s15, v50
	v_lshl_add_u64 v[50:51], v[50:51], 3, s[44:45]
	global_store_dwordx2 v[50:51], v[48:49], off

; __device__ __forceinline__ unsigned cvt_pk_bf16(float lo, float hi) { unsigned r; asm volatile("v_cvt_pk_bf16_f32 %0, %1, %2" : "=v"(r) : "v"(lo), "v"(hi)); return r; }
; #define stats ((float*)(KWS(F) + WS_STATS))
;     __device__ __forceinline__ void operator()(const f32x4 (&acc)[2][2][4][2], const Unit& u, int wr, int wc, int fr, int fq) const {
;     ...
;         for (int ai = 0; ai < 2; ++ai)
; #pragma unroll
;             for (int m = 0; m < 4; ++m) { const int row = row0 + ai * HALF + m * 16; bf16_t* rowp = base + (size_t)row * ldc + col0; float s1 = 0.f, s2 = 0.f;
;                 const float rs = rsv[ai][m];
; #pragma unroll
;                 for (int bj = 0; bj < 2; ++bj) { f32x4 v0 = acc[ai][bj][m][0] * rs, v1 = acc[ai][bj][m][1] * rs;
;                     if (ACT == 1) {
; #pragma unroll
;                         for (int e = 0; e < 4; ++e) { v0[e] = gelu_tanh(v0[e]); v1[e] = gelu_tanh(v1[e]); }
;                         s1 += ((v0[0] + v0[1]) + (v0[2] + v0[3])) + ((v1[0] + v1[1]) + (v1[2] + v1[3]));
;                         s2 += ((v0[0] * v0[0] + v0[1] * v0[1]) + (v0[2] * v0[2] + v0[3] * v0[3])) + ((v1[0] * v1[0] + v1[1] * v1[1]) + (v1[2] * v1[2] + v1[3] * v1[3]));
;                     }
;                     if (ACT == 2) {
; #pragma unroll
;                         for (int e = 0; e < 4; ++e) { const float a = __builtin_fmaxf(v0[e], 0.f), b = __builtin_fmaxf(v1[e], 0.f); v0[e] = a * a; v1[e] = b * b; }
;                     }
;                     u32x4 w; w.x = cvt_pk_bf16(v0[0], v0[1]); w.y = cvt_pk_bf16(v0[2], v0[3]); w.z = cvt_pk_bf16(v1[0], v1[1]); w.w = cvt_pk_bf16(v1[2], v1[3]);
;                     *(u32x4*)(rowp + bj * HALF) = w; }
;                 if (ACT == 1) { if (do_stats) {
;                     s1 = fq_sum(s1); s2 = fq_sum(s2);
;                     if (fq == 0) *(f32x2*)(stats + ((size_t)row * 32 + (u.pn - stats_pn0) * 4 + wc) * 2) = (f32x2){s1, s2}; } }
.LBB0_640:
	v_pk_mul_f32 v[44:45], v[44:45], v[140:141] op_sel_hi:[1,0]
	v_pk_mul_f32 v[52:53], v[42:43], v[140:141] op_sel_hi:[1,0]
	v_pk_mul_f32 v[42:43], v[40:41], v[140:141] op_sel_hi:[1,0]
	v_mul_f32_e32 v40, 0x3d372713, v44
	v_fma_f32 v40, v44, v40, 1.0
	v_mul_f32_e32 v40, v44, v40
	v_mul_f32_e32 v40, 0xc0135761, v40
	v_exp_f32_e32 v40, v40
	v_pk_mul_f32 v[46:47], v[46:47], v[140:141] op_sel_hi:[1,0]
	v_mul_f32_e32 v41, 0x3d372713, v42
	v_fma_f32 v41, v42, v41, 1.0
	v_add_f32_e32 v40, 1.0, v40
	v_rcp_f32_e32 v40, v40
	v_mul_f32_e32 v41, v42, v41
	v_mul_f32_e32 v41, 0xc0135761, v41
	v_exp_f32_e32 v41, v41
	v_mul_f32_e32 v40, v44, v40
	v_mul_f32_e32 v44, 0x3d372713, v43
	v_fma_f32 v44, v43, v44, 1.0
	v_mul_f32_e32 v44, v43, v44
	v_mul_f32_e32 v44, 0xc0135761, v44
	v_exp_f32_e32 v44, v44
	v_add_f32_e32 v41, 1.0, v41
	v_rcp_f32_e32 v41, v41
	v_add_u32_e32 v48, 0x90, v164
	v_add_f32_e32 v44, 1.0, v44
	v_rcp_f32_e32 v44, v44
	v_mul_f32_e32 v41, v42, v41
	v_mul_f32_e32 v42, 0x3d372713, v45
	v_fma_f32 v42, v45, v42, 1.0
	v_mul_f32_e32 v43, v43, v44
	v_mul_f32_e32 v44, 0x3d372713, v46
	v_fma_f32 v44, v46, v44, 1.0
	v_mul_f32_e32 v44, v46, v44
	v_mul_f32_e32 v44, 0xc0135761, v44
	v_exp_f32_e32 v44, v44
	v_mul_f32_e32 v42, v45, v42
	v_mul_f32_e32 v42, 0xc0135761, v42
	v_exp_f32_e32 v42, v42
	v_add_f32_e32 v44, 1.0, v44
	v_rcp_f32_e32 v44, v44
	v_ashrrev_i32_e32 v49, 31, v48
	v_add_f32_e32 v42, 1.0, v42
	v_rcp_f32_e32 v42, v42
	v_mul_f32_e32 v44, v46, v44
	v_mul_f32_e32 v46, 0x3d372713, v47
	v_fma_f32 v46, v47, v46, 1.0
	v_mul_f32_e32 v46, v47, v46
	v_mul_f32_e32 v46, 0xc0135761, v46
	v_exp_f32_e32 v46, v46
	v_mul_f32_e32 v42, v45, v42
	v_mul_f32_e32 v45, 0x3d372713, v52
	v_fma_f32 v45, v52, v45, 1.0
	v_add_f32_e32 v46, 1.0, v46
	v_rcp_f32_e32 v46, v46
	v_mul_f32_e32 v45, v52, v45
	v_mul_f32_e32 v45, 0xc0135761, v45
	v_exp_f32_e32 v45, v45
	v_mul_f32_e32 v46, v47, v46
	v_mul_f32_e32 v47, 0x3d372713, v53
	v_fma_f32 v47, v53, v47, 1.0
	v_mul_f32_e32 v47, v53, v47
	v_mul_f32_e32 v47, 0xc0135761, v47
	v_exp_f32_e32 v47, v47
	v_add_f32_e32 v45, 1.0, v45
	v_rcp_f32_e32 v45, v45
	v_lshlrev_b64 v[50:51], 13, v[48:49]
	v_add_f32_e32 v47, 1.0, v47
	v_rcp_f32_e32 v47, v47
	v_lshl_add_u64 v[50:51], v[134:135], 0, v[50:51]
	v_mul_f32_e32 v45, v52, v45
	v_cvt_pk_bf16_f32 v52, v40, v42
	v_mul_f32_e32 v47, v53, v47
	v_cvt_pk_bf16_f32 v53, v44, v46
	v_pk_mul_f32 v[36:37], v[36:37], v[140:141] op_sel_hi:[1,0]
	v_cvt_pk_bf16_f32 v54, v41, v43
	v_cvt_pk_bf16_f32 v55, v45, v47
	global_store_dwordx4 v[50:51], v[52:55], off sc1
	v_pk_mul_f32 v[38:39], v[38:39], v[140:141] op_sel_hi:[1,0]
	s_and_b64 vcc, exec, s[4:5]
	v_pk_mul_f32 v[52:53], v[34:35], v[140:141] op_sel_hi:[1,0]
	v_pk_mul_f32 v[34:35], v[32:33], v[140:141] op_sel_hi:[1,0]
	v_mul_f32_e32 v32, 0x3d372713, v36
	v_fma_f32 v32, v36, v32, 1.0
	v_mul_f32_e32 v32, v36, v32
	v_mul_f32_e32 v32, 0xc0135761, v32
	v_exp_f32_e32 v32, v32
	v_mul_f32_e32 v33, 0x3d372713, v34
	v_fma_f32 v33, v34, v33, 1.0
	v_mul_f32_e32 v33, v34, v33
	v_add_f32_e32 v32, 1.0, v32
	v_rcp_f32_e32 v32, v32
	v_mul_f32_e32 v33, 0xc0135761, v33
	v_exp_f32_e32 v33, v33
	v_mul_f32_e32 v32, v36, v32
	v_mul_f32_e32 v36, 0x3d372713, v35
	v_fma_f32 v36, v35, v36, 1.0
	v_mul_f32_e32 v36, v35, v36
	v_mul_f32_e32 v36, 0xc0135761, v36
	v_exp_f32_e32 v36, v36
	v_add_f32_e32 v33, 1.0, v33
	v_rcp_f32_e32 v33, v33
	v_add_f32_e32 v36, 1.0, v36
	v_rcp_f32_e32 v36, v36
	v_mul_f32_e32 v33, v34, v33
	v_mul_f32_e32 v34, 0x3d372713, v37
	v_fma_f32 v34, v37, v34, 1.0
	v_mul_f32_e32 v35, v35, v36
	v_mul_f32_e32 v36, 0x3d372713, v38
	v_fma_f32 v36, v38, v36, 1.0
	v_mul_f32_e32 v36, v38, v36
	v_mul_f32_e32 v36, 0xc0135761, v36
	v_exp_f32_e32 v36, v36
	v_mul_f32_e32 v34, v37, v34
	v_mul_f32_e32 v34, 0xc0135761, v34
	v_exp_f32_e32 v34, v34
	v_add_f32_e32 v36, 1.0, v36
	v_rcp_f32_e32 v36, v36
	v_add_f32_e32 v34, 1.0, v34
	v_rcp_f32_e32 v34, v34
	v_mul_f32_e32 v36, v38, v36
	v_mul_f32_e32 v38, 0x3d372713, v39
	v_fma_f32 v38, v39, v38, 1.0
	v_mul_f32_e32 v38, v39, v38
	v_mul_f32_e32 v38, 0xc0135761, v38
	v_exp_f32_e32 v38, v38
	v_mul_f32_e32 v34, v37, v34
	v_mul_f32_e32 v37, 0x3d372713, v52
	v_fma_f32 v37, v52, v37, 1.0
	v_add_f32_e32 v38, 1.0, v38
	v_rcp_f32_e32 v38, v38
	v_mul_f32_e32 v37, v52, v37
	v_mul_f32_e32 v37, 0xc0135761, v37
	v_exp_f32_e32 v37, v37
	v_mul_f32_e32 v38, v39, v38
	v_mul_f32_e32 v39, 0x3d372713, v53
	v_fma_f32 v39, v53, v39, 1.0
	v_mul_f32_e32 v39, v53, v39
	v_mul_f32_e32 v39, 0xc0135761, v39
	v_exp_f32_e32 v39, v39
	v_add_f32_e32 v37, 1.0, v37
	v_rcp_f32_e32 v37, v37
	v_add_f32_e32 v39, 1.0, v39
	v_rcp_f32_e32 v39, v39
	v_mul_f32_e32 v37, v52, v37
	v_cvt_pk_bf16_f32 v52, v32, v34
	v_mul_f32_e32 v39, v53, v39
	v_cvt_pk_bf16_f32 v53, v36, v38
	v_cvt_pk_bf16_f32 v54, v33, v35
	v_cvt_pk_bf16_f32 v55, v37, v39
	global_store_dwordx4 v[50:51], v[52:55], off offset:256 sc1
	s_cbranch_vccnz .LBB0_644
	v_mul_f32_e32 v50, v42, v42
	v_mul_f32_e32 v51, v46, v46
	v_fmac_f32_e32 v50, v40, v40
	v_fmac_f32_e32 v51, v44, v44
	v_add_f32_e32 v50, v50, v51
	v_mul_f32_e32 v51, v43, v43
	v_mul_f32_e32 v52, v47, v47
	v_fmac_f32_e32 v51, v41, v41
	v_fmac_f32_e32 v52, v45, v45
	v_add_f32_e32 v51, v51, v52
	v_add_f32_e32 v50, v50, v51
	v_mul_f32_e32 v51, v34, v34
	v_mul_f32_e32 v52, v38, v38
	v_fmac_f32_e32 v51, v32, v32
	v_fmac_f32_e32 v52, v36, v36
	v_add_f32_e32 v40, v40, v42
	v_add_f32_e32 v42, v44, v46
	v_add_f32_e32 v51, v51, v52
	v_mul_f32_e32 v52, v35, v35
	v_add_f32_e32 v40, v40, v42
	v_add_f32_e32 v41, v41, v43
	v_add_f32_e32 v42, v45, v47
	v_add_f32_e32 v32, v32, v34
	v_add_f32_e32 v34, v36, v38
	v_fmac_f32_e32 v52, v33, v33
	v_add_f32_e32 v41, v41, v42
	v_add_f32_e32 v32, v32, v34
	v_add_f32_e32 v33, v33, v35
	v_add_f32_e32 v34, v37, v39
	v_mul_f32_e32 v53, v39, v39
	v_add_f32_e32 v40, v40, v41
	v_add_f32_e32 v33, v33, v34
	v_fmac_f32_e32 v53, v37, v37
	v_add_f32_e32 v40, 0, v40
	v_add_f32_e32 v32, v32, v33
	v_add_f32_e32 v52, v52, v53
	v_add_f32_e32 v32, v32, v40
	v_add_f32_e32 v51, v51, v52
	v_mov_b32_e32 v33, v32
	v_add_f32_e32 v50, v50, v51
	s_nop 0
	v_permlane16_swap_b32_e32 v32, v33
	v_add_f32_e32 v32, v32, v33
	v_mov_b32_e32 v33, v50
	s_nop 1
	v_permlane16_swap_b32_e32 v50, v33
	v_add_f32_e32 v33, v50, v33
	v_mov_b32_e32 v34, v32
	v_mov_b32_e32 v35, v33
	s_nop 0
	v_permlane32_swap_b32_e32 v32, v34
	v_permlane32_swap_b32_e32 v33, v35
	s_and_saveexec_b64 s[0:1], s[38:39]
	s_cbranch_execz .LBB0_643
	s_lshl_b32 s20, s60, 2
	v_pk_add_f32 v[32:33], v[32:33], v[34:35]
	v_lshlrev_b64 v[34:35], 5, v[48:49]
	s_sub_i32 s48, s20, 32
	v_lshl_add_u64 v[34:35], v[34:35], 0, s[48:49]
	v_or_b32_e32 v34, s15, v34
	v_lshl_add_u64 v[34:35], v[34:35], 3, s[44:45]
	global_store_dwordx2 v[34:35], v[32:33], off

; __device__ __forceinline__ unsigned cvt_pk_bf16(float lo, float hi) { unsigned r; asm volatile("v_cvt_pk_bf16_f32 %0, %1, %2" : "=v"(r) : "v"(lo), "v"(hi)); return r; }
; #define stats ((float*)(KWS(F) + WS_STATS))
;     __device__ __forceinline__ void operator()(const f32x4 (&acc)[2][2][4][2], const Unit& u, int wr, int wc, int fr, int fq) const {
;     ...
;         for (int ai = 0; ai < 2; ++ai)
; #pragma unroll
;             for (int m = 0; m < 4; ++m) { const int row = row0 + ai * HALF + m * 16; bf16_t* rowp = base + (size_t)row * ldc + col0; float s1 = 0.f, s2 = 0.f;
;                 const float rs = rsv[ai][m];
; #pragma unroll
;                 for (int bj = 0; bj < 2; ++bj) { f32x4 v0 = acc[ai][bj][m][0] * rs, v1 = acc[ai][bj][m][1] * rs;
;                     if (ACT == 1) {
; #pragma unroll
;                         for (int e = 0; e < 4; ++e) { v0[e] = gelu_tanh(v0[e]); v1[e] = gelu_tanh(v1[e]); }
;                         s1 += ((v0[0] + v0[1]) + (v0[2] + v0[3])) + ((v1[0] + v1[1]) + (v1[2] + v1[3]));
;                         s2 += ((v0[0] * v0[0] + v0[1] * v0[1]) + (v0[2] * v0[2] + v0[3] * v0[3])) + ((v1[0] * v1[0] + v1[1] * v1[1]) + (v1[2] * v1[2] + v1[3] * v1[3]));
;                     }
;                     if (ACT == 2) {
; #pragma unroll
;                         for (int e = 0; e < 4; ++e) { const float a = __builtin_fmaxf(v0[e], 0.f), b = __builtin_fmaxf(v1[e], 0.f); v0[e] = a * a; v1[e] = b * b; }
;                     }
;                     u32x4 w; w.x = cvt_pk_bf16(v0[0], v0[1]); w.y = cvt_pk_bf16(v0[2], v0[3]); w.z = cvt_pk_bf16(v1[0], v1[1]); w.w = cvt_pk_bf16(v1[2], v1[3]);
;                     *(u32x4*)(rowp + bj * HALF) = w; }
;                 if (ACT == 1) { if (do_stats) {
;                     s1 = fq_sum(s1); s2 = fq_sum(s2);
;                     if (fq == 0) *(f32x2*)(stats + ((size_t)row * 32 + (u.pn - stats_pn0) * 4 + wc) * 2) = (f32x2){s1, s2}; } }
.LBB0_644:
	v_pk_mul_f32 v[28:29], v[28:29], v[136:137] op_sel_hi:[1,0]
	v_pk_mul_f32 v[36:37], v[26:27], v[136:137] op_sel_hi:[1,0]
	v_pk_mul_f32 v[26:27], v[24:25], v[136:137] op_sel_hi:[1,0]
	v_mul_f32_e32 v24, 0x3d372713, v28
	v_fma_f32 v24, v28, v24, 1.0
	v_mul_f32_e32 v24, v28, v24
	v_mul_f32_e32 v24, 0xc0135761, v24
	v_exp_f32_e32 v24, v24
	v_pk_mul_f32 v[30:31], v[30:31], v[136:137] op_sel_hi:[1,0]
	v_mul_f32_e32 v25, 0x3d372713, v26
	v_fma_f32 v25, v26, v25, 1.0
	v_add_f32_e32 v24, 1.0, v24
	v_rcp_f32_e32 v24, v24
	v_mul_f32_e32 v25, v26, v25
	v_mul_f32_e32 v25, 0xc0135761, v25
	v_exp_f32_e32 v25, v25
	v_mul_f32_e32 v24, v28, v24
	v_mul_f32_e32 v28, 0x3d372713, v27
	v_fma_f32 v28, v27, v28, 1.0
	v_mul_f32_e32 v28, v27, v28
	v_mul_f32_e32 v28, 0xc0135761, v28
	v_exp_f32_e32 v28, v28
	v_add_f32_e32 v25, 1.0, v25
	v_rcp_f32_e32 v25, v25
	v_add_u32_e32 v32, 0xa0, v164
	v_add_f32_e32 v28, 1.0, v28
	v_rcp_f32_e32 v28, v28
	v_mul_f32_e32 v25, v26, v25
	v_mul_f32_e32 v26, 0x3d372713, v29
	v_fma_f32 v26, v29, v26, 1.0
	v_mul_f32_e32 v27, v27, v28
	v_mul_f32_e32 v28, 0x3d372713, v30
	v_fma_f32 v28, v30, v28, 1.0
	v_mul_f32_e32 v28, v30, v28
	v_mul_f32_e32 v28, 0xc0135761, v28
	v_exp_f32_e32 v28, v28
	v_mul_f32_e32 v26, v29, v26
	v_mul_f32_e32 v26, 0xc0135761, v26
	v_exp_f32_e32 v26, v26
	v_add_f32_e32 v28, 1.0, v28
	v_rcp_f32_e32 v28, v28
	v_ashrrev_i32_e32 v33, 31, v32
	v_add_f32_e32 v26, 1.0, v26
	v_rcp_f32_e32 v26, v26
	v_mul_f32_e32 v28, v30, v28
	v_mul_f32_e32 v30, 0x3d372713, v31
	v_fma_f32 v30, v31, v30, 1.0
	v_mul_f32_e32 v30, v31, v30
	v_mul_f32_e32 v30, 0xc0135761, v30
	v_exp_f32_e32 v30, v30
	v_mul_f32_e32 v26, v29, v26
	v_mul_f32_e32 v29, 0x3d372713, v36
	v_fma_f32 v29, v36, v29, 1.0
	v_add_f32_e32 v30, 1.0, v30
	v_rcp_f32_e32 v30, v30
	v_mul_f32_e32 v29, v36, v29
	v_mul_f32_e32 v29, 0xc0135761, v29
	v_exp_f32_e32 v29, v29
	v_mul_f32_e32 v30, v31, v30
	v_mul_f32_e32 v31, 0x3d372713, v37
	v_fma_f32 v31, v37, v31, 1.0
	v_mul_f32_e32 v31, v37, v31
	v_mul_f32_e32 v31, 0xc0135761, v31
	v_exp_f32_e32 v31, v31
	v_add_f32_e32 v29, 1.0, v29
	v_rcp_f32_e32 v29, v29
	v_lshlrev_b64 v[34:35], 13, v[32:33]
	v_add_f32_e32 v31, 1.0, v31
	v_rcp_f32_e32 v31, v31
	v_lshl_add_u64 v[34:35], v[134:135], 0, v[34:35]
	v_mul_f32_e32 v29, v36, v29
	v_cvt_pk_bf16_f32 v36, v24, v26
	v_mul_f32_e32 v31, v37, v31
	v_cvt_pk_bf16_f32 v37, v28, v30
	v_pk_mul_f32 v[20:21], v[20:21], v[136:137] op_sel_hi:[1,0]
	v_cvt_pk_bf16_f32 v38, v25, v27
	v_cvt_pk_bf16_f32 v39, v29, v31
	global_store_dwordx4 v[34:35], v[36:39], off sc1
	v_pk_mul_f32 v[22:23], v[22:23], v[136:137] op_sel_hi:[1,0]
	s_and_b64 vcc, exec, s[4:5]
	v_pk_mul_f32 v[36:37], v[18:19], v[136:137] op_sel_hi:[1,0]
	v_pk_mul_f32 v[18:19], v[16:17], v[136:137] op_sel_hi:[1,0]
	v_mul_f32_e32 v16, 0x3d372713, v20
	v_fma_f32 v16, v20, v16, 1.0
	v_mul_f32_e32 v16, v20, v16
	v_mul_f32_e32 v16, 0xc0135761, v16
	v_exp_f32_e32 v16, v16
	v_mul_f32_e32 v17, 0x3d372713, v18
	v_fma_f32 v17, v18, v17, 1.0
	v_mul_f32_e32 v17, v18, v17
	v_add_f32_e32 v16, 1.0, v16
	v_rcp_f32_e32 v16, v16
	v_mul_f32_e32 v17, 0xc0135761, v17
	v_exp_f32_e32 v17, v17
	v_mul_f32_e32 v16, v20, v16
	v_mul_f32_e32 v20, 0x3d372713, v19
	v_fma_f32 v20, v19, v20, 1.0
	v_mul_f32_e32 v20, v19, v20
	v_mul_f32_e32 v20, 0xc0135761, v20
	v_exp_f32_e32 v20, v20
	v_add_f32_e32 v17, 1.0, v17
	v_rcp_f32_e32 v17, v17
	v_add_f32_e32 v20, 1.0, v20
	v_rcp_f32_e32 v20, v20
	v_mul_f32_e32 v17, v18, v17
	v_mul_f32_e32 v18, 0x3d372713, v21
	v_fma_f32 v18, v21, v18, 1.0
	v_mul_f32_e32 v19, v19, v20
	v_mul_f32_e32 v20, 0x3d372713, v22
	v_fma_f32 v20, v22, v20, 1.0
	v_mul_f32_e32 v20, v22, v20
	v_mul_f32_e32 v20, 0xc0135761, v20
	v_exp_f32_e32 v20, v20
	v_mul_f32_e32 v18, v21, v18
	v_mul_f32_e32 v18, 0xc0135761, v18
	v_exp_f32_e32 v18, v18
	v_add_f32_e32 v20, 1.0, v20
	v_rcp_f32_e32 v20, v20
	v_add_f32_e32 v18, 1.0, v18
	v_rcp_f32_e32 v18, v18
	v_mul_f32_e32 v20, v22, v20
	v_mul_f32_e32 v22, 0x3d372713, v23
	v_fma_f32 v22, v23, v22, 1.0
	v_mul_f32_e32 v22, v23, v22
	v_mul_f32_e32 v22, 0xc0135761, v22
	v_exp_f32_e32 v22, v22
	v_mul_f32_e32 v18, v21, v18
	v_mul_f32_e32 v21, 0x3d372713, v36
	v_fma_f32 v21, v36, v21, 1.0
	v_add_f32_e32 v22, 1.0, v22
	v_rcp_f32_e32 v22, v22
	v_mul_f32_e32 v21, v36, v21
	v_mul_f32_e32 v21, 0xc0135761, v21
	v_exp_f32_e32 v21, v21
	v_mul_f32_e32 v22, v23, v22
	v_mul_f32_e32 v23, 0x3d372713, v37
	v_fma_f32 v23, v37, v23, 1.0
	v_mul_f32_e32 v23, v37, v23
	v_mul_f32_e32 v23, 0xc0135761, v23
	v_exp_f32_e32 v23, v23
	v_add_f32_e32 v21, 1.0, v21
	v_rcp_f32_e32 v21, v21
	v_add_f32_e32 v23, 1.0, v23
	v_rcp_f32_e32 v23, v23
	v_mul_f32_e32 v21, v36, v21
	v_cvt_pk_bf16_f32 v36, v16, v18
	v_mul_f32_e32 v23, v37, v23
	v_cvt_pk_bf16_f32 v37, v20, v22
	v_cvt_pk_bf16_f32 v38, v17, v19
	v_cvt_pk_bf16_f32 v39, v21, v23
	global_store_dwordx4 v[34:35], v[36:39], off offset:256 sc1
	s_cbranch_vccnz .LBB0_648
	v_mul_f32_e32 v34, v26, v26
	v_mul_f32_e32 v35, v30, v30
	v_fmac_f32_e32 v34, v24, v24
	v_fmac_f32_e32 v35, v28, v28
	v_add_f32_e32 v34, v34, v35
	v_mul_f32_e32 v35, v27, v27
	v_mul_f32_e32 v36, v31, v31
	v_fmac_f32_e32 v35, v25, v25
	v_fmac_f32_e32 v36, v29, v29
	v_add_f32_e32 v35, v35, v36
	v_add_f32_e32 v34, v34, v35
	v_mul_f32_e32 v35, v18, v18
	v_mul_f32_e32 v36, v22, v22
	v_fmac_f32_e32 v35, v16, v16
	v_fmac_f32_e32 v36, v20, v20
	v_add_f32_e32 v24, v24, v26
	v_add_f32_e32 v26, v28, v30
	v_add_f32_e32 v35, v35, v36
	v_mul_f32_e32 v36, v19, v19
	v_add_f32_e32 v24, v24, v26
	v_add_f32_e32 v25, v25, v27
	v_add_f32_e32 v26, v29, v31
	v_add_f32_e32 v16, v16, v18
	v_add_f32_e32 v18, v20, v22
	v_fmac_f32_e32 v36, v17, v17
	v_add_f32_e32 v25, v25, v26
	v_add_f32_e32 v16, v16, v18
	v_add_f32_e32 v17, v17, v19
	v_add_f32_e32 v18, v21, v23
	v_mul_f32_e32 v37, v23, v23
	v_add_f32_e32 v24, v24, v25
	v_add_f32_e32 v17, v17, v18
	v_fmac_f32_e32 v37, v21, v21
	v_add_f32_e32 v24, 0, v24
	v_add_f32_e32 v16, v16, v17
	v_add_f32_e32 v36, v36, v37
	v_add_f32_e32 v16, v16, v24
	v_add_f32_e32 v35, v35, v36
	v_mov_b32_e32 v17, v16
	v_add_f32_e32 v34, v34, v35
	s_nop 0
	v_permlane16_swap_b32_e32 v16, v17
	v_add_f32_e32 v16, v16, v17
	v_mov_b32_e32 v17, v34
	s_nop 1
	v_permlane16_swap_b32_e32 v34, v17
	v_add_f32_e32 v17, v34, v17
	v_mov_b32_e32 v18, v16
	v_mov_b32_e32 v19, v17
	s_nop 0
	v_permlane32_swap_b32_e32 v16, v18
	v_permlane32_swap_b32_e32 v17, v19
	s_and_saveexec_b64 s[0:1], s[38:39]
	s_cbranch_execz .LBB0_647
	s_lshl_b32 s20, s60, 2
	v_pk_add_f32 v[16:17], v[16:17], v[18:19]
	v_lshlrev_b64 v[18:19], 5, v[32:33]
	s_sub_i32 s48, s20, 32
	v_lshl_add_u64 v[18:19], v[18:19], 0, s[48:49]
	v_or_b32_e32 v18, s15, v18
	v_lshl_add_u64 v[18:19], v[18:19], 3, s[44:45]
	global_store_dwordx2 v[18:19], v[16:17], off

; __device__ __forceinline__ unsigned cvt_pk_bf16(float lo, float hi) { unsigned r; asm volatile("v_cvt_pk_bf16_f32 %0, %1, %2" : "=v"(r) : "v"(lo), "v"(hi)); return r; }
; #define stats ((float*)(KWS(F) + WS_STATS))
;     __device__ __forceinline__ void operator()(const f32x4 (&acc)[2][2][4][2], const Unit& u, int wr, int wc, int fr, int fq) const {
;     ...
;         for (int ai = 0; ai < 2; ++ai)
; #pragma unroll
;             for (int m = 0; m < 4; ++m) { const int row = row0 + ai * HALF + m * 16; bf16_t* rowp = base + (size_t)row * ldc + col0; float s1 = 0.f, s2 = 0.f;
;                 const float rs = rsv[ai][m];
; #pragma unroll
;                 for (int bj = 0; bj < 2; ++bj) { f32x4 v0 = acc[ai][bj][m][0] * rs, v1 = acc[ai][bj][m][1] * rs;
;                     if (ACT == 1) {
; #pragma unroll
;                         for (int e = 0; e < 4; ++e) { v0[e] = gelu_tanh(v0[e]); v1[e] = gelu_tanh(v1[e]); }
;                         s1 += ((v0[0] + v0[1]) + (v0[2] + v0[3])) + ((v1[0] + v1[1]) + (v1[2] + v1[3]));
;                         s2 += ((v0[0] * v0[0] + v0[1] * v0[1]) + (v0[2] * v0[2] + v0[3] * v0[3])) + ((v1[0] * v1[0] + v1[1] * v1[1]) + (v1[2] * v1[2] + v1[3] * v1[3]));
;                     }
;                     if (ACT == 2) {
; #pragma unroll
;                         for (int e = 0; e < 4; ++e) { const float a = __builtin_fmaxf(v0[e], 0.f), b = __builtin_fmaxf(v1[e], 0.f); v0[e] = a * a; v1[e] = b * b; }
;                     }
;                     u32x4 w; w.x = cvt_pk_bf16(v0[0], v0[1]); w.y = cvt_pk_bf16(v0[2], v0[3]); w.z = cvt_pk_bf16(v1[0], v1[1]); w.w = cvt_pk_bf16(v1[2], v1[3]);
;                     *(u32x4*)(rowp + bj * HALF) = w; }
;                 if (ACT == 1) { if (do_stats) {
;                     s1 = fq_sum(s1); s2 = fq_sum(s2);
;                     if (fq == 0) *(f32x2*)(stats + ((size_t)row * 32 + (u.pn - stats_pn0) * 4 + wc) * 2) = (f32x2){s1, s2}; } }
.LBB0_648:
	v_pk_mul_f32 v[12:13], v[12:13], v[132:133] op_sel_hi:[1,0]
	v_pk_mul_f32 v[20:21], v[10:11], v[132:133] op_sel_hi:[1,0]
	v_pk_mul_f32 v[10:11], v[8:9], v[132:133] op_sel_hi:[1,0]
	v_mul_f32_e32 v8, 0x3d372713, v12
	v_fma_f32 v8, v12, v8, 1.0
	v_mul_f32_e32 v8, v12, v8
	v_mul_f32_e32 v8, 0xc0135761, v8
	v_exp_f32_e32 v8, v8
	v_pk_mul_f32 v[14:15], v[14:15], v[132:133] op_sel_hi:[1,0]
	v_mul_f32_e32 v9, 0x3d372713, v10
	v_fma_f32 v9, v10, v9, 1.0
	v_add_f32_e32 v8, 1.0, v8
	v_rcp_f32_e32 v8, v8
	v_mul_f32_e32 v9, v10, v9
	v_mul_f32_e32 v9, 0xc0135761, v9
	v_exp_f32_e32 v9, v9
	v_mul_f32_e32 v8, v12, v8
	v_mul_f32_e32 v12, 0x3d372713, v11
	v_fma_f32 v12, v11, v12, 1.0
	v_mul_f32_e32 v12, v11, v12
	v_mul_f32_e32 v12, 0xc0135761, v12
	v_exp_f32_e32 v12, v12
	v_add_f32_e32 v9, 1.0, v9
	v_rcp_f32_e32 v9, v9
	v_add_u32_e32 v16, 0xb0, v164
	v_add_f32_e32 v12, 1.0, v12
	v_rcp_f32_e32 v12, v12
	v_mul_f32_e32 v9, v10, v9
	v_mul_f32_e32 v10, 0x3d372713, v13
	v_fma_f32 v10, v13, v10, 1.0
	v_mul_f32_e32 v11, v11, v12
	v_mul_f32_e32 v12, 0x3d372713, v14
	v_fma_f32 v12, v14, v12, 1.0
	v_mul_f32_e32 v12, v14, v12
	v_mul_f32_e32 v12, 0xc0135761, v12
	v_exp_f32_e32 v12, v12
	v_mul_f32_e32 v10, v13, v10
	v_mul_f32_e32 v10, 0xc0135761, v10
	v_exp_f32_e32 v10, v10
	v_add_f32_e32 v12, 1.0, v12
	v_rcp_f32_e32 v12, v12
	v_ashrrev_i32_e32 v17, 31, v16
	v_add_f32_e32 v10, 1.0, v10
	v_rcp_f32_e32 v10, v10
	v_mul_f32_e32 v12, v14, v12
	v_mul_f32_e32 v14, 0x3d372713, v15
	v_fma_f32 v14, v15, v14, 1.0
	v_mul_f32_e32 v14, v15, v14
	v_mul_f32_e32 v14, 0xc0135761, v14
	v_exp_f32_e32 v14, v14
	v_mul_f32_e32 v10, v13, v10
	v_mul_f32_e32 v13, 0x3d372713, v20
	v_fma_f32 v13, v20, v13, 1.0
	v_add_f32_e32 v14, 1.0, v14
	v_rcp_f32_e32 v14, v14
	v_mul_f32_e32 v13, v20, v13
	v_mul_f32_e32 v13, 0xc0135761, v13
	v_exp_f32_e32 v13, v13
	v_mul_f32_e32 v14, v15, v14
	v_mul_f32_e32 v15, 0x3d372713, v21
	v_fma_f32 v15, v21, v15, 1.0
	v_mul_f32_e32 v15, v21, v15
	v_mul_f32_e32 v15, 0xc0135761, v15
	v_exp_f32_e32 v15, v15
	v_add_f32_e32 v13, 1.0, v13
	v_rcp_f32_e32 v13, v13
	v_lshlrev_b64 v[18:19], 13, v[16:17]
	v_add_f32_e32 v15, 1.0, v15
	v_rcp_f32_e32 v15, v15
	v_lshl_add_u64 v[18:19], v[134:135], 0, v[18:19]
	v_mul_f32_e32 v13, v20, v13
	v_cvt_pk_bf16_f32 v20, v8, v10
	v_mul_f32_e32 v15, v21, v15
	v_cvt_pk_bf16_f32 v21, v12, v14
	v_pk_mul_f32 v[4:5], v[4:5], v[132:133] op_sel_hi:[1,0]
	v_cvt_pk_bf16_f32 v22, v9, v11
	v_cvt_pk_bf16_f32 v23, v13, v15
	global_store_dwordx4 v[18:19], v[20:23], off sc1
	v_pk_mul_f32 v[6:7], v[6:7], v[132:133] op_sel_hi:[1,0]
	s_and_b64 vcc, exec, s[4:5]
	v_pk_mul_f32 v[20:21], v[2:3], v[132:133] op_sel_hi:[1,0]
	v_pk_mul_f32 v[2:3], v[0:1], v[132:133] op_sel_hi:[1,0]
	v_mul_f32_e32 v0, 0x3d372713, v4
	v_fma_f32 v0, v4, v0, 1.0
	v_mul_f32_e32 v0, v4, v0
	v_mul_f32_e32 v0, 0xc0135761, v0
	v_exp_f32_e32 v0, v0
	v_mul_f32_e32 v1, 0x3d372713, v2
	v_fma_f32 v1, v2, v1, 1.0
	v_mul_f32_e32 v1, v2, v1
	v_add_f32_e32 v0, 1.0, v0
	v_rcp_f32_e32 v0, v0
	v_mul_f32_e32 v1, 0xc0135761, v1
	v_exp_f32_e32 v1, v1
	v_mul_f32_e32 v0, v4, v0
	v_mul_f32_e32 v4, 0x3d372713, v3
	v_fma_f32 v4, v3, v4, 1.0
	v_mul_f32_e32 v4, v3, v4
	v_mul_f32_e32 v4, 0xc0135761, v4
	v_exp_f32_e32 v4, v4
	v_add_f32_e32 v1, 1.0, v1
	v_rcp_f32_e32 v1, v1
	v_add_f32_e32 v4, 1.0, v4
	v_rcp_f32_e32 v4, v4
	v_mul_f32_e32 v1, v2, v1
	v_mul_f32_e32 v2, 0x3d372713, v5
	v_fma_f32 v2, v5, v2, 1.0
	v_mul_f32_e32 v3, v3, v4
	v_mul_f32_e32 v4, 0x3d372713, v6
	v_fma_f32 v4, v6, v4, 1.0
	v_mul_f32_e32 v4, v6, v4
	v_mul_f32_e32 v4, 0xc0135761, v4
	v_exp_f32_e32 v4, v4
	v_mul_f32_e32 v2, v5, v2
	v_mul_f32_e32 v2, 0xc0135761, v2
	v_exp_f32_e32 v2, v2
	v_add_f32_e32 v4, 1.0, v4
	v_rcp_f32_e32 v4, v4
	v_add_f32_e32 v2, 1.0, v2
	v_rcp_f32_e32 v2, v2
	v_mul_f32_e32 v4, v6, v4
	v_mul_f32_e32 v6, 0x3d372713, v7
	v_fma_f32 v6, v7, v6, 1.0
	v_mul_f32_e32 v6, v7, v6
	v_mul_f32_e32 v6, 0xc0135761, v6
	v_exp_f32_e32 v6, v6
	v_mul_f32_e32 v2, v5, v2
	v_mul_f32_e32 v5, 0x3d372713, v20
	v_fma_f32 v5, v20, v5, 1.0
	v_add_f32_e32 v6, 1.0, v6
	v_rcp_f32_e32 v6, v6
	v_mul_f32_e32 v5, v20, v5
	v_mul_f32_e32 v5, 0xc0135761, v5
	v_exp_f32_e32 v5, v5
	v_mul_f32_e32 v6, v7, v6
	v_mul_f32_e32 v7, 0x3d372713, v21
	v_fma_f32 v7, v21, v7, 1.0
	v_mul_f32_e32 v7, v21, v7
	v_mul_f32_e32 v7, 0xc0135761, v7
	v_exp_f32_e32 v7, v7
	v_add_f32_e32 v5, 1.0, v5
	v_rcp_f32_e32 v5, v5
	v_add_f32_e32 v7, 1.0, v7
	v_rcp_f32_e32 v7, v7
	v_mul_f32_e32 v5, v20, v5
	v_cvt_pk_bf16_f32 v20, v0, v2
	v_mul_f32_e32 v7, v21, v7
	v_cvt_pk_bf16_f32 v21, v4, v6
	v_cvt_pk_bf16_f32 v22, v1, v3
	v_cvt_pk_bf16_f32 v23, v5, v7
	global_store_dwordx4 v[18:19], v[20:23], off offset:256 sc1
	s_cbranch_vccnz .LBB0_652
	v_mul_f32_e32 v18, v10, v10
	v_mul_f32_e32 v19, v14, v14
	v_fmac_f32_e32 v18, v8, v8
	v_fmac_f32_e32 v19, v12, v12
	v_add_f32_e32 v18, v18, v19
	v_mul_f32_e32 v19, v11, v11
	v_mul_f32_e32 v20, v15, v15
	v_fmac_f32_e32 v19, v9, v9
	v_fmac_f32_e32 v20, v13, v13
	v_add_f32_e32 v19, v19, v20
	v_add_f32_e32 v18, v18, v19
	v_mul_f32_e32 v19, v2, v2
	v_mul_f32_e32 v20, v6, v6
	v_fmac_f32_e32 v19, v0, v0
	v_fmac_f32_e32 v20, v4, v4
	v_add_f32_e32 v8, v8, v10
	v_add_f32_e32 v10, v12, v14
	v_add_f32_e32 v19, v19, v20
	v_mul_f32_e32 v20, v3, v3
	v_add_f32_e32 v8, v8, v10
	v_add_f32_e32 v9, v9, v11
	v_add_f32_e32 v10, v13, v15
	v_add_f32_e32 v0, v0, v2
	v_add_f32_e32 v2, v4, v6
	v_fmac_f32_e32 v20, v1, v1
	v_add_f32_e32 v9, v9, v10
	v_add_f32_e32 v0, v0, v2
	v_add_f32_e32 v1, v1, v3
	v_add_f32_e32 v2, v5, v7
	v_mul_f32_e32 v21, v7, v7
	v_add_f32_e32 v8, v8, v9
	v_add_f32_e32 v1, v1, v2
	v_fmac_f32_e32 v21, v5, v5
	v_add_f32_e32 v8, 0, v8
	v_add_f32_e32 v0, v0, v1
	v_add_f32_e32 v20, v20, v21
	v_add_f32_e32 v0, v0, v8
	v_add_f32_e32 v19, v19, v20
	v_mov_b32_e32 v1, v0
	v_add_f32_e32 v18, v18, v19
	s_nop 0
	v_permlane16_swap_b32_e32 v0, v1
	v_add_f32_e32 v0, v0, v1
	v_mov_b32_e32 v1, v18
	s_nop 1
	v_permlane16_swap_b32_e32 v18, v1
	v_add_f32_e32 v1, v18, v1
	v_mov_b32_e32 v2, v0
	v_mov_b32_e32 v3, v1
	s_nop 0
	v_permlane32_swap_b32_e32 v0, v2
	v_permlane32_swap_b32_e32 v1, v3
	s_and_saveexec_b64 s[0:1], s[38:39]
	s_cbranch_execz .LBB0_651
	s_lshl_b32 s4, s60, 2
	v_pk_add_f32 v[0:1], v[0:1], v[2:3]
	v_lshlrev_b64 v[2:3], 5, v[16:17]
	s_sub_i32 s48, s4, 32
	v_lshl_add_u64 v[2:3], v[2:3], 0, s[48:49]
	v_or_b32_e32 v2, s15, v2
	v_lshl_add_u64 v[2:3], v[2:3], 3, s[44:45]
	global_store_dwordx2 v[2:3], v[0:1], off
